# static priority: waves 4-7 (trailing half) run each GEMM K-loop at s_setprio 1, all per-segment setprio flips in the 9 K-loops deleted; on top of previous best
# speedup vs baseline: 1.0133x; 1.0033x over previous
.LBB0_1789:
	s_ashr_i32 s45, s44, 31
	s_lshl_b64 s[74:75], s[44:45], 21
	s_add_u32 s84, s16, s74
	s_addc_u32 s85, s17, s75
	s_and_b64 s[74:75], s[4:5], exec
	s_cselect_b32 s45, s85, s7
	s_cselect_b32 s74, s84, s6
	s_ashr_i32 s43, s42, 31
	s_lshl_b64 s[76:77], s[42:43], 21
	s_add_u32 s86, s10, s76
	s_addc_u32 s87, s11, s77
	s_and_b64 s[76:77], s[4:5], exec
	s_cselect_b32 s43, s87, s89
	s_cselect_b32 s75, s86, s88
	s_add_u32 s6, s6, 0x100080
	s_addc_u32 s7, s7, 0
	s_add_u32 s76, s88, 0x100
	v_mov_b32_e32 v2, 0
	s_addc_u32 s77, s89, 0
	s_mov_b32 s78, -2
	v_mov_b32_e32 v3, v2
	v_mov_b32_e32 v4, v2
	v_mov_b32_e32 v5, v2
	v_mov_b32_e32 v6, v2
	v_mov_b32_e32 v7, v2
	v_mov_b32_e32 v8, v2
	v_mov_b32_e32 v9, v2
	v_mov_b32_e32 v14, v2
	v_mov_b32_e32 v15, v2
	v_mov_b32_e32 v16, v2
	v_mov_b32_e32 v17, v2
	v_mov_b32_e32 v22, v2
	v_mov_b32_e32 v23, v2
	v_mov_b32_e32 v24, v2
	v_mov_b32_e32 v25, v2
	v_mov_b32_e32 v30, v2
	v_mov_b32_e32 v31, v2
	v_mov_b32_e32 v32, v2
	v_mov_b32_e32 v33, v2
	v_mov_b32_e32 v38, v2
	v_mov_b32_e32 v39, v2
	v_mov_b32_e32 v40, v2
	v_mov_b32_e32 v41, v2
	v_mov_b32_e32 v46, v2
	v_mov_b32_e32 v47, v2
	v_mov_b32_e32 v48, v2
	v_mov_b32_e32 v49, v2
	v_mov_b32_e32 v54, v2
	v_mov_b32_e32 v55, v2
	v_mov_b32_e32 v56, v2
	v_mov_b32_e32 v57, v2
	v_mov_b32_e32 v10, v2
	v_mov_b32_e32 v11, v2
	v_mov_b32_e32 v12, v2
	v_mov_b32_e32 v13, v2
	v_mov_b32_e32 v18, v2
	v_mov_b32_e32 v19, v2
	v_mov_b32_e32 v20, v2
	v_mov_b32_e32 v21, v2
	v_mov_b32_e32 v26, v2
	v_mov_b32_e32 v27, v2
	v_mov_b32_e32 v28, v2
	v_mov_b32_e32 v29, v2
	v_mov_b32_e32 v34, v2
	v_mov_b32_e32 v35, v2
	v_mov_b32_e32 v36, v2
	v_mov_b32_e32 v37, v2
	v_mov_b32_e32 v42, v2
	v_mov_b32_e32 v43, v2
	v_mov_b32_e32 v44, v2
	v_mov_b32_e32 v45, v2
	v_mov_b32_e32 v50, v2
	v_mov_b32_e32 v51, v2
	v_mov_b32_e32 v52, v2
	v_mov_b32_e32 v53, v2
	v_mov_b32_e32 v58, v2
	v_mov_b32_e32 v59, v2
	v_mov_b32_e32 v60, v2
	v_mov_b32_e32 v61, v2
	v_mov_b32_e32 v62, v2
	v_mov_b32_e32 v63, v2
	v_mov_b32_e32 v64, v2
	v_mov_b32_e32 v65, v2
	v_mov_b32_e32 v66, v2
	v_mov_b32_e32 v67, v2
	v_mov_b32_e32 v68, v2
	v_mov_b32_e32 v69, v2
	v_mov_b32_e32 v70, v2
	v_mov_b32_e32 v71, v2
	v_mov_b32_e32 v72, v2
	v_mov_b32_e32 v73, v2
	v_mov_b32_e32 v78, v2
	v_mov_b32_e32 v79, v2
	v_mov_b32_e32 v80, v2
	v_mov_b32_e32 v81, v2
	v_mov_b32_e32 v86, v2
	v_mov_b32_e32 v87, v2
	v_mov_b32_e32 v88, v2
	v_mov_b32_e32 v89, v2
	v_mov_b32_e32 v94, v2
	v_mov_b32_e32 v95, v2
	v_mov_b32_e32 v96, v2
	v_mov_b32_e32 v97, v2
	v_mov_b32_e32 v102, v2
	v_mov_b32_e32 v103, v2
	v_mov_b32_e32 v104, v2
	v_mov_b32_e32 v105, v2
	v_mov_b32_e32 v110, v2
	v_mov_b32_e32 v111, v2
	v_mov_b32_e32 v112, v2
	v_mov_b32_e32 v113, v2
	v_mov_b32_e32 v118, v2
	v_mov_b32_e32 v119, v2
	v_mov_b32_e32 v120, v2
	v_mov_b32_e32 v121, v2
	v_mov_b32_e32 v74, v2
	v_mov_b32_e32 v75, v2
	v_mov_b32_e32 v76, v2
	v_mov_b32_e32 v77, v2
	v_mov_b32_e32 v82, v2
	v_mov_b32_e32 v83, v2
	v_mov_b32_e32 v84, v2
	v_mov_b32_e32 v85, v2
	v_mov_b32_e32 v90, v2
	v_mov_b32_e32 v91, v2
	v_mov_b32_e32 v92, v2
	v_mov_b32_e32 v93, v2
	v_mov_b32_e32 v98, v2
	v_mov_b32_e32 v99, v2
	v_mov_b32_e32 v100, v2
	v_mov_b32_e32 v101, v2
	v_mov_b32_e32 v106, v2
	v_mov_b32_e32 v107, v2
	v_mov_b32_e32 v108, v2
	v_mov_b32_e32 v109, v2
	v_mov_b32_e32 v114, v2
	v_mov_b32_e32 v115, v2
	v_mov_b32_e32 v116, v2
	v_mov_b32_e32 v117, v2
	v_mov_b32_e32 v122, v2
	v_mov_b32_e32 v123, v2
	v_mov_b32_e32 v124, v2
	v_mov_b32_e32 v125, v2
	v_mov_b32_e32 v126, v2
	v_mov_b32_e32 v127, v2
	v_mov_b32_e32 v128, v2
	v_mov_b32_e32 v129, v2
	s_and_b64 vcc, exec, s[40:41]
	s_cbranch_vccnz .Lsprio_0
	s_setprio 1
.Lsprio_0:
.LBB0_1790:
	ds_read_b128 v[146:149], v159
	ds_read_b128 v[150:153], v159 offset:1024
	ds_read_b128 v[164:167], v159 offset:2048
	ds_read_b128 v[168:171], v159 offset:3072
	ds_read_b128 v[172:175], v160
	ds_read_b128 v[176:179], v160 offset:1024
	ds_read_b128 v[186:189], v160 offset:2048
	ds_read_b128 v[190:193], v160 offset:3072
	s_add_u32 s79, s6, 0xfff00080
	s_addc_u32 s80, s7, -1
	s_cmp_eq_u32 s78, 60
	s_cselect_b32 s91, s45, s80
	s_cselect_b32 s90, s74, s79
	s_cselect_b32 s89, s43, s77
	s_cselect_b32 s88, s75, s76
	s_add_i32 m0, s33, 0xc000
	ds_read_b128 v[194:197], v161
	ds_read_b128 v[198:201], v161 offset:1024
	ds_read_b128 v[202:205], v161 offset:2048
	ds_read_b128 v[206:209], v161 offset:3072
	ds_read_b128 v[210:213], v161 offset:4096
	ds_read_b128 v[214:217], v161 offset:5120
	ds_read_b128 v[218:221], v161 offset:6144
	ds_read_b128 v[222:225], v161 offset:7168
	global_load_lds_dwordx4 v138, s[6:7]
	s_add_i32 m0, s33, 0xe000
	s_nop 0
	global_load_lds_dwordx4 v140, s[6:7]
	s_waitcnt vmcnt(8)
	s_waitcnt lgkmcnt(0)
	s_barrier
	v_mfma_f32_16x16x32_bf16 v[126:129], v[146:149], v[194:197], v[126:129]
	v_mfma_f32_16x16x32_bf16 v[126:129], v[150:153], v[198:201], v[126:129]
	v_mfma_f32_16x16x32_bf16 v[122:125], v[164:167], v[194:197], v[122:125]
	v_mfma_f32_16x16x32_bf16 v[122:125], v[168:171], v[198:201], v[122:125]
	v_mfma_f32_16x16x32_bf16 v[118:121], v[172:175], v[194:197], v[118:121]
	v_mfma_f32_16x16x32_bf16 v[118:121], v[176:179], v[198:201], v[118:121]
	v_mfma_f32_16x16x32_bf16 v[110:113], v[186:189], v[194:197], v[110:113]
	v_mfma_f32_16x16x32_bf16 v[110:113], v[190:193], v[198:201], v[110:113]
	v_mfma_f32_16x16x32_bf16 v[114:117], v[146:149], v[202:205], v[114:117]
	v_mfma_f32_16x16x32_bf16 v[114:117], v[150:153], v[206:209], v[114:117]
	v_mfma_f32_16x16x32_bf16 v[106:109], v[164:167], v[202:205], v[106:109]
	v_mfma_f32_16x16x32_bf16 v[106:109], v[168:171], v[206:209], v[106:109]
	v_mfma_f32_16x16x32_bf16 v[102:105], v[172:175], v[202:205], v[102:105]
	v_mfma_f32_16x16x32_bf16 v[102:105], v[176:179], v[206:209], v[102:105]
	v_mfma_f32_16x16x32_bf16 v[94:97], v[186:189], v[202:205], v[94:97]
	v_mfma_f32_16x16x32_bf16 v[94:97], v[190:193], v[206:209], v[94:97]
	v_mfma_f32_16x16x32_bf16 v[98:101], v[146:149], v[210:213], v[98:101]
	v_mfma_f32_16x16x32_bf16 v[98:101], v[150:153], v[214:217], v[98:101]
	v_mfma_f32_16x16x32_bf16 v[90:93], v[164:167], v[210:213], v[90:93]
	v_mfma_f32_16x16x32_bf16 v[90:93], v[168:171], v[214:217], v[90:93]
	v_mfma_f32_16x16x32_bf16 v[86:89], v[172:175], v[210:213], v[86:89]
	v_mfma_f32_16x16x32_bf16 v[86:89], v[176:179], v[214:217], v[86:89]
	v_mfma_f32_16x16x32_bf16 v[78:81], v[186:189], v[210:213], v[78:81]
	v_mfma_f32_16x16x32_bf16 v[78:81], v[190:193], v[214:217], v[78:81]
	v_mfma_f32_16x16x32_bf16 v[82:85], v[146:149], v[218:221], v[82:85]
	v_mfma_f32_16x16x32_bf16 v[82:85], v[150:153], v[222:225], v[82:85]
	v_mfma_f32_16x16x32_bf16 v[74:77], v[164:167], v[218:221], v[74:77]
	v_mfma_f32_16x16x32_bf16 v[74:77], v[168:171], v[222:225], v[74:77]
	v_mfma_f32_16x16x32_bf16 v[70:73], v[172:175], v[218:221], v[70:73]
	v_mfma_f32_16x16x32_bf16 v[70:73], v[176:179], v[222:225], v[70:73]
	v_mfma_f32_16x16x32_bf16 v[66:69], v[186:189], v[218:221], v[66:69]
	v_mfma_f32_16x16x32_bf16 v[66:69], v[190:193], v[222:225], v[66:69]
	s_barrier
	s_add_i32 s79, s69, s25
	s_add_u32 s98, s88, 0x80
	s_addc_u32 s99, s89, 0
	s_mov_b32 m0, s79
	ds_read_b128 v[194:197], v161 offset:16384
	ds_read_b128 v[198:201], v161 offset:17408
	ds_read_b128 v[202:205], v161 offset:18432
	ds_read_b128 v[206:209], v161 offset:19456
	ds_read_b128 v[210:213], v161 offset:20480
	ds_read_b128 v[214:217], v161 offset:21504
	ds_read_b128 v[218:221], v161 offset:22528
	ds_read_b128 v[222:225], v161 offset:23552
	global_load_lds_dwordx4 v132, s[88:89]
	s_add_i32 m0, s79, 0x2000
	s_add_u32 s80, s88, 0x100000
	s_addc_u32 s81, s89, 0
	s_add_i32 s79, s70, s25
	global_load_lds_dwordx4 v136, s[88:89]
	s_mov_b32 m0, s79
	global_load_lds_dwordx4 v132, s[80:81]
	s_add_i32 m0, s79, 0x2000
	s_nop 0
	global_load_lds_dwordx4 v136, s[80:81]
	s_add_u32 s100, s90, 0x80
	s_addc_u32 s101, s91, 0
	s_mov_b32 m0, s33
	s_nop 0
	global_load_lds_dwordx4 v130, s[90:91]
	s_mov_b32 m0, s35
	s_nop 0
	global_load_lds_dwordx4 v134, s[90:91]
	s_waitcnt vmcnt(8)
	s_waitcnt lgkmcnt(0)
	s_barrier
	v_mfma_f32_16x16x32_bf16 v[62:65], v[146:149], v[194:197], v[62:65]
	v_mfma_f32_16x16x32_bf16 v[62:65], v[150:153], v[198:201], v[62:65]
	v_mfma_f32_16x16x32_bf16 v[58:61], v[164:167], v[194:197], v[58:61]
	v_mfma_f32_16x16x32_bf16 v[58:61], v[168:171], v[198:201], v[58:61]
	v_mfma_f32_16x16x32_bf16 v[54:57], v[172:175], v[194:197], v[54:57]
	v_mfma_f32_16x16x32_bf16 v[54:57], v[176:179], v[198:201], v[54:57]
	v_mfma_f32_16x16x32_bf16 v[46:49], v[186:189], v[194:197], v[46:49]
	v_mfma_f32_16x16x32_bf16 v[46:49], v[190:193], v[198:201], v[46:49]
	v_mfma_f32_16x16x32_bf16 v[50:53], v[146:149], v[202:205], v[50:53]
	v_mfma_f32_16x16x32_bf16 v[50:53], v[150:153], v[206:209], v[50:53]
	v_mfma_f32_16x16x32_bf16 v[42:45], v[164:167], v[202:205], v[42:45]
	v_mfma_f32_16x16x32_bf16 v[42:45], v[168:171], v[206:209], v[42:45]
	v_mfma_f32_16x16x32_bf16 v[38:41], v[172:175], v[202:205], v[38:41]
	v_mfma_f32_16x16x32_bf16 v[38:41], v[176:179], v[206:209], v[38:41]
	v_mfma_f32_16x16x32_bf16 v[30:33], v[186:189], v[202:205], v[30:33]
	v_mfma_f32_16x16x32_bf16 v[30:33], v[190:193], v[206:209], v[30:33]
	v_mfma_f32_16x16x32_bf16 v[34:37], v[146:149], v[210:213], v[34:37]
	v_mfma_f32_16x16x32_bf16 v[34:37], v[150:153], v[214:217], v[34:37]
	v_mfma_f32_16x16x32_bf16 v[26:29], v[164:167], v[210:213], v[26:29]
	v_mfma_f32_16x16x32_bf16 v[26:29], v[168:171], v[214:217], v[26:29]
	v_mfma_f32_16x16x32_bf16 v[22:25], v[172:175], v[210:213], v[22:25]
	v_mfma_f32_16x16x32_bf16 v[22:25], v[176:179], v[214:217], v[22:25]
	v_mfma_f32_16x16x32_bf16 v[14:17], v[186:189], v[210:213], v[14:17]
	v_mfma_f32_16x16x32_bf16 v[14:17], v[190:193], v[214:217], v[14:17]
	v_mfma_f32_16x16x32_bf16 v[18:21], v[146:149], v[218:221], v[18:21]
	v_mfma_f32_16x16x32_bf16 v[18:21], v[150:153], v[222:225], v[18:21]
	v_mfma_f32_16x16x32_bf16 v[10:13], v[164:167], v[218:221], v[10:13]
	v_mfma_f32_16x16x32_bf16 v[10:13], v[168:171], v[222:225], v[10:13]
	v_mfma_f32_16x16x32_bf16 v[6:9], v[172:175], v[218:221], v[6:9]
	v_mfma_f32_16x16x32_bf16 v[6:9], v[176:179], v[222:225], v[6:9]
	v_mfma_f32_16x16x32_bf16 v[2:5], v[186:189], v[218:221], v[2:5]
	v_mfma_f32_16x16x32_bf16 v[2:5], v[190:193], v[222:225], v[2:5]
	s_barrier
	s_add_i32 s79, 0, 0x18000
	s_add_i32 s82, 0, 0x1c000
	v_add_u32_e32 v168, s79, v155
	v_add_u32_e32 v183, s82, v155
	ds_read_b128 v[146:149], v168
	ds_read_b128 v[150:153], v168 offset:1024
	ds_read_b128 v[164:167], v168 offset:2048
	ds_read_b128 v[168:171], v168 offset:3072
	ds_read_b128 v[172:175], v183
	ds_read_b128 v[176:179], v183 offset:1024
	ds_read_b128 v[186:189], v183 offset:2048
	ds_read_b128 v[190:193], v183 offset:3072
	s_add_u32 s80, s90, 0x100000
	s_addc_u32 s81, s91, 0
	s_mov_b32 m0, s59
	ds_read_b128 v[194:197], v161 offset:32768
	ds_read_b128 v[198:201], v161 offset:33792
	ds_read_b128 v[202:205], v161 offset:34816
	ds_read_b128 v[206:209], v161 offset:35840
	ds_read_b128 v[210:213], v161 offset:36864
	ds_read_b128 v[214:217], v161 offset:37888
	ds_read_b128 v[218:221], v161 offset:38912
	ds_read_b128 v[222:225], v161 offset:39936
	global_load_lds_dwordx4 v130, s[80:81]
	s_mov_b32 m0, s62
	s_nop 0
	global_load_lds_dwordx4 v134, s[80:81]
	s_waitcnt vmcnt(8)
	s_waitcnt lgkmcnt(0)
	s_barrier
	v_mfma_f32_16x16x32_bf16 v[126:129], v[146:149], v[194:197], v[126:129]
	v_mfma_f32_16x16x32_bf16 v[126:129], v[150:153], v[198:201], v[126:129]
	v_mfma_f32_16x16x32_bf16 v[122:125], v[164:167], v[194:197], v[122:125]
	v_mfma_f32_16x16x32_bf16 v[122:125], v[168:171], v[198:201], v[122:125]
	v_mfma_f32_16x16x32_bf16 v[118:121], v[172:175], v[194:197], v[118:121]
	v_mfma_f32_16x16x32_bf16 v[118:121], v[176:179], v[198:201], v[118:121]
	v_mfma_f32_16x16x32_bf16 v[110:113], v[186:189], v[194:197], v[110:113]
	v_mfma_f32_16x16x32_bf16 v[110:113], v[190:193], v[198:201], v[110:113]
	v_mfma_f32_16x16x32_bf16 v[114:117], v[146:149], v[202:205], v[114:117]
	v_mfma_f32_16x16x32_bf16 v[114:117], v[150:153], v[206:209], v[114:117]
	v_mfma_f32_16x16x32_bf16 v[106:109], v[164:167], v[202:205], v[106:109]
	v_mfma_f32_16x16x32_bf16 v[106:109], v[168:171], v[206:209], v[106:109]
	v_mfma_f32_16x16x32_bf16 v[102:105], v[172:175], v[202:205], v[102:105]
	v_mfma_f32_16x16x32_bf16 v[102:105], v[176:179], v[206:209], v[102:105]
	v_mfma_f32_16x16x32_bf16 v[94:97], v[186:189], v[202:205], v[94:97]
	v_mfma_f32_16x16x32_bf16 v[94:97], v[190:193], v[206:209], v[94:97]
	v_mfma_f32_16x16x32_bf16 v[98:101], v[146:149], v[210:213], v[98:101]
	v_mfma_f32_16x16x32_bf16 v[98:101], v[150:153], v[214:217], v[98:101]
	v_mfma_f32_16x16x32_bf16 v[90:93], v[164:167], v[210:213], v[90:93]
	v_mfma_f32_16x16x32_bf16 v[90:93], v[168:171], v[214:217], v[90:93]
	v_mfma_f32_16x16x32_bf16 v[86:89], v[172:175], v[210:213], v[86:89]
	v_mfma_f32_16x16x32_bf16 v[86:89], v[176:179], v[214:217], v[86:89]
	v_mfma_f32_16x16x32_bf16 v[78:81], v[186:189], v[210:213], v[78:81]
	v_mfma_f32_16x16x32_bf16 v[78:81], v[190:193], v[214:217], v[78:81]
	v_mfma_f32_16x16x32_bf16 v[82:85], v[146:149], v[218:221], v[82:85]
	v_mfma_f32_16x16x32_bf16 v[82:85], v[150:153], v[222:225], v[82:85]
	v_mfma_f32_16x16x32_bf16 v[74:77], v[164:167], v[218:221], v[74:77]
	v_mfma_f32_16x16x32_bf16 v[74:77], v[168:171], v[222:225], v[74:77]
	v_mfma_f32_16x16x32_bf16 v[70:73], v[172:175], v[218:221], v[70:73]
	v_mfma_f32_16x16x32_bf16 v[70:73], v[176:179], v[222:225], v[70:73]
	v_mfma_f32_16x16x32_bf16 v[66:69], v[186:189], v[218:221], v[66:69]
	v_mfma_f32_16x16x32_bf16 v[66:69], v[190:193], v[222:225], v[66:69]
	s_barrier
	s_add_i32 s79, s79, s25
	s_mov_b32 m0, s79
	ds_read_b128 v[194:197], v161 offset:49152
	ds_read_b128 v[198:201], v161 offset:50176
	ds_read_b128 v[202:205], v161 offset:51200
	ds_read_b128 v[206:209], v161 offset:52224
	ds_read_b128 v[210:213], v161 offset:53248
	ds_read_b128 v[214:217], v161 offset:54272
	ds_read_b128 v[218:221], v161 offset:55296
	ds_read_b128 v[222:225], v161 offset:56320
	global_load_lds_dwordx4 v132, s[98:99]
	s_add_i32 m0, s79, 0x2000
	s_add_u32 s80, s88, 0x100080
	s_addc_u32 s81, s89, 0
	s_add_i32 s79, s82, s25
	global_load_lds_dwordx4 v136, s[98:99]
	s_mov_b32 m0, s79
	s_nop 0
	global_load_lds_dwordx4 v132, s[80:81]
	s_add_i32 m0, s79, 0x2000
	s_nop 0
	global_load_lds_dwordx4 v136, s[80:81]
	s_mov_b32 m0, s66
	s_nop 0
	global_load_lds_dwordx4 v130, s[100:101]
	s_mov_b32 m0, s67
	s_nop 0
	global_load_lds_dwordx4 v134, s[100:101]
	s_waitcnt vmcnt(8)
	s_waitcnt lgkmcnt(0)
	s_barrier
	v_mfma_f32_16x16x32_bf16 v[62:65], v[146:149], v[194:197], v[62:65]
	v_mfma_f32_16x16x32_bf16 v[62:65], v[150:153], v[198:201], v[62:65]
	v_mfma_f32_16x16x32_bf16 v[58:61], v[164:167], v[194:197], v[58:61]
	v_mfma_f32_16x16x32_bf16 v[58:61], v[168:171], v[198:201], v[58:61]
	v_mfma_f32_16x16x32_bf16 v[54:57], v[172:175], v[194:197], v[54:57]
	v_mfma_f32_16x16x32_bf16 v[54:57], v[176:179], v[198:201], v[54:57]
	v_mfma_f32_16x16x32_bf16 v[46:49], v[186:189], v[194:197], v[46:49]
	v_mfma_f32_16x16x32_bf16 v[46:49], v[190:193], v[198:201], v[46:49]
	v_mfma_f32_16x16x32_bf16 v[50:53], v[146:149], v[202:205], v[50:53]
	v_mfma_f32_16x16x32_bf16 v[50:53], v[150:153], v[206:209], v[50:53]
	v_mfma_f32_16x16x32_bf16 v[42:45], v[164:167], v[202:205], v[42:45]
	v_mfma_f32_16x16x32_bf16 v[42:45], v[168:171], v[206:209], v[42:45]
	v_mfma_f32_16x16x32_bf16 v[38:41], v[172:175], v[202:205], v[38:41]
	v_mfma_f32_16x16x32_bf16 v[38:41], v[176:179], v[206:209], v[38:41]
	v_mfma_f32_16x16x32_bf16 v[30:33], v[186:189], v[202:205], v[30:33]
	v_mfma_f32_16x16x32_bf16 v[30:33], v[190:193], v[206:209], v[30:33]
	v_mfma_f32_16x16x32_bf16 v[34:37], v[146:149], v[210:213], v[34:37]
	v_mfma_f32_16x16x32_bf16 v[34:37], v[150:153], v[214:217], v[34:37]
	v_mfma_f32_16x16x32_bf16 v[26:29], v[164:167], v[210:213], v[26:29]
	v_mfma_f32_16x16x32_bf16 v[26:29], v[168:171], v[214:217], v[26:29]
	v_mfma_f32_16x16x32_bf16 v[22:25], v[172:175], v[210:213], v[22:25]
	v_mfma_f32_16x16x32_bf16 v[22:25], v[176:179], v[214:217], v[22:25]
	v_mfma_f32_16x16x32_bf16 v[14:17], v[186:189], v[210:213], v[14:17]
	v_mfma_f32_16x16x32_bf16 v[14:17], v[190:193], v[214:217], v[14:17]
	v_mfma_f32_16x16x32_bf16 v[18:21], v[146:149], v[218:221], v[18:21]
	v_mfma_f32_16x16x32_bf16 v[18:21], v[150:153], v[222:225], v[18:21]
	v_mfma_f32_16x16x32_bf16 v[10:13], v[164:167], v[218:221], v[10:13]
	v_mfma_f32_16x16x32_bf16 v[10:13], v[168:171], v[222:225], v[10:13]
	v_mfma_f32_16x16x32_bf16 v[6:9], v[172:175], v[218:221], v[6:9]
	v_mfma_f32_16x16x32_bf16 v[6:9], v[176:179], v[222:225], v[6:9]
	v_mfma_f32_16x16x32_bf16 v[2:5], v[186:189], v[218:221], v[2:5]
	v_mfma_f32_16x16x32_bf16 v[2:5], v[190:193], v[222:225], v[2:5]
	s_barrier
	s_add_i32 s78, s78, 2
	s_add_u32 s6, s6, 0x100
	s_addc_u32 s7, s7, 0
	s_add_u32 s76, s76, 0x100
	s_addc_u32 s77, s77, 0
	s_cmp_gt_u32 s78, 61
	s_cbranch_scc0 .LBB0_1790
	s_setprio 0
	s_and_b64 vcc, exec, s[40:41]
	s_cbranch_vccz .LBB0_1793
	s_barrier

.LBB0_2108:
	s_ashr_i32 s45, s44, 31
	s_lshl_b64 s[46:47], s[44:45], 21
	s_add_u32 s46, s10, s46
	s_addc_u32 s47, s11, s47
	s_and_b64 s[48:49], s[6:7], exec
	s_cselect_b32 s26, s47, s51
	s_cselect_b32 s45, s46, s50
	s_ashr_i32 s43, s42, 31
	s_lshl_b64 s[48:49], s[42:43], 21
	v_readlane_b32 s70, v245, 4
	v_readlane_b32 s71, v245, 5
	s_add_u32 s48, s70, s48
	s_addc_u32 s49, s71, s49
	s_and_b64 s[70:71], s[6:7], exec
	s_cselect_b32 s43, s49, s83
	s_cselect_b32 s70, s48, s82
	s_add_u32 s50, s50, 0x100080
	s_addc_u32 s51, s51, 0
	s_add_u32 s71, s82, 0x100
	v_mov_b32_e32 v2, 0
	s_addc_u32 s72, s83, 0
	s_mov_b32 s73, -2
	s_waitcnt lgkmcnt(0)
	v_mov_b32_e32 v3, v2
	v_mov_b32_e32 v4, v2
	v_mov_b32_e32 v5, v2
	v_mov_b32_e32 v6, v2
	v_mov_b32_e32 v7, v2
	v_mov_b32_e32 v8, v2
	v_mov_b32_e32 v9, v2
	v_mov_b32_e32 v18, v2
	v_mov_b32_e32 v19, v2
	v_mov_b32_e32 v20, v2
	v_mov_b32_e32 v21, v2
	v_mov_b32_e32 v22, v2
	v_mov_b32_e32 v23, v2
	v_mov_b32_e32 v24, v2
	v_mov_b32_e32 v25, v2
	v_mov_b32_e32 v34, v2
	v_mov_b32_e32 v35, v2
	v_mov_b32_e32 v36, v2
	v_mov_b32_e32 v37, v2
	v_mov_b32_e32 v38, v2
	v_mov_b32_e32 v39, v2
	v_mov_b32_e32 v40, v2
	v_mov_b32_e32 v41, v2
	v_mov_b32_e32 v50, v2
	v_mov_b32_e32 v51, v2
	v_mov_b32_e32 v52, v2
	v_mov_b32_e32 v53, v2
	v_mov_b32_e32 v54, v2
	v_mov_b32_e32 v55, v2
	v_mov_b32_e32 v56, v2
	v_mov_b32_e32 v57, v2
	v_mov_b32_e32 v10, v2
	v_mov_b32_e32 v11, v2
	v_mov_b32_e32 v12, v2
	v_mov_b32_e32 v13, v2
	v_mov_b32_e32 v14, v2
	v_mov_b32_e32 v15, v2
	v_mov_b32_e32 v16, v2
	v_mov_b32_e32 v17, v2
	v_mov_b32_e32 v26, v2
	v_mov_b32_e32 v27, v2
	v_mov_b32_e32 v28, v2
	v_mov_b32_e32 v29, v2
	v_mov_b32_e32 v30, v2
	v_mov_b32_e32 v31, v2
	v_mov_b32_e32 v32, v2
	v_mov_b32_e32 v33, v2
	v_mov_b32_e32 v42, v2
	v_mov_b32_e32 v43, v2
	v_mov_b32_e32 v44, v2
	v_mov_b32_e32 v45, v2
	v_mov_b32_e32 v46, v2
	v_mov_b32_e32 v47, v2
	v_mov_b32_e32 v48, v2
	v_mov_b32_e32 v49, v2
	v_mov_b32_e32 v58, v2
	v_mov_b32_e32 v59, v2
	v_mov_b32_e32 v60, v2
	v_mov_b32_e32 v61, v2
	v_mov_b32_e32 v62, v2
	v_mov_b32_e32 v63, v2
	v_mov_b32_e32 v64, v2
	v_mov_b32_e32 v65, v2
	v_mov_b32_e32 v66, v2
	v_mov_b32_e32 v67, v2
	v_mov_b32_e32 v68, v2
	v_mov_b32_e32 v69, v2
	v_mov_b32_e32 v70, v2
	v_mov_b32_e32 v71, v2
	v_mov_b32_e32 v72, v2
	v_mov_b32_e32 v73, v2
	v_mov_b32_e32 v82, v2
	v_mov_b32_e32 v83, v2
	v_mov_b32_e32 v84, v2
	v_mov_b32_e32 v85, v2
	v_mov_b32_e32 v86, v2
	v_mov_b32_e32 v87, v2
	v_mov_b32_e32 v88, v2
	v_mov_b32_e32 v89, v2
	v_mov_b32_e32 v98, v2
	v_mov_b32_e32 v99, v2
	v_mov_b32_e32 v100, v2
	v_mov_b32_e32 v101, v2
	v_mov_b32_e32 v102, v2
	v_mov_b32_e32 v103, v2
	v_mov_b32_e32 v104, v2
	v_mov_b32_e32 v105, v2
	v_mov_b32_e32 v114, v2
	v_mov_b32_e32 v115, v2
	v_mov_b32_e32 v116, v2
	v_mov_b32_e32 v117, v2
	v_mov_b32_e32 v118, v2
	v_mov_b32_e32 v119, v2
	v_mov_b32_e32 v120, v2
	v_mov_b32_e32 v121, v2
	v_mov_b32_e32 v74, v2
	v_mov_b32_e32 v75, v2
	v_mov_b32_e32 v76, v2
	v_mov_b32_e32 v77, v2
	v_mov_b32_e32 v78, v2
	v_mov_b32_e32 v79, v2
	v_mov_b32_e32 v80, v2
	v_mov_b32_e32 v81, v2
	v_mov_b32_e32 v90, v2
	v_mov_b32_e32 v91, v2
	v_mov_b32_e32 v92, v2
	v_mov_b32_e32 v93, v2
	v_mov_b32_e32 v94, v2
	v_mov_b32_e32 v95, v2
	v_mov_b32_e32 v96, v2
	v_mov_b32_e32 v97, v2
	v_mov_b32_e32 v106, v2
	v_mov_b32_e32 v107, v2
	v_mov_b32_e32 v108, v2
	v_mov_b32_e32 v109, v2
	v_mov_b32_e32 v110, v2
	v_mov_b32_e32 v111, v2
	v_mov_b32_e32 v112, v2
	v_mov_b32_e32 v113, v2
	v_mov_b32_e32 v122, v2
	v_mov_b32_e32 v123, v2
	v_mov_b32_e32 v124, v2
	v_mov_b32_e32 v125, v2
	v_mov_b32_e32 v126, v2
	v_mov_b32_e32 v127, v2
	v_mov_b32_e32 v128, v2
	v_mov_b32_e32 v129, v2
	s_and_b64 vcc, exec, s[40:41]
	s_cbranch_vccnz .Lsprio_1
	s_setprio 1
.Lsprio_1:
.LBB0_2109:
	ds_read_b128 v[130:133], v155
	ds_read_b128 v[134:137], v155 offset:1024
	ds_read_b128 v[138:141], v155 offset:2048
	ds_read_b128 v[142:145], v155 offset:3072
	ds_read_b128 v[166:169], v176
	ds_read_b128 v[170:173], v176 offset:1024
	ds_read_b128 v[186:189], v176 offset:2048
	ds_read_b128 v[190:193], v176 offset:3072
	s_add_u32 s74, s50, 0xfff00080
	s_addc_u32 s75, s51, -1
	s_cmp_eq_u32 s73, 60
	s_cselect_b32 s85, s26, s75
	s_cselect_b32 s84, s45, s74
	s_cselect_b32 s83, s43, s72
	s_cselect_b32 s82, s70, s71
	s_add_i32 m0, s23, 0xc000
	ds_read_b128 v[194:197], v177
	ds_read_b128 v[198:201], v177 offset:1024
	ds_read_b128 v[202:205], v177 offset:2048
	ds_read_b128 v[206:209], v177 offset:3072
	ds_read_b128 v[210:213], v177 offset:4096
	ds_read_b128 v[214:217], v177 offset:5120
	ds_read_b128 v[218:221], v177 offset:6144
	ds_read_b128 v[222:225], v177 offset:7168
	global_load_lds_dwordx4 v158, s[50:51]
	s_add_i32 m0, s23, 0xe000
	s_nop 0
	global_load_lds_dwordx4 v160, s[50:51]
	s_waitcnt vmcnt(8)
	s_waitcnt lgkmcnt(0)
	s_barrier
	v_mfma_f32_16x16x32_bf16 v[126:129], v[130:133], v[194:197], v[126:129]
	v_mfma_f32_16x16x32_bf16 v[126:129], v[134:137], v[198:201], v[126:129]
	v_mfma_f32_16x16x32_bf16 v[122:125], v[138:141], v[194:197], v[122:125]
	v_mfma_f32_16x16x32_bf16 v[122:125], v[142:145], v[198:201], v[122:125]
	v_mfma_f32_16x16x32_bf16 v[118:121], v[166:169], v[194:197], v[118:121]
	v_mfma_f32_16x16x32_bf16 v[118:121], v[170:173], v[198:201], v[118:121]
	v_mfma_f32_16x16x32_bf16 v[114:117], v[186:189], v[194:197], v[114:117]
	v_mfma_f32_16x16x32_bf16 v[114:117], v[190:193], v[198:201], v[114:117]
	v_mfma_f32_16x16x32_bf16 v[110:113], v[130:133], v[202:205], v[110:113]
	v_mfma_f32_16x16x32_bf16 v[110:113], v[134:137], v[206:209], v[110:113]
	v_mfma_f32_16x16x32_bf16 v[106:109], v[138:141], v[202:205], v[106:109]
	v_mfma_f32_16x16x32_bf16 v[106:109], v[142:145], v[206:209], v[106:109]
	v_mfma_f32_16x16x32_bf16 v[102:105], v[166:169], v[202:205], v[102:105]
	v_mfma_f32_16x16x32_bf16 v[102:105], v[170:173], v[206:209], v[102:105]
	v_mfma_f32_16x16x32_bf16 v[98:101], v[186:189], v[202:205], v[98:101]
	v_mfma_f32_16x16x32_bf16 v[98:101], v[190:193], v[206:209], v[98:101]
	v_mfma_f32_16x16x32_bf16 v[94:97], v[130:133], v[210:213], v[94:97]
	v_mfma_f32_16x16x32_bf16 v[94:97], v[134:137], v[214:217], v[94:97]
	v_mfma_f32_16x16x32_bf16 v[90:93], v[138:141], v[210:213], v[90:93]
	v_mfma_f32_16x16x32_bf16 v[90:93], v[142:145], v[214:217], v[90:93]
	v_mfma_f32_16x16x32_bf16 v[86:89], v[166:169], v[210:213], v[86:89]
	v_mfma_f32_16x16x32_bf16 v[86:89], v[170:173], v[214:217], v[86:89]
	v_mfma_f32_16x16x32_bf16 v[82:85], v[186:189], v[210:213], v[82:85]
	v_mfma_f32_16x16x32_bf16 v[82:85], v[190:193], v[214:217], v[82:85]
	v_mfma_f32_16x16x32_bf16 v[78:81], v[130:133], v[218:221], v[78:81]
	v_mfma_f32_16x16x32_bf16 v[78:81], v[134:137], v[222:225], v[78:81]
	v_mfma_f32_16x16x32_bf16 v[74:77], v[138:141], v[218:221], v[74:77]
	v_mfma_f32_16x16x32_bf16 v[74:77], v[142:145], v[222:225], v[74:77]
	v_mfma_f32_16x16x32_bf16 v[70:73], v[166:169], v[218:221], v[70:73]
	v_mfma_f32_16x16x32_bf16 v[70:73], v[170:173], v[222:225], v[70:73]
	v_mfma_f32_16x16x32_bf16 v[66:69], v[186:189], v[218:221], v[66:69]
	v_mfma_f32_16x16x32_bf16 v[66:69], v[190:193], v[222:225], v[66:69]
	s_barrier
	s_add_i32 s74, s67, s3
	s_add_u32 s98, s82, 0x80
	s_addc_u32 s99, s83, 0
	s_mov_b32 m0, s74
	ds_read_b128 v[194:197], v177 offset:16384
	ds_read_b128 v[198:201], v177 offset:17408
	ds_read_b128 v[202:205], v177 offset:18432
	ds_read_b128 v[206:209], v177 offset:19456
	ds_read_b128 v[210:213], v177 offset:20480
	ds_read_b128 v[214:217], v177 offset:21504
	ds_read_b128 v[218:221], v177 offset:22528
	ds_read_b128 v[222:225], v177 offset:23552
	global_load_lds_dwordx4 v148, s[82:83]
	s_add_i32 m0, s74, 0x2000
	s_add_u32 s74, s82, 0x100000
	s_addc_u32 s75, s83, 0
	s_add_i32 s76, s68, s3
	global_load_lds_dwordx4 v152, s[82:83]
	s_mov_b32 m0, s76
	global_load_lds_dwordx4 v148, s[74:75]
	s_add_i32 m0, s76, 0x2000
	s_nop 0
	global_load_lds_dwordx4 v152, s[74:75]
	s_add_u32 s100, s84, 0x80
	s_addc_u32 s101, s85, 0
	s_mov_b32 m0, s23
	s_nop 0
	global_load_lds_dwordx4 v146, s[84:85]
	s_mov_b32 m0, s25
	s_nop 0
	global_load_lds_dwordx4 v150, s[84:85]
	s_waitcnt vmcnt(8)
	s_waitcnt lgkmcnt(0)
	s_barrier
	v_mfma_f32_16x16x32_bf16 v[62:65], v[130:133], v[194:197], v[62:65]
	v_mfma_f32_16x16x32_bf16 v[62:65], v[134:137], v[198:201], v[62:65]
	v_mfma_f32_16x16x32_bf16 v[58:61], v[138:141], v[194:197], v[58:61]
	v_mfma_f32_16x16x32_bf16 v[58:61], v[142:145], v[198:201], v[58:61]
	v_mfma_f32_16x16x32_bf16 v[54:57], v[166:169], v[194:197], v[54:57]
	v_mfma_f32_16x16x32_bf16 v[54:57], v[170:173], v[198:201], v[54:57]
	v_mfma_f32_16x16x32_bf16 v[50:53], v[186:189], v[194:197], v[50:53]
	v_mfma_f32_16x16x32_bf16 v[50:53], v[190:193], v[198:201], v[50:53]
	v_mfma_f32_16x16x32_bf16 v[46:49], v[130:133], v[202:205], v[46:49]
	v_mfma_f32_16x16x32_bf16 v[46:49], v[134:137], v[206:209], v[46:49]
	v_mfma_f32_16x16x32_bf16 v[42:45], v[138:141], v[202:205], v[42:45]
	v_mfma_f32_16x16x32_bf16 v[42:45], v[142:145], v[206:209], v[42:45]
	v_mfma_f32_16x16x32_bf16 v[38:41], v[166:169], v[202:205], v[38:41]
	v_mfma_f32_16x16x32_bf16 v[38:41], v[170:173], v[206:209], v[38:41]
	v_mfma_f32_16x16x32_bf16 v[34:37], v[186:189], v[202:205], v[34:37]
	v_mfma_f32_16x16x32_bf16 v[34:37], v[190:193], v[206:209], v[34:37]
	v_mfma_f32_16x16x32_bf16 v[30:33], v[130:133], v[210:213], v[30:33]
	v_mfma_f32_16x16x32_bf16 v[30:33], v[134:137], v[214:217], v[30:33]
	v_mfma_f32_16x16x32_bf16 v[26:29], v[138:141], v[210:213], v[26:29]
	v_mfma_f32_16x16x32_bf16 v[26:29], v[142:145], v[214:217], v[26:29]
	v_mfma_f32_16x16x32_bf16 v[22:25], v[166:169], v[210:213], v[22:25]
	v_mfma_f32_16x16x32_bf16 v[22:25], v[170:173], v[214:217], v[22:25]
	v_mfma_f32_16x16x32_bf16 v[18:21], v[186:189], v[210:213], v[18:21]
	v_mfma_f32_16x16x32_bf16 v[18:21], v[190:193], v[214:217], v[18:21]
	v_mfma_f32_16x16x32_bf16 v[14:17], v[130:133], v[218:221], v[14:17]
	v_mfma_f32_16x16x32_bf16 v[14:17], v[134:137], v[222:225], v[14:17]
	v_mfma_f32_16x16x32_bf16 v[10:13], v[138:141], v[218:221], v[10:13]
	v_mfma_f32_16x16x32_bf16 v[10:13], v[142:145], v[222:225], v[10:13]
	v_mfma_f32_16x16x32_bf16 v[6:9], v[166:169], v[218:221], v[6:9]
	v_mfma_f32_16x16x32_bf16 v[6:9], v[170:173], v[222:225], v[6:9]
	v_mfma_f32_16x16x32_bf16 v[2:5], v[186:189], v[218:221], v[2:5]
	v_mfma_f32_16x16x32_bf16 v[2:5], v[190:193], v[222:225], v[2:5]
	s_barrier
	s_add_i32 s76, 0, 0x18000
	s_add_i32 s77, 0, 0x1c000
	v_add_u32_e32 v142, s76, v174
	v_add_u32_e32 v179, s77, v174
	ds_read_b128 v[130:133], v142
	ds_read_b128 v[134:137], v142 offset:1024
	ds_read_b128 v[138:141], v142 offset:2048
	ds_read_b128 v[142:145], v142 offset:3072
	ds_read_b128 v[166:169], v179
	ds_read_b128 v[170:173], v179 offset:1024
	ds_read_b128 v[186:189], v179 offset:2048
	ds_read_b128 v[190:193], v179 offset:3072
	s_add_u32 s74, s84, 0x100000
	s_addc_u32 s75, s85, 0
	s_mov_b32 m0, s33
	ds_read_b128 v[194:197], v177 offset:32768
	ds_read_b128 v[198:201], v177 offset:33792
	ds_read_b128 v[202:205], v177 offset:34816
	ds_read_b128 v[206:209], v177 offset:35840
	ds_read_b128 v[210:213], v177 offset:36864
	ds_read_b128 v[214:217], v177 offset:37888
	ds_read_b128 v[218:221], v177 offset:38912
	ds_read_b128 v[222:225], v177 offset:39936
	global_load_lds_dwordx4 v146, s[74:75]
	s_mov_b32 m0, s35
	s_nop 0
	global_load_lds_dwordx4 v150, s[74:75]
	s_waitcnt vmcnt(8)
	s_waitcnt lgkmcnt(0)
	s_barrier
	v_mfma_f32_16x16x32_bf16 v[126:129], v[130:133], v[194:197], v[126:129]
	v_mfma_f32_16x16x32_bf16 v[126:129], v[134:137], v[198:201], v[126:129]
	v_mfma_f32_16x16x32_bf16 v[122:125], v[138:141], v[194:197], v[122:125]
	v_mfma_f32_16x16x32_bf16 v[122:125], v[142:145], v[198:201], v[122:125]
	v_mfma_f32_16x16x32_bf16 v[118:121], v[166:169], v[194:197], v[118:121]
	v_mfma_f32_16x16x32_bf16 v[118:121], v[170:173], v[198:201], v[118:121]
	v_mfma_f32_16x16x32_bf16 v[114:117], v[186:189], v[194:197], v[114:117]
	v_mfma_f32_16x16x32_bf16 v[114:117], v[190:193], v[198:201], v[114:117]
	v_mfma_f32_16x16x32_bf16 v[110:113], v[130:133], v[202:205], v[110:113]
	v_mfma_f32_16x16x32_bf16 v[110:113], v[134:137], v[206:209], v[110:113]
	v_mfma_f32_16x16x32_bf16 v[106:109], v[138:141], v[202:205], v[106:109]
	v_mfma_f32_16x16x32_bf16 v[106:109], v[142:145], v[206:209], v[106:109]
	v_mfma_f32_16x16x32_bf16 v[102:105], v[166:169], v[202:205], v[102:105]
	v_mfma_f32_16x16x32_bf16 v[102:105], v[170:173], v[206:209], v[102:105]
	v_mfma_f32_16x16x32_bf16 v[98:101], v[186:189], v[202:205], v[98:101]
	v_mfma_f32_16x16x32_bf16 v[98:101], v[190:193], v[206:209], v[98:101]
	v_mfma_f32_16x16x32_bf16 v[94:97], v[130:133], v[210:213], v[94:97]
	v_mfma_f32_16x16x32_bf16 v[94:97], v[134:137], v[214:217], v[94:97]
	v_mfma_f32_16x16x32_bf16 v[90:93], v[138:141], v[210:213], v[90:93]
	v_mfma_f32_16x16x32_bf16 v[90:93], v[142:145], v[214:217], v[90:93]
	v_mfma_f32_16x16x32_bf16 v[86:89], v[166:169], v[210:213], v[86:89]
	v_mfma_f32_16x16x32_bf16 v[86:89], v[170:173], v[214:217], v[86:89]
	v_mfma_f32_16x16x32_bf16 v[82:85], v[186:189], v[210:213], v[82:85]
	v_mfma_f32_16x16x32_bf16 v[82:85], v[190:193], v[214:217], v[82:85]
	v_mfma_f32_16x16x32_bf16 v[78:81], v[130:133], v[218:221], v[78:81]
	v_mfma_f32_16x16x32_bf16 v[78:81], v[134:137], v[222:225], v[78:81]
	v_mfma_f32_16x16x32_bf16 v[74:77], v[138:141], v[218:221], v[74:77]
	v_mfma_f32_16x16x32_bf16 v[74:77], v[142:145], v[222:225], v[74:77]
	v_mfma_f32_16x16x32_bf16 v[70:73], v[166:169], v[218:221], v[70:73]
	v_mfma_f32_16x16x32_bf16 v[70:73], v[170:173], v[222:225], v[70:73]
	v_mfma_f32_16x16x32_bf16 v[66:69], v[186:189], v[218:221], v[66:69]
	v_mfma_f32_16x16x32_bf16 v[66:69], v[190:193], v[222:225], v[66:69]
	s_barrier
	s_add_i32 s74, s76, s3
	s_mov_b32 m0, s74
	ds_read_b128 v[194:197], v177 offset:49152
	ds_read_b128 v[198:201], v177 offset:50176
	ds_read_b128 v[202:205], v177 offset:51200
	ds_read_b128 v[206:209], v177 offset:52224
	ds_read_b128 v[210:213], v177 offset:53248
	ds_read_b128 v[214:217], v177 offset:54272
	ds_read_b128 v[218:221], v177 offset:55296
	ds_read_b128 v[222:225], v177 offset:56320
	global_load_lds_dwordx4 v148, s[98:99]
	s_add_i32 m0, s74, 0x2000
	s_add_u32 s74, s82, 0x100080
	s_addc_u32 s75, s83, 0
	s_add_i32 s76, s77, s3
	global_load_lds_dwordx4 v152, s[98:99]
	s_mov_b32 m0, s76
	s_nop 0
	global_load_lds_dwordx4 v148, s[74:75]
	s_add_i32 m0, s76, 0x2000
	s_nop 0
	global_load_lds_dwordx4 v152, s[74:75]
	s_mov_b32 m0, s62
	s_nop 0
	global_load_lds_dwordx4 v146, s[100:101]
	s_mov_b32 m0, s63
	s_nop 0
	global_load_lds_dwordx4 v150, s[100:101]
	s_waitcnt vmcnt(8)
	s_waitcnt lgkmcnt(0)
	s_barrier
	v_mfma_f32_16x16x32_bf16 v[62:65], v[130:133], v[194:197], v[62:65]
	v_mfma_f32_16x16x32_bf16 v[62:65], v[134:137], v[198:201], v[62:65]
	v_mfma_f32_16x16x32_bf16 v[58:61], v[138:141], v[194:197], v[58:61]
	v_mfma_f32_16x16x32_bf16 v[58:61], v[142:145], v[198:201], v[58:61]
	v_mfma_f32_16x16x32_bf16 v[54:57], v[166:169], v[194:197], v[54:57]
	v_mfma_f32_16x16x32_bf16 v[54:57], v[170:173], v[198:201], v[54:57]
	v_mfma_f32_16x16x32_bf16 v[50:53], v[186:189], v[194:197], v[50:53]
	v_mfma_f32_16x16x32_bf16 v[50:53], v[190:193], v[198:201], v[50:53]
	v_mfma_f32_16x16x32_bf16 v[46:49], v[130:133], v[202:205], v[46:49]
	v_mfma_f32_16x16x32_bf16 v[46:49], v[134:137], v[206:209], v[46:49]
	v_mfma_f32_16x16x32_bf16 v[42:45], v[138:141], v[202:205], v[42:45]
	v_mfma_f32_16x16x32_bf16 v[42:45], v[142:145], v[206:209], v[42:45]
	v_mfma_f32_16x16x32_bf16 v[38:41], v[166:169], v[202:205], v[38:41]
	v_mfma_f32_16x16x32_bf16 v[38:41], v[170:173], v[206:209], v[38:41]
	v_mfma_f32_16x16x32_bf16 v[34:37], v[186:189], v[202:205], v[34:37]
	v_mfma_f32_16x16x32_bf16 v[34:37], v[190:193], v[206:209], v[34:37]
	v_mfma_f32_16x16x32_bf16 v[30:33], v[130:133], v[210:213], v[30:33]
	v_mfma_f32_16x16x32_bf16 v[30:33], v[134:137], v[214:217], v[30:33]
	v_mfma_f32_16x16x32_bf16 v[26:29], v[138:141], v[210:213], v[26:29]
	v_mfma_f32_16x16x32_bf16 v[26:29], v[142:145], v[214:217], v[26:29]
	v_mfma_f32_16x16x32_bf16 v[22:25], v[166:169], v[210:213], v[22:25]
	v_mfma_f32_16x16x32_bf16 v[22:25], v[170:173], v[214:217], v[22:25]
	v_mfma_f32_16x16x32_bf16 v[18:21], v[186:189], v[210:213], v[18:21]
	v_mfma_f32_16x16x32_bf16 v[18:21], v[190:193], v[214:217], v[18:21]
	v_mfma_f32_16x16x32_bf16 v[14:17], v[130:133], v[218:221], v[14:17]
	v_mfma_f32_16x16x32_bf16 v[14:17], v[134:137], v[222:225], v[14:17]
	v_mfma_f32_16x16x32_bf16 v[10:13], v[138:141], v[218:221], v[10:13]
	v_mfma_f32_16x16x32_bf16 v[10:13], v[142:145], v[222:225], v[10:13]
	v_mfma_f32_16x16x32_bf16 v[6:9], v[166:169], v[218:221], v[6:9]
	v_mfma_f32_16x16x32_bf16 v[6:9], v[170:173], v[222:225], v[6:9]
	v_mfma_f32_16x16x32_bf16 v[2:5], v[186:189], v[218:221], v[2:5]
	v_mfma_f32_16x16x32_bf16 v[2:5], v[190:193], v[222:225], v[2:5]
	s_barrier
	s_add_i32 s73, s73, 2
	s_add_u32 s50, s50, 0x100
	s_addc_u32 s51, s51, 0
	s_add_u32 s71, s71, 0x100
	s_addc_u32 s72, s72, 0
	s_cmp_gt_u32 s73, 61
	s_cbranch_scc0 .LBB0_2109
	s_setprio 0
	s_and_b64 vcc, exec, s[40:41]
	s_cbranch_vccz .LBB0_2112
	s_barrier

.LBB0_2211:
	s_ashr_i32 s45, s44, 31
	s_lshl_b64 s[46:47], s[44:45], 21
	s_add_u32 s46, s16, s46
	s_addc_u32 s47, s17, s47
	s_and_b64 s[48:49], s[4:5], exec
	s_cselect_b32 s45, s47, s7
	s_cselect_b32 s75, s46, s6
	s_ashr_i32 s43, s42, 31
	s_lshl_b64 s[48:49], s[42:43], 21
	v_readlane_b32 s76, v245, 6
	v_readlane_b32 s77, v245, 7
	s_add_u32 s48, s76, s48
	s_addc_u32 s49, s77, s49
	s_and_b64 s[76:77], s[4:5], exec
	s_cselect_b32 s43, s49, s51
	s_cselect_b32 s76, s48, s50
	s_add_u32 s6, s6, 0x100080
	s_addc_u32 s7, s7, 0
	s_add_u32 s77, s50, 0x100
	v_mov_b32_e32 v2, 0
	s_addc_u32 s78, s51, 0
	s_mov_b32 s79, -2
	v_mov_b32_e32 v3, v2
	v_mov_b32_e32 v4, v2
	v_mov_b32_e32 v5, v2
	v_mov_b32_e32 v10, v2
	v_mov_b32_e32 v11, v2
	v_mov_b32_e32 v12, v2
	v_mov_b32_e32 v13, v2
	v_mov_b32_e32 v18, v2
	v_mov_b32_e32 v19, v2
	v_mov_b32_e32 v20, v2
	v_mov_b32_e32 v21, v2
	v_mov_b32_e32 v26, v2
	v_mov_b32_e32 v27, v2
	v_mov_b32_e32 v28, v2
	v_mov_b32_e32 v29, v2
	v_mov_b32_e32 v34, v2
	v_mov_b32_e32 v35, v2
	v_mov_b32_e32 v36, v2
	v_mov_b32_e32 v37, v2
	v_mov_b32_e32 v42, v2
	v_mov_b32_e32 v43, v2
	v_mov_b32_e32 v44, v2
	v_mov_b32_e32 v45, v2
	v_mov_b32_e32 v50, v2
	v_mov_b32_e32 v51, v2
	v_mov_b32_e32 v52, v2
	v_mov_b32_e32 v53, v2
	v_mov_b32_e32 v58, v2
	v_mov_b32_e32 v59, v2
	v_mov_b32_e32 v60, v2
	v_mov_b32_e32 v61, v2
	v_mov_b32_e32 v6, v2
	v_mov_b32_e32 v7, v2
	v_mov_b32_e32 v8, v2
	v_mov_b32_e32 v9, v2
	v_mov_b32_e32 v14, v2
	v_mov_b32_e32 v15, v2
	v_mov_b32_e32 v16, v2
	v_mov_b32_e32 v17, v2
	v_mov_b32_e32 v22, v2
	v_mov_b32_e32 v23, v2
	v_mov_b32_e32 v24, v2
	v_mov_b32_e32 v25, v2
	v_mov_b32_e32 v30, v2
	v_mov_b32_e32 v31, v2
	v_mov_b32_e32 v32, v2
	v_mov_b32_e32 v33, v2
	v_mov_b32_e32 v38, v2
	v_mov_b32_e32 v39, v2
	v_mov_b32_e32 v40, v2
	v_mov_b32_e32 v41, v2
	v_mov_b32_e32 v46, v2
	v_mov_b32_e32 v47, v2
	v_mov_b32_e32 v48, v2
	v_mov_b32_e32 v49, v2
	v_mov_b32_e32 v54, v2
	v_mov_b32_e32 v55, v2
	v_mov_b32_e32 v56, v2
	v_mov_b32_e32 v57, v2
	v_mov_b32_e32 v62, v2
	v_mov_b32_e32 v63, v2
	v_mov_b32_e32 v64, v2
	v_mov_b32_e32 v65, v2
	v_mov_b32_e32 v66, v2
	v_mov_b32_e32 v67, v2
	v_mov_b32_e32 v68, v2
	v_mov_b32_e32 v69, v2
	v_mov_b32_e32 v74, v2
	v_mov_b32_e32 v75, v2
	v_mov_b32_e32 v76, v2
	v_mov_b32_e32 v77, v2
	v_mov_b32_e32 v82, v2
	v_mov_b32_e32 v83, v2
	v_mov_b32_e32 v84, v2
	v_mov_b32_e32 v85, v2
	v_mov_b32_e32 v90, v2
	v_mov_b32_e32 v91, v2
	v_mov_b32_e32 v92, v2
	v_mov_b32_e32 v93, v2
	v_mov_b32_e32 v98, v2
	v_mov_b32_e32 v99, v2
	v_mov_b32_e32 v100, v2
	v_mov_b32_e32 v101, v2
	v_mov_b32_e32 v106, v2
	v_mov_b32_e32 v107, v2
	v_mov_b32_e32 v108, v2
	v_mov_b32_e32 v109, v2
	v_mov_b32_e32 v114, v2
	v_mov_b32_e32 v115, v2
	v_mov_b32_e32 v116, v2
	v_mov_b32_e32 v117, v2
	v_mov_b32_e32 v122, v2
	v_mov_b32_e32 v123, v2
	v_mov_b32_e32 v124, v2
	v_mov_b32_e32 v125, v2
	v_mov_b32_e32 v70, v2
	v_mov_b32_e32 v71, v2
	v_mov_b32_e32 v72, v2
	v_mov_b32_e32 v73, v2
	v_mov_b32_e32 v78, v2
	v_mov_b32_e32 v79, v2
	v_mov_b32_e32 v80, v2
	v_mov_b32_e32 v81, v2
	v_mov_b32_e32 v86, v2
	v_mov_b32_e32 v87, v2
	v_mov_b32_e32 v88, v2
	v_mov_b32_e32 v89, v2
	v_mov_b32_e32 v94, v2
	v_mov_b32_e32 v95, v2
	v_mov_b32_e32 v96, v2
	v_mov_b32_e32 v97, v2
	v_mov_b32_e32 v102, v2
	v_mov_b32_e32 v103, v2
	v_mov_b32_e32 v104, v2
	v_mov_b32_e32 v105, v2
	v_mov_b32_e32 v110, v2
	v_mov_b32_e32 v111, v2
	v_mov_b32_e32 v112, v2
	v_mov_b32_e32 v113, v2
	v_mov_b32_e32 v118, v2
	v_mov_b32_e32 v119, v2
	v_mov_b32_e32 v120, v2
	v_mov_b32_e32 v121, v2
	v_mov_b32_e32 v126, v2
	v_mov_b32_e32 v127, v2
	v_mov_b32_e32 v128, v2
	v_mov_b32_e32 v129, v2
	s_and_b64 vcc, exec, s[40:41]
	s_cbranch_vccnz .Lsprio_2
	s_setprio 1
.Lsprio_2:
.LBB0_2212:
	ds_read_b128 v[150:153], v162
	ds_read_b128 v[168:171], v162 offset:1024
	ds_read_b128 v[172:175], v162 offset:2048
	ds_read_b128 v[176:179], v162 offset:3072
	ds_read_b128 v[186:189], v163
	ds_read_b128 v[190:193], v163 offset:1024
	ds_read_b128 v[194:197], v163 offset:2048
	ds_read_b128 v[198:201], v163 offset:3072
	s_add_u32 s50, s6, 0xfff00080
	s_addc_u32 s51, s7, -1
	s_cmp_eq_u32 s79, 60
	s_cselect_b32 s81, s45, s51
	s_cselect_b32 s80, s75, s50
	s_cselect_b32 s51, s43, s78
	s_cselect_b32 s50, s76, s77
	s_add_i32 m0, s33, 0xc000
	ds_read_b128 v[202:205], v164
	ds_read_b128 v[206:209], v164 offset:1024
	ds_read_b128 v[210:213], v164 offset:2048
	ds_read_b128 v[214:217], v164 offset:3072
	ds_read_b128 v[218:221], v164 offset:4096
	ds_read_b128 v[222:225], v164 offset:5120
	ds_read_b128 v[226:229], v164 offset:6144
	ds_read_b128 v[230:233], v164 offset:7168
	global_load_lds_dwordx4 v142, s[6:7]
	s_add_i32 m0, s33, 0xe000
	s_nop 0
	global_load_lds_dwordx4 v144, s[6:7]
	s_waitcnt vmcnt(8)
	s_waitcnt lgkmcnt(0)
	s_barrier
	v_mfma_f32_16x16x32_bf16 v[126:129], v[150:153], v[202:205], v[126:129]
	v_mfma_f32_16x16x32_bf16 v[126:129], v[168:171], v[206:209], v[126:129]
	v_mfma_f32_16x16x32_bf16 v[118:121], v[172:175], v[202:205], v[118:121]
	v_mfma_f32_16x16x32_bf16 v[118:121], v[176:179], v[206:209], v[118:121]
	v_mfma_f32_16x16x32_bf16 v[122:125], v[186:189], v[202:205], v[122:125]
	v_mfma_f32_16x16x32_bf16 v[122:125], v[190:193], v[206:209], v[122:125]
	v_mfma_f32_16x16x32_bf16 v[114:117], v[194:197], v[202:205], v[114:117]
	v_mfma_f32_16x16x32_bf16 v[114:117], v[198:201], v[206:209], v[114:117]
	v_mfma_f32_16x16x32_bf16 v[110:113], v[150:153], v[210:213], v[110:113]
	v_mfma_f32_16x16x32_bf16 v[110:113], v[168:171], v[214:217], v[110:113]
	v_mfma_f32_16x16x32_bf16 v[102:105], v[172:175], v[210:213], v[102:105]
	v_mfma_f32_16x16x32_bf16 v[102:105], v[176:179], v[214:217], v[102:105]
	v_mfma_f32_16x16x32_bf16 v[106:109], v[186:189], v[210:213], v[106:109]
	v_mfma_f32_16x16x32_bf16 v[106:109], v[190:193], v[214:217], v[106:109]
	v_mfma_f32_16x16x32_bf16 v[98:101], v[194:197], v[210:213], v[98:101]
	v_mfma_f32_16x16x32_bf16 v[98:101], v[198:201], v[214:217], v[98:101]
	v_mfma_f32_16x16x32_bf16 v[94:97], v[150:153], v[218:221], v[94:97]
	v_mfma_f32_16x16x32_bf16 v[94:97], v[168:171], v[222:225], v[94:97]
	v_mfma_f32_16x16x32_bf16 v[86:89], v[172:175], v[218:221], v[86:89]
	v_mfma_f32_16x16x32_bf16 v[86:89], v[176:179], v[222:225], v[86:89]
	v_mfma_f32_16x16x32_bf16 v[90:93], v[186:189], v[218:221], v[90:93]
	v_mfma_f32_16x16x32_bf16 v[90:93], v[190:193], v[222:225], v[90:93]
	v_mfma_f32_16x16x32_bf16 v[82:85], v[194:197], v[218:221], v[82:85]
	v_mfma_f32_16x16x32_bf16 v[82:85], v[198:201], v[222:225], v[82:85]
	v_mfma_f32_16x16x32_bf16 v[78:81], v[150:153], v[226:229], v[78:81]
	v_mfma_f32_16x16x32_bf16 v[78:81], v[168:171], v[230:233], v[78:81]
	v_mfma_f32_16x16x32_bf16 v[70:73], v[172:175], v[226:229], v[70:73]
	v_mfma_f32_16x16x32_bf16 v[70:73], v[176:179], v[230:233], v[70:73]
	v_mfma_f32_16x16x32_bf16 v[74:77], v[186:189], v[226:229], v[74:77]
	v_mfma_f32_16x16x32_bf16 v[74:77], v[190:193], v[230:233], v[74:77]
	v_mfma_f32_16x16x32_bf16 v[66:69], v[194:197], v[226:229], v[66:69]
	v_mfma_f32_16x16x32_bf16 v[66:69], v[198:201], v[230:233], v[66:69]
	s_barrier
	s_add_i32 s82, s68, s29
	s_add_u32 s98, s50, 0x80
	s_addc_u32 s99, s51, 0
	s_mov_b32 m0, s82
	ds_read_b128 v[202:205], v164 offset:16384
	ds_read_b128 v[206:209], v164 offset:17408
	ds_read_b128 v[210:213], v164 offset:18432
	ds_read_b128 v[214:217], v164 offset:19456
	ds_read_b128 v[218:221], v164 offset:20480
	ds_read_b128 v[222:225], v164 offset:21504
	ds_read_b128 v[226:229], v164 offset:22528
	ds_read_b128 v[230:233], v164 offset:23552
	global_load_lds_dwordx4 v134, s[50:51]
	s_add_i32 m0, s82, 0x2000
	s_add_u32 s82, s50, 0x100000
	s_addc_u32 s83, s51, 0
	s_add_i32 s84, s69, s29
	global_load_lds_dwordx4 v138, s[50:51]
	s_mov_b32 m0, s84
	global_load_lds_dwordx4 v134, s[82:83]
	s_add_i32 m0, s84, 0x2000
	s_nop 0
	global_load_lds_dwordx4 v138, s[82:83]
	s_add_u32 s100, s80, 0x80
	s_addc_u32 s101, s81, 0
	s_mov_b32 m0, s33
	s_nop 0
	global_load_lds_dwordx4 v132, s[80:81]
	s_mov_b32 m0, s35
	s_nop 0
	global_load_lds_dwordx4 v136, s[80:81]
	s_waitcnt vmcnt(8)
	s_waitcnt lgkmcnt(0)
	s_barrier
	v_mfma_f32_16x16x32_bf16 v[62:65], v[150:153], v[202:205], v[62:65]
	v_mfma_f32_16x16x32_bf16 v[62:65], v[168:171], v[206:209], v[62:65]
	v_mfma_f32_16x16x32_bf16 v[54:57], v[172:175], v[202:205], v[54:57]
	v_mfma_f32_16x16x32_bf16 v[54:57], v[176:179], v[206:209], v[54:57]
	v_mfma_f32_16x16x32_bf16 v[58:61], v[186:189], v[202:205], v[58:61]
	v_mfma_f32_16x16x32_bf16 v[58:61], v[190:193], v[206:209], v[58:61]
	v_mfma_f32_16x16x32_bf16 v[50:53], v[194:197], v[202:205], v[50:53]
	v_mfma_f32_16x16x32_bf16 v[50:53], v[198:201], v[206:209], v[50:53]
	v_mfma_f32_16x16x32_bf16 v[46:49], v[150:153], v[210:213], v[46:49]
	v_mfma_f32_16x16x32_bf16 v[46:49], v[168:171], v[214:217], v[46:49]
	v_mfma_f32_16x16x32_bf16 v[38:41], v[172:175], v[210:213], v[38:41]
	v_mfma_f32_16x16x32_bf16 v[38:41], v[176:179], v[214:217], v[38:41]
	v_mfma_f32_16x16x32_bf16 v[42:45], v[186:189], v[210:213], v[42:45]
	v_mfma_f32_16x16x32_bf16 v[42:45], v[190:193], v[214:217], v[42:45]
	v_mfma_f32_16x16x32_bf16 v[34:37], v[194:197], v[210:213], v[34:37]
	v_mfma_f32_16x16x32_bf16 v[34:37], v[198:201], v[214:217], v[34:37]
	v_mfma_f32_16x16x32_bf16 v[30:33], v[150:153], v[218:221], v[30:33]
	v_mfma_f32_16x16x32_bf16 v[30:33], v[168:171], v[222:225], v[30:33]
	v_mfma_f32_16x16x32_bf16 v[22:25], v[172:175], v[218:221], v[22:25]
	v_mfma_f32_16x16x32_bf16 v[22:25], v[176:179], v[222:225], v[22:25]
	v_mfma_f32_16x16x32_bf16 v[26:29], v[186:189], v[218:221], v[26:29]
	v_mfma_f32_16x16x32_bf16 v[26:29], v[190:193], v[222:225], v[26:29]
	v_mfma_f32_16x16x32_bf16 v[18:21], v[194:197], v[218:221], v[18:21]
	v_mfma_f32_16x16x32_bf16 v[18:21], v[198:201], v[222:225], v[18:21]
	v_mfma_f32_16x16x32_bf16 v[14:17], v[150:153], v[226:229], v[14:17]
	v_mfma_f32_16x16x32_bf16 v[14:17], v[168:171], v[230:233], v[14:17]
	v_mfma_f32_16x16x32_bf16 v[6:9], v[172:175], v[226:229], v[6:9]
	v_mfma_f32_16x16x32_bf16 v[6:9], v[176:179], v[230:233], v[6:9]
	v_mfma_f32_16x16x32_bf16 v[10:13], v[186:189], v[226:229], v[10:13]
	v_mfma_f32_16x16x32_bf16 v[10:13], v[190:193], v[230:233], v[10:13]
	v_mfma_f32_16x16x32_bf16 v[2:5], v[194:197], v[226:229], v[2:5]
	v_mfma_f32_16x16x32_bf16 v[2:5], v[198:201], v[230:233], v[2:5]
	s_barrier
	s_add_i32 s82, 0, 0x18000
	v_add_u32_e32 v140, s82, v158
	s_add_i32 s83, 0, 0x1c000
	ds_read_b128 v[150:153], v140
	ds_read_b128 v[168:171], v140 offset:1024
	ds_read_b128 v[172:175], v140 offset:2048
	ds_read_b128 v[176:179], v140 offset:3072
	v_add_u32_e32 v140, s83, v158
	ds_read_b128 v[186:189], v140
	ds_read_b128 v[190:193], v140 offset:1024
	ds_read_b128 v[194:197], v140 offset:2048
	ds_read_b128 v[198:201], v140 offset:3072
	s_add_u32 s80, s80, 0x100000
	s_addc_u32 s81, s81, 0
	s_mov_b32 m0, s59
	ds_read_b128 v[202:205], v164 offset:32768
	ds_read_b128 v[206:209], v164 offset:33792
	ds_read_b128 v[210:213], v164 offset:34816
	ds_read_b128 v[214:217], v164 offset:35840
	ds_read_b128 v[218:221], v164 offset:36864
	ds_read_b128 v[222:225], v164 offset:37888
	ds_read_b128 v[226:229], v164 offset:38912
	ds_read_b128 v[230:233], v164 offset:39936
	global_load_lds_dwordx4 v132, s[80:81]
	s_mov_b32 m0, s62
	s_nop 0
	global_load_lds_dwordx4 v136, s[80:81]
	s_waitcnt vmcnt(8)
	s_waitcnt lgkmcnt(0)
	s_barrier
	v_mfma_f32_16x16x32_bf16 v[126:129], v[150:153], v[202:205], v[126:129]
	v_mfma_f32_16x16x32_bf16 v[126:129], v[168:171], v[206:209], v[126:129]
	v_mfma_f32_16x16x32_bf16 v[118:121], v[172:175], v[202:205], v[118:121]
	v_mfma_f32_16x16x32_bf16 v[118:121], v[176:179], v[206:209], v[118:121]
	v_mfma_f32_16x16x32_bf16 v[122:125], v[186:189], v[202:205], v[122:125]
	v_mfma_f32_16x16x32_bf16 v[122:125], v[190:193], v[206:209], v[122:125]
	v_mfma_f32_16x16x32_bf16 v[114:117], v[194:197], v[202:205], v[114:117]
	v_mfma_f32_16x16x32_bf16 v[114:117], v[198:201], v[206:209], v[114:117]
	v_mfma_f32_16x16x32_bf16 v[110:113], v[150:153], v[210:213], v[110:113]
	v_mfma_f32_16x16x32_bf16 v[110:113], v[168:171], v[214:217], v[110:113]
	v_mfma_f32_16x16x32_bf16 v[102:105], v[172:175], v[210:213], v[102:105]
	v_mfma_f32_16x16x32_bf16 v[102:105], v[176:179], v[214:217], v[102:105]
	v_mfma_f32_16x16x32_bf16 v[106:109], v[186:189], v[210:213], v[106:109]
	v_mfma_f32_16x16x32_bf16 v[106:109], v[190:193], v[214:217], v[106:109]
	v_mfma_f32_16x16x32_bf16 v[98:101], v[194:197], v[210:213], v[98:101]
	v_mfma_f32_16x16x32_bf16 v[98:101], v[198:201], v[214:217], v[98:101]
	v_mfma_f32_16x16x32_bf16 v[94:97], v[150:153], v[218:221], v[94:97]
	v_mfma_f32_16x16x32_bf16 v[94:97], v[168:171], v[222:225], v[94:97]
	v_mfma_f32_16x16x32_bf16 v[86:89], v[172:175], v[218:221], v[86:89]
	v_mfma_f32_16x16x32_bf16 v[86:89], v[176:179], v[222:225], v[86:89]
	v_mfma_f32_16x16x32_bf16 v[90:93], v[186:189], v[218:221], v[90:93]
	v_mfma_f32_16x16x32_bf16 v[90:93], v[190:193], v[222:225], v[90:93]
	v_mfma_f32_16x16x32_bf16 v[82:85], v[194:197], v[218:221], v[82:85]
	v_mfma_f32_16x16x32_bf16 v[82:85], v[198:201], v[222:225], v[82:85]
	v_mfma_f32_16x16x32_bf16 v[78:81], v[150:153], v[226:229], v[78:81]
	v_mfma_f32_16x16x32_bf16 v[78:81], v[168:171], v[230:233], v[78:81]
	v_mfma_f32_16x16x32_bf16 v[70:73], v[172:175], v[226:229], v[70:73]
	v_mfma_f32_16x16x32_bf16 v[70:73], v[176:179], v[230:233], v[70:73]
	v_mfma_f32_16x16x32_bf16 v[74:77], v[186:189], v[226:229], v[74:77]
	v_mfma_f32_16x16x32_bf16 v[74:77], v[190:193], v[230:233], v[74:77]
	v_mfma_f32_16x16x32_bf16 v[66:69], v[194:197], v[226:229], v[66:69]
	v_mfma_f32_16x16x32_bf16 v[66:69], v[198:201], v[230:233], v[66:69]
	s_barrier
	s_add_i32 s80, s82, s29
	s_mov_b32 m0, s80
	ds_read_b128 v[202:205], v164 offset:49152
	ds_read_b128 v[206:209], v164 offset:50176
	ds_read_b128 v[210:213], v164 offset:51200
	ds_read_b128 v[214:217], v164 offset:52224
	ds_read_b128 v[218:221], v164 offset:53248
	ds_read_b128 v[222:225], v164 offset:54272
	ds_read_b128 v[226:229], v164 offset:55296
	ds_read_b128 v[230:233], v164 offset:56320
	global_load_lds_dwordx4 v134, s[98:99]
	s_add_i32 m0, s80, 0x2000
	s_add_u32 s50, s50, 0x100080
	s_addc_u32 s51, s51, 0
	s_add_i32 s80, s83, s29
	global_load_lds_dwordx4 v138, s[98:99]
	s_mov_b32 m0, s80
	s_nop 0
	global_load_lds_dwordx4 v134, s[50:51]
	s_add_i32 m0, s80, 0x2000
	s_nop 0
	global_load_lds_dwordx4 v138, s[50:51]
	s_mov_b32 m0, s65
	s_nop 0
	global_load_lds_dwordx4 v132, s[100:101]
	s_mov_b32 m0, s66
	s_nop 0
	global_load_lds_dwordx4 v136, s[100:101]
	s_waitcnt vmcnt(8)
	s_waitcnt lgkmcnt(0)
	s_barrier
	v_mfma_f32_16x16x32_bf16 v[62:65], v[150:153], v[202:205], v[62:65]
	v_mfma_f32_16x16x32_bf16 v[62:65], v[168:171], v[206:209], v[62:65]
	v_mfma_f32_16x16x32_bf16 v[54:57], v[172:175], v[202:205], v[54:57]
	v_mfma_f32_16x16x32_bf16 v[54:57], v[176:179], v[206:209], v[54:57]
	v_mfma_f32_16x16x32_bf16 v[58:61], v[186:189], v[202:205], v[58:61]
	v_mfma_f32_16x16x32_bf16 v[58:61], v[190:193], v[206:209], v[58:61]
	v_mfma_f32_16x16x32_bf16 v[50:53], v[194:197], v[202:205], v[50:53]
	v_mfma_f32_16x16x32_bf16 v[50:53], v[198:201], v[206:209], v[50:53]
	v_mfma_f32_16x16x32_bf16 v[46:49], v[150:153], v[210:213], v[46:49]
	v_mfma_f32_16x16x32_bf16 v[46:49], v[168:171], v[214:217], v[46:49]
	v_mfma_f32_16x16x32_bf16 v[38:41], v[172:175], v[210:213], v[38:41]
	v_mfma_f32_16x16x32_bf16 v[38:41], v[176:179], v[214:217], v[38:41]
	v_mfma_f32_16x16x32_bf16 v[42:45], v[186:189], v[210:213], v[42:45]
	v_mfma_f32_16x16x32_bf16 v[42:45], v[190:193], v[214:217], v[42:45]
	v_mfma_f32_16x16x32_bf16 v[34:37], v[194:197], v[210:213], v[34:37]
	v_mfma_f32_16x16x32_bf16 v[34:37], v[198:201], v[214:217], v[34:37]
	v_mfma_f32_16x16x32_bf16 v[30:33], v[150:153], v[218:221], v[30:33]
	v_mfma_f32_16x16x32_bf16 v[30:33], v[168:171], v[222:225], v[30:33]
	v_mfma_f32_16x16x32_bf16 v[22:25], v[172:175], v[218:221], v[22:25]
	v_mfma_f32_16x16x32_bf16 v[22:25], v[176:179], v[222:225], v[22:25]
	v_mfma_f32_16x16x32_bf16 v[26:29], v[186:189], v[218:221], v[26:29]
	v_mfma_f32_16x16x32_bf16 v[26:29], v[190:193], v[222:225], v[26:29]
	v_mfma_f32_16x16x32_bf16 v[18:21], v[194:197], v[218:221], v[18:21]
	v_mfma_f32_16x16x32_bf16 v[18:21], v[198:201], v[222:225], v[18:21]
	v_mfma_f32_16x16x32_bf16 v[14:17], v[150:153], v[226:229], v[14:17]
	v_mfma_f32_16x16x32_bf16 v[14:17], v[168:171], v[230:233], v[14:17]
	v_mfma_f32_16x16x32_bf16 v[6:9], v[172:175], v[226:229], v[6:9]
	v_mfma_f32_16x16x32_bf16 v[6:9], v[176:179], v[230:233], v[6:9]
	v_mfma_f32_16x16x32_bf16 v[10:13], v[186:189], v[226:229], v[10:13]
	v_mfma_f32_16x16x32_bf16 v[10:13], v[190:193], v[230:233], v[10:13]
	v_mfma_f32_16x16x32_bf16 v[2:5], v[194:197], v[226:229], v[2:5]
	v_mfma_f32_16x16x32_bf16 v[2:5], v[198:201], v[230:233], v[2:5]
	s_barrier
	s_add_i32 s79, s79, 2
	s_add_u32 s6, s6, 0x100
	s_addc_u32 s7, s7, 0
	s_add_u32 s77, s77, 0x100
	s_addc_u32 s78, s78, 0
	s_cmp_gt_u32 s79, 61
	s_cbranch_scc0 .LBB0_2212
	s_setprio 0
	s_and_b64 vcc, exec, s[40:41]
	s_cbranch_vccz .LBB0_2215
	s_barrier

.LBB0_2339:
	s_add_u32 s40, s40, 0x2b0080
	s_addc_u32 s41, s41, 0
	s_add_u32 s12, s42, 0x100
	v_mov_b32_e32 v2, 0
	s_addc_u32 s70, s43, 0
	s_mov_b32 s71, -2
	s_waitcnt lgkmcnt(0)
	v_mov_b32_e32 v3, v2
	v_mov_b32_e32 v4, v2
	v_mov_b32_e32 v5, v2
	v_mov_b32_e32 v6, v2
	v_mov_b32_e32 v7, v2
	v_mov_b32_e32 v8, v2
	v_mov_b32_e32 v9, v2
	v_mov_b32_e32 v18, v2
	v_mov_b32_e32 v19, v2
	v_mov_b32_e32 v20, v2
	v_mov_b32_e32 v21, v2
	v_mov_b32_e32 v22, v2
	v_mov_b32_e32 v23, v2
	v_mov_b32_e32 v24, v2
	v_mov_b32_e32 v25, v2
	v_mov_b32_e32 v34, v2
	v_mov_b32_e32 v35, v2
	v_mov_b32_e32 v36, v2
	v_mov_b32_e32 v37, v2
	v_mov_b32_e32 v38, v2
	v_mov_b32_e32 v39, v2
	v_mov_b32_e32 v40, v2
	v_mov_b32_e32 v41, v2
	v_mov_b32_e32 v50, v2
	v_mov_b32_e32 v51, v2
	v_mov_b32_e32 v52, v2
	v_mov_b32_e32 v53, v2
	v_mov_b32_e32 v54, v2
	v_mov_b32_e32 v55, v2
	v_mov_b32_e32 v56, v2
	v_mov_b32_e32 v57, v2
	v_mov_b32_e32 v10, v2
	v_mov_b32_e32 v11, v2
	v_mov_b32_e32 v12, v2
	v_mov_b32_e32 v13, v2
	v_mov_b32_e32 v14, v2
	v_mov_b32_e32 v15, v2
	v_mov_b32_e32 v16, v2
	v_mov_b32_e32 v17, v2
	v_mov_b32_e32 v26, v2
	v_mov_b32_e32 v27, v2
	v_mov_b32_e32 v28, v2
	v_mov_b32_e32 v29, v2
	v_mov_b32_e32 v30, v2
	v_mov_b32_e32 v31, v2
	v_mov_b32_e32 v32, v2
	v_mov_b32_e32 v33, v2
	v_mov_b32_e32 v42, v2
	v_mov_b32_e32 v43, v2
	v_mov_b32_e32 v44, v2
	v_mov_b32_e32 v45, v2
	v_mov_b32_e32 v46, v2
	v_mov_b32_e32 v47, v2
	v_mov_b32_e32 v48, v2
	v_mov_b32_e32 v49, v2
	v_mov_b32_e32 v58, v2
	v_mov_b32_e32 v59, v2
	v_mov_b32_e32 v60, v2
	v_mov_b32_e32 v61, v2
	v_mov_b32_e32 v62, v2
	v_mov_b32_e32 v63, v2
	v_mov_b32_e32 v64, v2
	v_mov_b32_e32 v65, v2
	v_mov_b32_e32 v66, v2
	v_mov_b32_e32 v67, v2
	v_mov_b32_e32 v68, v2
	v_mov_b32_e32 v69, v2
	v_mov_b32_e32 v70, v2
	v_mov_b32_e32 v71, v2
	v_mov_b32_e32 v72, v2
	v_mov_b32_e32 v73, v2
	v_mov_b32_e32 v82, v2
	v_mov_b32_e32 v83, v2
	v_mov_b32_e32 v84, v2
	v_mov_b32_e32 v85, v2
	v_mov_b32_e32 v86, v2
	v_mov_b32_e32 v87, v2
	v_mov_b32_e32 v88, v2
	v_mov_b32_e32 v89, v2
	v_mov_b32_e32 v98, v2
	v_mov_b32_e32 v99, v2
	v_mov_b32_e32 v100, v2
	v_mov_b32_e32 v101, v2
	v_mov_b32_e32 v102, v2
	v_mov_b32_e32 v103, v2
	v_mov_b32_e32 v104, v2
	v_mov_b32_e32 v105, v2
	v_mov_b32_e32 v114, v2
	v_mov_b32_e32 v115, v2
	v_mov_b32_e32 v116, v2
	v_mov_b32_e32 v117, v2
	v_mov_b32_e32 v118, v2
	v_mov_b32_e32 v119, v2
	v_mov_b32_e32 v120, v2
	v_mov_b32_e32 v121, v2
	v_mov_b32_e32 v74, v2
	v_mov_b32_e32 v75, v2
	v_mov_b32_e32 v76, v2
	v_mov_b32_e32 v77, v2
	v_mov_b32_e32 v78, v2
	v_mov_b32_e32 v79, v2
	v_mov_b32_e32 v80, v2
	v_mov_b32_e32 v81, v2
	v_mov_b32_e32 v90, v2
	v_mov_b32_e32 v91, v2
	v_mov_b32_e32 v92, v2
	v_mov_b32_e32 v93, v2
	v_mov_b32_e32 v94, v2
	v_mov_b32_e32 v95, v2
	v_mov_b32_e32 v96, v2
	v_mov_b32_e32 v97, v2
	v_mov_b32_e32 v106, v2
	v_mov_b32_e32 v107, v2
	v_mov_b32_e32 v108, v2
	v_mov_b32_e32 v109, v2
	v_mov_b32_e32 v110, v2
	v_mov_b32_e32 v111, v2
	v_mov_b32_e32 v112, v2
	v_mov_b32_e32 v113, v2
	v_mov_b32_e32 v122, v2
	v_mov_b32_e32 v123, v2
	v_mov_b32_e32 v124, v2
	v_mov_b32_e32 v125, v2
	v_mov_b32_e32 v126, v2
	v_mov_b32_e32 v127, v2
	v_mov_b32_e32 v128, v2
	v_mov_b32_e32 v129, v2
	s_and_b64 vcc, exec, s[36:37]
	s_cbranch_vccnz .Lsprio_3
	s_setprio 1
.Lsprio_3:
.LBB0_2340:
	ds_read_b128 v[130:133], v163
	ds_read_b128 v[134:137], v163 offset:1024
	ds_read_b128 v[138:141], v163 offset:2048
	ds_read_b128 v[142:145], v163 offset:3072
	ds_read_b128 v[146:149], v190
	ds_read_b128 v[150:153], v190 offset:1024
	ds_read_b128 v[174:177], v190 offset:2048
	ds_read_b128 v[178:181], v190 offset:3072
	s_add_u32 s42, s40, 0xffd50080
	s_addc_u32 s43, s41, -1
	s_cmpk_eq_i32 s71, 0xa8
	s_cselect_b32 s45, s1, s43
	s_cselect_b32 s44, s0, s42
	s_cselect_b32 s43, s39, s70
	s_cselect_b32 s42, s38, s12
	s_add_i32 m0, s46, 0xc000
	ds_read_b128 v[186:189], v191
	ds_read_b128 v[194:197], v191 offset:1024
	ds_read_b128 v[198:201], v191 offset:2048
	ds_read_b128 v[202:205], v191 offset:3072
	ds_read_b128 v[206:209], v191 offset:4096
	ds_read_b128 v[210:213], v191 offset:5120
	ds_read_b128 v[214:217], v191 offset:6144
	ds_read_b128 v[218:221], v191 offset:7168
	global_load_lds_dwordx4 v166, s[40:41]
	s_add_i32 m0, s46, 0xe000
	s_nop 0
	global_load_lds_dwordx4 v168, s[40:41]
	s_waitcnt vmcnt(8)
	s_waitcnt lgkmcnt(0)
	s_barrier
	v_mfma_f32_16x16x32_bf16 v[126:129], v[130:133], v[186:189], v[126:129]
	v_mfma_f32_16x16x32_bf16 v[126:129], v[134:137], v[194:197], v[126:129]
	v_mfma_f32_16x16x32_bf16 v[122:125], v[138:141], v[186:189], v[122:125]
	v_mfma_f32_16x16x32_bf16 v[122:125], v[142:145], v[194:197], v[122:125]
	v_mfma_f32_16x16x32_bf16 v[118:121], v[146:149], v[186:189], v[118:121]
	v_mfma_f32_16x16x32_bf16 v[118:121], v[150:153], v[194:197], v[118:121]
	v_mfma_f32_16x16x32_bf16 v[114:117], v[174:177], v[186:189], v[114:117]
	v_mfma_f32_16x16x32_bf16 v[114:117], v[178:181], v[194:197], v[114:117]
	v_mfma_f32_16x16x32_bf16 v[110:113], v[130:133], v[198:201], v[110:113]
	v_mfma_f32_16x16x32_bf16 v[110:113], v[134:137], v[202:205], v[110:113]
	v_mfma_f32_16x16x32_bf16 v[106:109], v[138:141], v[198:201], v[106:109]
	v_mfma_f32_16x16x32_bf16 v[106:109], v[142:145], v[202:205], v[106:109]
	v_mfma_f32_16x16x32_bf16 v[102:105], v[146:149], v[198:201], v[102:105]
	v_mfma_f32_16x16x32_bf16 v[102:105], v[150:153], v[202:205], v[102:105]
	v_mfma_f32_16x16x32_bf16 v[98:101], v[174:177], v[198:201], v[98:101]
	v_mfma_f32_16x16x32_bf16 v[98:101], v[178:181], v[202:205], v[98:101]
	v_mfma_f32_16x16x32_bf16 v[94:97], v[130:133], v[206:209], v[94:97]
	v_mfma_f32_16x16x32_bf16 v[94:97], v[134:137], v[210:213], v[94:97]
	v_mfma_f32_16x16x32_bf16 v[90:93], v[138:141], v[206:209], v[90:93]
	v_mfma_f32_16x16x32_bf16 v[90:93], v[142:145], v[210:213], v[90:93]
	v_mfma_f32_16x16x32_bf16 v[86:89], v[146:149], v[206:209], v[86:89]
	v_mfma_f32_16x16x32_bf16 v[86:89], v[150:153], v[210:213], v[86:89]
	v_mfma_f32_16x16x32_bf16 v[82:85], v[174:177], v[206:209], v[82:85]
	v_mfma_f32_16x16x32_bf16 v[82:85], v[178:181], v[210:213], v[82:85]
	v_mfma_f32_16x16x32_bf16 v[78:81], v[130:133], v[214:217], v[78:81]
	v_mfma_f32_16x16x32_bf16 v[78:81], v[134:137], v[218:221], v[78:81]
	v_mfma_f32_16x16x32_bf16 v[74:77], v[138:141], v[214:217], v[74:77]
	v_mfma_f32_16x16x32_bf16 v[74:77], v[142:145], v[218:221], v[74:77]
	v_mfma_f32_16x16x32_bf16 v[70:73], v[146:149], v[214:217], v[70:73]
	v_mfma_f32_16x16x32_bf16 v[70:73], v[150:153], v[218:221], v[70:73]
	v_mfma_f32_16x16x32_bf16 v[66:69], v[174:177], v[214:217], v[66:69]
	v_mfma_f32_16x16x32_bf16 v[66:69], v[178:181], v[218:221], v[66:69]
	s_barrier
	s_add_i32 s72, s65, s35
	s_add_u32 s98, s42, 0x80
	s_addc_u32 s99, s43, 0
	s_mov_b32 m0, s72
	ds_read_b128 v[186:189], v191 offset:16384
	ds_read_b128 v[194:197], v191 offset:17408
	ds_read_b128 v[198:201], v191 offset:18432
	ds_read_b128 v[202:205], v191 offset:19456
	ds_read_b128 v[206:209], v191 offset:20480
	ds_read_b128 v[210:213], v191 offset:21504
	ds_read_b128 v[214:217], v191 offset:22528
	ds_read_b128 v[218:221], v191 offset:23552
	global_load_lds_dwordx4 v156, s[42:43]
	s_add_i32 m0, s72, 0x2000
	s_add_u32 s72, s42, 0x2b0000
	s_addc_u32 s73, s43, 0
	s_add_i32 s74, s66, s35
	global_load_lds_dwordx4 v160, s[42:43]
	s_mov_b32 m0, s74
	global_load_lds_dwordx4 v156, s[72:73]
	s_add_i32 m0, s74, 0x2000
	s_nop 0
	global_load_lds_dwordx4 v160, s[72:73]
	s_add_u32 s100, s44, 0x80
	s_addc_u32 s101, s45, 0
	s_mov_b32 m0, s46
	s_nop 0
	global_load_lds_dwordx4 v154, s[44:45]
	s_mov_b32 m0, s47
	s_nop 0
	global_load_lds_dwordx4 v158, s[44:45]
	s_waitcnt vmcnt(8)
	s_waitcnt lgkmcnt(0)
	s_barrier
	v_mfma_f32_16x16x32_bf16 v[62:65], v[130:133], v[186:189], v[62:65]
	v_mfma_f32_16x16x32_bf16 v[62:65], v[134:137], v[194:197], v[62:65]
	v_mfma_f32_16x16x32_bf16 v[58:61], v[138:141], v[186:189], v[58:61]
	v_mfma_f32_16x16x32_bf16 v[58:61], v[142:145], v[194:197], v[58:61]
	v_mfma_f32_16x16x32_bf16 v[54:57], v[146:149], v[186:189], v[54:57]
	v_mfma_f32_16x16x32_bf16 v[54:57], v[150:153], v[194:197], v[54:57]
	v_mfma_f32_16x16x32_bf16 v[50:53], v[174:177], v[186:189], v[50:53]
	v_mfma_f32_16x16x32_bf16 v[50:53], v[178:181], v[194:197], v[50:53]
	v_mfma_f32_16x16x32_bf16 v[46:49], v[130:133], v[198:201], v[46:49]
	v_mfma_f32_16x16x32_bf16 v[46:49], v[134:137], v[202:205], v[46:49]
	v_mfma_f32_16x16x32_bf16 v[42:45], v[138:141], v[198:201], v[42:45]
	v_mfma_f32_16x16x32_bf16 v[42:45], v[142:145], v[202:205], v[42:45]
	v_mfma_f32_16x16x32_bf16 v[38:41], v[146:149], v[198:201], v[38:41]
	v_mfma_f32_16x16x32_bf16 v[38:41], v[150:153], v[202:205], v[38:41]
	v_mfma_f32_16x16x32_bf16 v[34:37], v[174:177], v[198:201], v[34:37]
	v_mfma_f32_16x16x32_bf16 v[34:37], v[178:181], v[202:205], v[34:37]
	v_mfma_f32_16x16x32_bf16 v[30:33], v[130:133], v[206:209], v[30:33]
	v_mfma_f32_16x16x32_bf16 v[30:33], v[134:137], v[210:213], v[30:33]
	v_mfma_f32_16x16x32_bf16 v[26:29], v[138:141], v[206:209], v[26:29]
	v_mfma_f32_16x16x32_bf16 v[26:29], v[142:145], v[210:213], v[26:29]
	v_mfma_f32_16x16x32_bf16 v[22:25], v[146:149], v[206:209], v[22:25]
	v_mfma_f32_16x16x32_bf16 v[22:25], v[150:153], v[210:213], v[22:25]
	v_mfma_f32_16x16x32_bf16 v[18:21], v[174:177], v[206:209], v[18:21]
	v_mfma_f32_16x16x32_bf16 v[18:21], v[178:181], v[210:213], v[18:21]
	v_mfma_f32_16x16x32_bf16 v[14:17], v[130:133], v[214:217], v[14:17]
	v_mfma_f32_16x16x32_bf16 v[14:17], v[134:137], v[218:221], v[14:17]
	v_mfma_f32_16x16x32_bf16 v[10:13], v[138:141], v[214:217], v[10:13]
	v_mfma_f32_16x16x32_bf16 v[10:13], v[142:145], v[218:221], v[10:13]
	v_mfma_f32_16x16x32_bf16 v[6:9], v[146:149], v[214:217], v[6:9]
	v_mfma_f32_16x16x32_bf16 v[6:9], v[150:153], v[218:221], v[6:9]
	v_mfma_f32_16x16x32_bf16 v[2:5], v[174:177], v[214:217], v[2:5]
	v_mfma_f32_16x16x32_bf16 v[2:5], v[178:181], v[218:221], v[2:5]
	s_barrier
	s_add_i32 s72, 0, 0x18000
	s_add_i32 s73, 0, 0x1c000
	v_add_u32_e32 v142, s72, v183
	v_add_u32_e32 v178, s73, v183
	ds_read_b128 v[130:133], v142
	ds_read_b128 v[134:137], v142 offset:1024
	ds_read_b128 v[138:141], v142 offset:2048
	ds_read_b128 v[142:145], v142 offset:3072
	ds_read_b128 v[146:149], v178
	ds_read_b128 v[150:153], v178 offset:1024
	ds_read_b128 v[174:177], v178 offset:2048
	ds_read_b128 v[178:181], v178 offset:3072
	s_add_u32 s44, s44, 0x2b0000
	s_addc_u32 s45, s45, 0
	s_mov_b32 m0, s48
	ds_read_b128 v[186:189], v191 offset:32768
	ds_read_b128 v[194:197], v191 offset:33792
	ds_read_b128 v[198:201], v191 offset:34816
	ds_read_b128 v[202:205], v191 offset:35840
	ds_read_b128 v[206:209], v191 offset:36864
	ds_read_b128 v[210:213], v191 offset:37888
	ds_read_b128 v[214:217], v191 offset:38912
	ds_read_b128 v[218:221], v191 offset:39936
	global_load_lds_dwordx4 v154, s[44:45]
	s_mov_b32 m0, s49
	s_nop 0
	global_load_lds_dwordx4 v158, s[44:45]
	s_waitcnt vmcnt(8)
	s_waitcnt lgkmcnt(0)
	s_barrier
	v_mfma_f32_16x16x32_bf16 v[126:129], v[130:133], v[186:189], v[126:129]
	v_mfma_f32_16x16x32_bf16 v[126:129], v[134:137], v[194:197], v[126:129]
	v_mfma_f32_16x16x32_bf16 v[122:125], v[138:141], v[186:189], v[122:125]
	v_mfma_f32_16x16x32_bf16 v[122:125], v[142:145], v[194:197], v[122:125]
	v_mfma_f32_16x16x32_bf16 v[118:121], v[146:149], v[186:189], v[118:121]
	v_mfma_f32_16x16x32_bf16 v[118:121], v[150:153], v[194:197], v[118:121]
	v_mfma_f32_16x16x32_bf16 v[114:117], v[174:177], v[186:189], v[114:117]
	v_mfma_f32_16x16x32_bf16 v[114:117], v[178:181], v[194:197], v[114:117]
	v_mfma_f32_16x16x32_bf16 v[110:113], v[130:133], v[198:201], v[110:113]
	v_mfma_f32_16x16x32_bf16 v[110:113], v[134:137], v[202:205], v[110:113]
	v_mfma_f32_16x16x32_bf16 v[106:109], v[138:141], v[198:201], v[106:109]
	v_mfma_f32_16x16x32_bf16 v[106:109], v[142:145], v[202:205], v[106:109]
	v_mfma_f32_16x16x32_bf16 v[102:105], v[146:149], v[198:201], v[102:105]
	v_mfma_f32_16x16x32_bf16 v[102:105], v[150:153], v[202:205], v[102:105]
	v_mfma_f32_16x16x32_bf16 v[98:101], v[174:177], v[198:201], v[98:101]
	v_mfma_f32_16x16x32_bf16 v[98:101], v[178:181], v[202:205], v[98:101]
	v_mfma_f32_16x16x32_bf16 v[94:97], v[130:133], v[206:209], v[94:97]
	v_mfma_f32_16x16x32_bf16 v[94:97], v[134:137], v[210:213], v[94:97]
	v_mfma_f32_16x16x32_bf16 v[90:93], v[138:141], v[206:209], v[90:93]
	v_mfma_f32_16x16x32_bf16 v[90:93], v[142:145], v[210:213], v[90:93]
	v_mfma_f32_16x16x32_bf16 v[86:89], v[146:149], v[206:209], v[86:89]
	v_mfma_f32_16x16x32_bf16 v[86:89], v[150:153], v[210:213], v[86:89]
	v_mfma_f32_16x16x32_bf16 v[82:85], v[174:177], v[206:209], v[82:85]
	v_mfma_f32_16x16x32_bf16 v[82:85], v[178:181], v[210:213], v[82:85]
	v_mfma_f32_16x16x32_bf16 v[78:81], v[130:133], v[214:217], v[78:81]
	v_mfma_f32_16x16x32_bf16 v[78:81], v[134:137], v[218:221], v[78:81]
	v_mfma_f32_16x16x32_bf16 v[74:77], v[138:141], v[214:217], v[74:77]
	v_mfma_f32_16x16x32_bf16 v[74:77], v[142:145], v[218:221], v[74:77]
	v_mfma_f32_16x16x32_bf16 v[70:73], v[146:149], v[214:217], v[70:73]
	v_mfma_f32_16x16x32_bf16 v[70:73], v[150:153], v[218:221], v[70:73]
	v_mfma_f32_16x16x32_bf16 v[66:69], v[174:177], v[214:217], v[66:69]
	v_mfma_f32_16x16x32_bf16 v[66:69], v[178:181], v[218:221], v[66:69]
	s_barrier
	s_add_i32 s44, s72, s35
	s_mov_b32 m0, s44
	ds_read_b128 v[186:189], v191 offset:49152
	ds_read_b128 v[194:197], v191 offset:50176
	ds_read_b128 v[198:201], v191 offset:51200
	ds_read_b128 v[202:205], v191 offset:52224
	ds_read_b128 v[206:209], v191 offset:53248
	ds_read_b128 v[210:213], v191 offset:54272
	ds_read_b128 v[214:217], v191 offset:55296
	ds_read_b128 v[218:221], v191 offset:56320
	global_load_lds_dwordx4 v156, s[98:99]
	s_add_i32 m0, s44, 0x2000
	s_add_u32 s42, s42, 0x2b0080
	s_addc_u32 s43, s43, 0
	s_add_i32 s44, s73, s35
	global_load_lds_dwordx4 v160, s[98:99]
	s_mov_b32 m0, s44
	s_nop 0
	global_load_lds_dwordx4 v156, s[42:43]
	s_add_i32 m0, s44, 0x2000
	s_nop 0
	global_load_lds_dwordx4 v160, s[42:43]
	s_mov_b32 m0, s51
	s_nop 0
	global_load_lds_dwordx4 v154, s[100:101]
	s_mov_b32 m0, s59
	s_nop 0
	global_load_lds_dwordx4 v158, s[100:101]
	s_waitcnt vmcnt(8)
	s_waitcnt lgkmcnt(0)
	s_barrier
	v_mfma_f32_16x16x32_bf16 v[62:65], v[130:133], v[186:189], v[62:65]
	v_mfma_f32_16x16x32_bf16 v[62:65], v[134:137], v[194:197], v[62:65]
	v_mfma_f32_16x16x32_bf16 v[58:61], v[138:141], v[186:189], v[58:61]
	v_mfma_f32_16x16x32_bf16 v[58:61], v[142:145], v[194:197], v[58:61]
	v_mfma_f32_16x16x32_bf16 v[54:57], v[146:149], v[186:189], v[54:57]
	v_mfma_f32_16x16x32_bf16 v[54:57], v[150:153], v[194:197], v[54:57]
	v_mfma_f32_16x16x32_bf16 v[50:53], v[174:177], v[186:189], v[50:53]
	v_mfma_f32_16x16x32_bf16 v[50:53], v[178:181], v[194:197], v[50:53]
	v_mfma_f32_16x16x32_bf16 v[46:49], v[130:133], v[198:201], v[46:49]
	v_mfma_f32_16x16x32_bf16 v[46:49], v[134:137], v[202:205], v[46:49]
	v_mfma_f32_16x16x32_bf16 v[42:45], v[138:141], v[198:201], v[42:45]
	v_mfma_f32_16x16x32_bf16 v[42:45], v[142:145], v[202:205], v[42:45]
	v_mfma_f32_16x16x32_bf16 v[38:41], v[146:149], v[198:201], v[38:41]
	v_mfma_f32_16x16x32_bf16 v[38:41], v[150:153], v[202:205], v[38:41]
	v_mfma_f32_16x16x32_bf16 v[34:37], v[174:177], v[198:201], v[34:37]
	v_mfma_f32_16x16x32_bf16 v[34:37], v[178:181], v[202:205], v[34:37]
	v_mfma_f32_16x16x32_bf16 v[30:33], v[130:133], v[206:209], v[30:33]
	v_mfma_f32_16x16x32_bf16 v[30:33], v[134:137], v[210:213], v[30:33]
	v_mfma_f32_16x16x32_bf16 v[26:29], v[138:141], v[206:209], v[26:29]
	v_mfma_f32_16x16x32_bf16 v[26:29], v[142:145], v[210:213], v[26:29]
	v_mfma_f32_16x16x32_bf16 v[22:25], v[146:149], v[206:209], v[22:25]
	v_mfma_f32_16x16x32_bf16 v[22:25], v[150:153], v[210:213], v[22:25]
	v_mfma_f32_16x16x32_bf16 v[18:21], v[174:177], v[206:209], v[18:21]
	v_mfma_f32_16x16x32_bf16 v[18:21], v[178:181], v[210:213], v[18:21]
	v_mfma_f32_16x16x32_bf16 v[14:17], v[130:133], v[214:217], v[14:17]
	v_mfma_f32_16x16x32_bf16 v[14:17], v[134:137], v[218:221], v[14:17]
	v_mfma_f32_16x16x32_bf16 v[10:13], v[138:141], v[214:217], v[10:13]
	v_mfma_f32_16x16x32_bf16 v[10:13], v[142:145], v[218:221], v[10:13]
	v_mfma_f32_16x16x32_bf16 v[6:9], v[146:149], v[214:217], v[6:9]
	v_mfma_f32_16x16x32_bf16 v[6:9], v[150:153], v[218:221], v[6:9]
	v_mfma_f32_16x16x32_bf16 v[2:5], v[174:177], v[214:217], v[2:5]
	v_mfma_f32_16x16x32_bf16 v[2:5], v[178:181], v[218:221], v[2:5]
	s_barrier
	s_add_i32 s71, s71, 2
	s_add_u32 s40, s40, 0x100
	s_addc_u32 s41, s41, 0
	s_add_u32 s12, s12, 0x100
	s_addc_u32 s70, s70, 0
	s_cmpk_gt_u32 s71, 0xa9
	s_cbranch_scc0 .LBB0_2340
	s_setprio 0
	s_and_b64 vcc, exec, s[36:37]
	s_cbranch_vccz .LBB0_2343
	s_barrier

.LBB0_2463:
	s_ashr_i32 s47, s46, 31
	s_lshl_b64 s[48:49], s[46:47], 21
	s_add_u32 s48, s16, s48
	s_addc_u32 s49, s17, s49
	s_and_b64 s[50:51], s[4:5], exec
	s_cselect_b32 s47, s49, s7
	s_cselect_b32 s83, s48, s6
	s_ashr_i32 s45, s44, 31
	s_lshl_b64 s[50:51], s[44:45], 21
	v_readlane_b32 s76, v245, 10
	v_readlane_b32 s77, v245, 11
	s_add_u32 s50, s76, s50
	s_addc_u32 s51, s77, s51
	s_and_b64 s[76:77], s[4:5], exec
	s_cselect_b32 s45, s51, s75
	s_cselect_b32 s84, s50, s74
	s_add_u32 s6, s6, 0x100080
	s_addc_u32 s7, s7, 0
	s_add_u32 s85, s74, 0x100
	v_mov_b32_e32 v2, 0
	s_addc_u32 s86, s75, 0
	s_mov_b32 s87, -2
	v_mov_b32_e32 v3, v2
	v_mov_b32_e32 v4, v2
	v_mov_b32_e32 v5, v2
	v_mov_b32_e32 v6, v2
	v_mov_b32_e32 v7, v2
	v_mov_b32_e32 v8, v2
	v_mov_b32_e32 v9, v2
	v_mov_b32_e32 v14, v2
	v_mov_b32_e32 v15, v2
	v_mov_b32_e32 v16, v2
	v_mov_b32_e32 v17, v2
	v_mov_b32_e32 v22, v2
	v_mov_b32_e32 v23, v2
	v_mov_b32_e32 v24, v2
	v_mov_b32_e32 v25, v2
	v_mov_b32_e32 v30, v2
	v_mov_b32_e32 v31, v2
	v_mov_b32_e32 v32, v2
	v_mov_b32_e32 v33, v2
	v_mov_b32_e32 v38, v2
	v_mov_b32_e32 v39, v2
	v_mov_b32_e32 v40, v2
	v_mov_b32_e32 v41, v2
	v_mov_b32_e32 v46, v2
	v_mov_b32_e32 v47, v2
	v_mov_b32_e32 v48, v2
	v_mov_b32_e32 v49, v2
	v_mov_b32_e32 v54, v2
	v_mov_b32_e32 v55, v2
	v_mov_b32_e32 v56, v2
	v_mov_b32_e32 v57, v2
	v_mov_b32_e32 v10, v2
	v_mov_b32_e32 v11, v2
	v_mov_b32_e32 v12, v2
	v_mov_b32_e32 v13, v2
	v_mov_b32_e32 v18, v2
	v_mov_b32_e32 v19, v2
	v_mov_b32_e32 v20, v2
	v_mov_b32_e32 v21, v2
	v_mov_b32_e32 v26, v2
	v_mov_b32_e32 v27, v2
	v_mov_b32_e32 v28, v2
	v_mov_b32_e32 v29, v2
	v_mov_b32_e32 v34, v2
	v_mov_b32_e32 v35, v2
	v_mov_b32_e32 v36, v2
	v_mov_b32_e32 v37, v2
	v_mov_b32_e32 v42, v2
	v_mov_b32_e32 v43, v2
	v_mov_b32_e32 v44, v2
	v_mov_b32_e32 v45, v2
	v_mov_b32_e32 v50, v2
	v_mov_b32_e32 v51, v2
	v_mov_b32_e32 v52, v2
	v_mov_b32_e32 v53, v2
	v_mov_b32_e32 v58, v2
	v_mov_b32_e32 v59, v2
	v_mov_b32_e32 v60, v2
	v_mov_b32_e32 v61, v2
	v_mov_b32_e32 v62, v2
	v_mov_b32_e32 v63, v2
	v_mov_b32_e32 v64, v2
	v_mov_b32_e32 v65, v2
	v_mov_b32_e32 v66, v2
	v_mov_b32_e32 v67, v2
	v_mov_b32_e32 v68, v2
	v_mov_b32_e32 v69, v2
	v_mov_b32_e32 v70, v2
	v_mov_b32_e32 v71, v2
	v_mov_b32_e32 v72, v2
	v_mov_b32_e32 v73, v2
	v_mov_b32_e32 v82, v2
	v_mov_b32_e32 v83, v2
	v_mov_b32_e32 v84, v2
	v_mov_b32_e32 v85, v2
	v_mov_b32_e32 v86, v2
	v_mov_b32_e32 v87, v2
	v_mov_b32_e32 v88, v2
	v_mov_b32_e32 v89, v2
	v_mov_b32_e32 v98, v2
	v_mov_b32_e32 v99, v2
	v_mov_b32_e32 v100, v2
	v_mov_b32_e32 v101, v2
	v_mov_b32_e32 v102, v2
	v_mov_b32_e32 v103, v2
	v_mov_b32_e32 v104, v2
	v_mov_b32_e32 v105, v2
	v_mov_b32_e32 v114, v2
	v_mov_b32_e32 v115, v2
	v_mov_b32_e32 v116, v2
	v_mov_b32_e32 v117, v2
	v_mov_b32_e32 v118, v2
	v_mov_b32_e32 v119, v2
	v_mov_b32_e32 v120, v2
	v_mov_b32_e32 v121, v2
	v_mov_b32_e32 v74, v2
	v_mov_b32_e32 v75, v2
	v_mov_b32_e32 v76, v2
	v_mov_b32_e32 v77, v2
	v_mov_b32_e32 v78, v2
	v_mov_b32_e32 v79, v2
	v_mov_b32_e32 v80, v2
	v_mov_b32_e32 v81, v2
	v_mov_b32_e32 v90, v2
	v_mov_b32_e32 v91, v2
	v_mov_b32_e32 v92, v2
	v_mov_b32_e32 v93, v2
	v_mov_b32_e32 v94, v2
	v_mov_b32_e32 v95, v2
	v_mov_b32_e32 v96, v2
	v_mov_b32_e32 v97, v2
	v_mov_b32_e32 v106, v2
	v_mov_b32_e32 v107, v2
	v_mov_b32_e32 v108, v2
	v_mov_b32_e32 v109, v2
	v_mov_b32_e32 v110, v2
	v_mov_b32_e32 v111, v2
	v_mov_b32_e32 v112, v2
	v_mov_b32_e32 v113, v2
	v_mov_b32_e32 v122, v2
	v_mov_b32_e32 v123, v2
	v_mov_b32_e32 v124, v2
	v_mov_b32_e32 v125, v2
	v_mov_b32_e32 v126, v2
	v_mov_b32_e32 v127, v2
	v_mov_b32_e32 v128, v2
	v_mov_b32_e32 v129, v2
	s_and_b64 vcc, exec, s[38:39]
	s_cbranch_vccnz .Lsprio_4
	s_setprio 1
.Lsprio_4:
.LBB0_2464:
	ds_read_b128 v[150:153], v167
	ds_read_b128 v[172:175], v167 offset:1024
	ds_read_b128 v[176:179], v167 offset:2048
	ds_read_b128 v[184:187], v167 offset:3072
	ds_read_b128 v[188:191], v168
	ds_read_b128 v[192:195], v168 offset:1024
	ds_read_b128 v[196:199], v168 offset:2048
	ds_read_b128 v[200:203], v168 offset:3072
	s_add_u32 s74, s6, 0xfff00080
	s_addc_u32 s75, s7, -1
	s_cmp_eq_u32 s87, 60
	s_cselect_b32 s77, s47, s75
	s_cselect_b32 s76, s83, s74
	s_cselect_b32 s75, s45, s86
	s_cselect_b32 s74, s84, s85
	s_add_i32 m0, s59, 0xc000
	ds_read_b128 v[204:207], v169
	ds_read_b128 v[208:211], v169 offset:1024
	ds_read_b128 v[212:215], v169 offset:2048
	ds_read_b128 v[216:219], v169 offset:3072
	ds_read_b128 v[220:223], v169 offset:4096
	ds_read_b128 v[224:227], v169 offset:5120
	ds_read_b128 v[228:231], v169 offset:6144
	ds_read_b128 v[232:235], v169 offset:7168
	global_load_lds_dwordx4 v142, s[6:7]
	s_add_i32 m0, s59, 0xe000
	s_nop 0
	global_load_lds_dwordx4 v144, s[6:7]
	s_waitcnt vmcnt(8)
	s_waitcnt lgkmcnt(0)
	s_barrier
	v_mfma_f32_16x16x32_bf16 v[126:129], v[150:153], v[204:207], v[126:129]
	v_mfma_f32_16x16x32_bf16 v[126:129], v[172:175], v[208:211], v[126:129]
	v_mfma_f32_16x16x32_bf16 v[122:125], v[176:179], v[204:207], v[122:125]
	v_mfma_f32_16x16x32_bf16 v[122:125], v[184:187], v[208:211], v[122:125]
	v_mfma_f32_16x16x32_bf16 v[118:121], v[188:191], v[204:207], v[118:121]
	v_mfma_f32_16x16x32_bf16 v[118:121], v[192:195], v[208:211], v[118:121]
	v_mfma_f32_16x16x32_bf16 v[114:117], v[196:199], v[204:207], v[114:117]
	v_mfma_f32_16x16x32_bf16 v[114:117], v[200:203], v[208:211], v[114:117]
	v_mfma_f32_16x16x32_bf16 v[110:113], v[150:153], v[212:215], v[110:113]
	v_mfma_f32_16x16x32_bf16 v[110:113], v[172:175], v[216:219], v[110:113]
	v_mfma_f32_16x16x32_bf16 v[106:109], v[176:179], v[212:215], v[106:109]
	v_mfma_f32_16x16x32_bf16 v[106:109], v[184:187], v[216:219], v[106:109]
	v_mfma_f32_16x16x32_bf16 v[102:105], v[188:191], v[212:215], v[102:105]
	v_mfma_f32_16x16x32_bf16 v[102:105], v[192:195], v[216:219], v[102:105]
	v_mfma_f32_16x16x32_bf16 v[98:101], v[196:199], v[212:215], v[98:101]
	v_mfma_f32_16x16x32_bf16 v[98:101], v[200:203], v[216:219], v[98:101]
	v_mfma_f32_16x16x32_bf16 v[94:97], v[150:153], v[220:223], v[94:97]
	v_mfma_f32_16x16x32_bf16 v[94:97], v[172:175], v[224:227], v[94:97]
	v_mfma_f32_16x16x32_bf16 v[90:93], v[176:179], v[220:223], v[90:93]
	v_mfma_f32_16x16x32_bf16 v[90:93], v[184:187], v[224:227], v[90:93]
	v_mfma_f32_16x16x32_bf16 v[86:89], v[188:191], v[220:223], v[86:89]
	v_mfma_f32_16x16x32_bf16 v[86:89], v[192:195], v[224:227], v[86:89]
	v_mfma_f32_16x16x32_bf16 v[82:85], v[196:199], v[220:223], v[82:85]
	v_mfma_f32_16x16x32_bf16 v[82:85], v[200:203], v[224:227], v[82:85]
	v_mfma_f32_16x16x32_bf16 v[78:81], v[150:153], v[228:231], v[78:81]
	v_mfma_f32_16x16x32_bf16 v[78:81], v[172:175], v[232:235], v[78:81]
	v_mfma_f32_16x16x32_bf16 v[74:77], v[176:179], v[228:231], v[74:77]
	v_mfma_f32_16x16x32_bf16 v[74:77], v[184:187], v[232:235], v[74:77]
	v_mfma_f32_16x16x32_bf16 v[70:73], v[188:191], v[228:231], v[70:73]
	v_mfma_f32_16x16x32_bf16 v[70:73], v[192:195], v[232:235], v[70:73]
	v_mfma_f32_16x16x32_bf16 v[66:69], v[196:199], v[228:231], v[66:69]
	v_mfma_f32_16x16x32_bf16 v[66:69], v[200:203], v[232:235], v[66:69]
	s_barrier
	s_add_i32 s88, s70, s27
	s_add_u32 s98, s74, 0x80
	s_addc_u32 s99, s75, 0
	s_mov_b32 m0, s88
	ds_read_b128 v[204:207], v169 offset:16384
	ds_read_b128 v[208:211], v169 offset:17408
	ds_read_b128 v[212:215], v169 offset:18432
	ds_read_b128 v[216:219], v169 offset:19456
	ds_read_b128 v[220:223], v169 offset:20480
	ds_read_b128 v[224:227], v169 offset:21504
	ds_read_b128 v[228:231], v169 offset:22528
	ds_read_b128 v[232:235], v169 offset:23552
	global_load_lds_dwordx4 v132, s[74:75]
	s_add_i32 m0, s88, 0x2000
	s_add_u32 s88, s74, 0x100000
	s_addc_u32 s89, s75, 0
	s_add_i32 s90, s71, s27
	global_load_lds_dwordx4 v136, s[74:75]
	s_mov_b32 m0, s90
	global_load_lds_dwordx4 v132, s[88:89]
	s_add_i32 m0, s90, 0x2000
	s_nop 0
	global_load_lds_dwordx4 v136, s[88:89]
	s_add_u32 s100, s76, 0x80
	s_addc_u32 s101, s77, 0
	s_mov_b32 m0, s59
	s_nop 0
	global_load_lds_dwordx4 v130, s[76:77]
	s_mov_b32 m0, s62
	s_nop 0
	global_load_lds_dwordx4 v134, s[76:77]
	s_waitcnt vmcnt(8)
	s_waitcnt lgkmcnt(0)
	s_barrier
	v_mfma_f32_16x16x32_bf16 v[62:65], v[150:153], v[204:207], v[62:65]
	v_mfma_f32_16x16x32_bf16 v[62:65], v[172:175], v[208:211], v[62:65]
	v_mfma_f32_16x16x32_bf16 v[58:61], v[176:179], v[204:207], v[58:61]
	v_mfma_f32_16x16x32_bf16 v[58:61], v[184:187], v[208:211], v[58:61]
	v_mfma_f32_16x16x32_bf16 v[54:57], v[188:191], v[204:207], v[54:57]
	v_mfma_f32_16x16x32_bf16 v[54:57], v[192:195], v[208:211], v[54:57]
	v_mfma_f32_16x16x32_bf16 v[46:49], v[196:199], v[204:207], v[46:49]
	v_mfma_f32_16x16x32_bf16 v[46:49], v[200:203], v[208:211], v[46:49]
	v_mfma_f32_16x16x32_bf16 v[50:53], v[150:153], v[212:215], v[50:53]
	v_mfma_f32_16x16x32_bf16 v[50:53], v[172:175], v[216:219], v[50:53]
	v_mfma_f32_16x16x32_bf16 v[42:45], v[176:179], v[212:215], v[42:45]
	v_mfma_f32_16x16x32_bf16 v[42:45], v[184:187], v[216:219], v[42:45]
	v_mfma_f32_16x16x32_bf16 v[38:41], v[188:191], v[212:215], v[38:41]
	v_mfma_f32_16x16x32_bf16 v[38:41], v[192:195], v[216:219], v[38:41]
	v_mfma_f32_16x16x32_bf16 v[30:33], v[196:199], v[212:215], v[30:33]
	v_mfma_f32_16x16x32_bf16 v[30:33], v[200:203], v[216:219], v[30:33]
	v_mfma_f32_16x16x32_bf16 v[34:37], v[150:153], v[220:223], v[34:37]
	v_mfma_f32_16x16x32_bf16 v[34:37], v[172:175], v[224:227], v[34:37]
	v_mfma_f32_16x16x32_bf16 v[26:29], v[176:179], v[220:223], v[26:29]
	v_mfma_f32_16x16x32_bf16 v[26:29], v[184:187], v[224:227], v[26:29]
	v_mfma_f32_16x16x32_bf16 v[22:25], v[188:191], v[220:223], v[22:25]
	v_mfma_f32_16x16x32_bf16 v[22:25], v[192:195], v[224:227], v[22:25]
	v_mfma_f32_16x16x32_bf16 v[14:17], v[196:199], v[220:223], v[14:17]
	v_mfma_f32_16x16x32_bf16 v[14:17], v[200:203], v[224:227], v[14:17]
	v_mfma_f32_16x16x32_bf16 v[18:21], v[150:153], v[228:231], v[18:21]
	v_mfma_f32_16x16x32_bf16 v[18:21], v[172:175], v[232:235], v[18:21]
	v_mfma_f32_16x16x32_bf16 v[10:13], v[176:179], v[228:231], v[10:13]
	v_mfma_f32_16x16x32_bf16 v[10:13], v[184:187], v[232:235], v[10:13]
	v_mfma_f32_16x16x32_bf16 v[6:9], v[188:191], v[228:231], v[6:9]
	v_mfma_f32_16x16x32_bf16 v[6:9], v[192:195], v[232:235], v[6:9]
	v_mfma_f32_16x16x32_bf16 v[2:5], v[196:199], v[228:231], v[2:5]
	v_mfma_f32_16x16x32_bf16 v[2:5], v[200:203], v[232:235], v[2:5]
	s_barrier
	s_add_i32 s88, 0, 0x18000
	v_add_u32_e32 v140, s88, v163
	s_add_i32 s89, 0, 0x1c000
	ds_read_b128 v[150:153], v140
	ds_read_b128 v[172:175], v140 offset:1024
	ds_read_b128 v[176:179], v140 offset:2048
	ds_read_b128 v[184:187], v140 offset:3072
	v_add_u32_e32 v140, s89, v163
	ds_read_b128 v[188:191], v140
	ds_read_b128 v[192:195], v140 offset:1024
	ds_read_b128 v[196:199], v140 offset:2048
	ds_read_b128 v[200:203], v140 offset:3072
	s_add_u32 s76, s76, 0x100000
	s_addc_u32 s77, s77, 0
	s_mov_b32 m0, s63
	ds_read_b128 v[204:207], v169 offset:32768
	ds_read_b128 v[208:211], v169 offset:33792
	ds_read_b128 v[212:215], v169 offset:34816
	ds_read_b128 v[216:219], v169 offset:35840
	ds_read_b128 v[220:223], v169 offset:36864
	ds_read_b128 v[224:227], v169 offset:37888
	ds_read_b128 v[228:231], v169 offset:38912
	ds_read_b128 v[232:235], v169 offset:39936
	global_load_lds_dwordx4 v130, s[76:77]
	s_mov_b32 m0, s65
	s_nop 0
	global_load_lds_dwordx4 v134, s[76:77]
	s_waitcnt vmcnt(8)
	s_waitcnt lgkmcnt(0)
	s_barrier
	v_mfma_f32_16x16x32_bf16 v[126:129], v[150:153], v[204:207], v[126:129]
	v_mfma_f32_16x16x32_bf16 v[126:129], v[172:175], v[208:211], v[126:129]
	v_mfma_f32_16x16x32_bf16 v[122:125], v[176:179], v[204:207], v[122:125]
	v_mfma_f32_16x16x32_bf16 v[122:125], v[184:187], v[208:211], v[122:125]
	v_mfma_f32_16x16x32_bf16 v[118:121], v[188:191], v[204:207], v[118:121]
	v_mfma_f32_16x16x32_bf16 v[118:121], v[192:195], v[208:211], v[118:121]
	v_mfma_f32_16x16x32_bf16 v[114:117], v[196:199], v[204:207], v[114:117]
	v_mfma_f32_16x16x32_bf16 v[114:117], v[200:203], v[208:211], v[114:117]
	v_mfma_f32_16x16x32_bf16 v[110:113], v[150:153], v[212:215], v[110:113]
	v_mfma_f32_16x16x32_bf16 v[110:113], v[172:175], v[216:219], v[110:113]
	v_mfma_f32_16x16x32_bf16 v[106:109], v[176:179], v[212:215], v[106:109]
	v_mfma_f32_16x16x32_bf16 v[106:109], v[184:187], v[216:219], v[106:109]
	v_mfma_f32_16x16x32_bf16 v[102:105], v[188:191], v[212:215], v[102:105]
	v_mfma_f32_16x16x32_bf16 v[102:105], v[192:195], v[216:219], v[102:105]
	v_mfma_f32_16x16x32_bf16 v[98:101], v[196:199], v[212:215], v[98:101]
	v_mfma_f32_16x16x32_bf16 v[98:101], v[200:203], v[216:219], v[98:101]
	v_mfma_f32_16x16x32_bf16 v[94:97], v[150:153], v[220:223], v[94:97]
	v_mfma_f32_16x16x32_bf16 v[94:97], v[172:175], v[224:227], v[94:97]
	v_mfma_f32_16x16x32_bf16 v[90:93], v[176:179], v[220:223], v[90:93]
	v_mfma_f32_16x16x32_bf16 v[90:93], v[184:187], v[224:227], v[90:93]
	v_mfma_f32_16x16x32_bf16 v[86:89], v[188:191], v[220:223], v[86:89]
	v_mfma_f32_16x16x32_bf16 v[86:89], v[192:195], v[224:227], v[86:89]
	v_mfma_f32_16x16x32_bf16 v[82:85], v[196:199], v[220:223], v[82:85]
	v_mfma_f32_16x16x32_bf16 v[82:85], v[200:203], v[224:227], v[82:85]
	v_mfma_f32_16x16x32_bf16 v[78:81], v[150:153], v[228:231], v[78:81]
	v_mfma_f32_16x16x32_bf16 v[78:81], v[172:175], v[232:235], v[78:81]
	v_mfma_f32_16x16x32_bf16 v[74:77], v[176:179], v[228:231], v[74:77]
	v_mfma_f32_16x16x32_bf16 v[74:77], v[184:187], v[232:235], v[74:77]
	v_mfma_f32_16x16x32_bf16 v[70:73], v[188:191], v[228:231], v[70:73]
	v_mfma_f32_16x16x32_bf16 v[70:73], v[192:195], v[232:235], v[70:73]
	v_mfma_f32_16x16x32_bf16 v[66:69], v[196:199], v[228:231], v[66:69]
	v_mfma_f32_16x16x32_bf16 v[66:69], v[200:203], v[232:235], v[66:69]
	s_barrier
	s_add_i32 s76, s88, s27
	s_mov_b32 m0, s76
	ds_read_b128 v[204:207], v169 offset:49152
	ds_read_b128 v[208:211], v169 offset:50176
	ds_read_b128 v[212:215], v169 offset:51200
	ds_read_b128 v[216:219], v169 offset:52224
	ds_read_b128 v[220:223], v169 offset:53248
	ds_read_b128 v[224:227], v169 offset:54272
	ds_read_b128 v[228:231], v169 offset:55296
	ds_read_b128 v[232:235], v169 offset:56320
	global_load_lds_dwordx4 v132, s[98:99]
	s_add_i32 m0, s76, 0x2000
	s_add_u32 s74, s74, 0x100080
	s_addc_u32 s75, s75, 0
	s_add_i32 s76, s89, s27
	global_load_lds_dwordx4 v136, s[98:99]
	s_mov_b32 m0, s76
	s_nop 0
	global_load_lds_dwordx4 v132, s[74:75]
	s_add_i32 m0, s76, 0x2000
	s_nop 0
	global_load_lds_dwordx4 v136, s[74:75]
	s_mov_b32 m0, s67
	s_nop 0
	global_load_lds_dwordx4 v130, s[100:101]
	s_mov_b32 m0, s68
	s_nop 0
	global_load_lds_dwordx4 v134, s[100:101]
	s_waitcnt vmcnt(8)
	s_waitcnt lgkmcnt(0)
	s_barrier
	v_mfma_f32_16x16x32_bf16 v[62:65], v[150:153], v[204:207], v[62:65]
	v_mfma_f32_16x16x32_bf16 v[62:65], v[172:175], v[208:211], v[62:65]
	v_mfma_f32_16x16x32_bf16 v[58:61], v[176:179], v[204:207], v[58:61]
	v_mfma_f32_16x16x32_bf16 v[58:61], v[184:187], v[208:211], v[58:61]
	v_mfma_f32_16x16x32_bf16 v[54:57], v[188:191], v[204:207], v[54:57]
	v_mfma_f32_16x16x32_bf16 v[54:57], v[192:195], v[208:211], v[54:57]
	v_mfma_f32_16x16x32_bf16 v[46:49], v[196:199], v[204:207], v[46:49]
	v_mfma_f32_16x16x32_bf16 v[46:49], v[200:203], v[208:211], v[46:49]
	v_mfma_f32_16x16x32_bf16 v[50:53], v[150:153], v[212:215], v[50:53]
	v_mfma_f32_16x16x32_bf16 v[50:53], v[172:175], v[216:219], v[50:53]
	v_mfma_f32_16x16x32_bf16 v[42:45], v[176:179], v[212:215], v[42:45]
	v_mfma_f32_16x16x32_bf16 v[42:45], v[184:187], v[216:219], v[42:45]
	v_mfma_f32_16x16x32_bf16 v[38:41], v[188:191], v[212:215], v[38:41]
	v_mfma_f32_16x16x32_bf16 v[38:41], v[192:195], v[216:219], v[38:41]
	v_mfma_f32_16x16x32_bf16 v[30:33], v[196:199], v[212:215], v[30:33]
	v_mfma_f32_16x16x32_bf16 v[30:33], v[200:203], v[216:219], v[30:33]
	v_mfma_f32_16x16x32_bf16 v[34:37], v[150:153], v[220:223], v[34:37]
	v_mfma_f32_16x16x32_bf16 v[34:37], v[172:175], v[224:227], v[34:37]
	v_mfma_f32_16x16x32_bf16 v[26:29], v[176:179], v[220:223], v[26:29]
	v_mfma_f32_16x16x32_bf16 v[26:29], v[184:187], v[224:227], v[26:29]
	v_mfma_f32_16x16x32_bf16 v[22:25], v[188:191], v[220:223], v[22:25]
	v_mfma_f32_16x16x32_bf16 v[22:25], v[192:195], v[224:227], v[22:25]
	v_mfma_f32_16x16x32_bf16 v[14:17], v[196:199], v[220:223], v[14:17]
	v_mfma_f32_16x16x32_bf16 v[14:17], v[200:203], v[224:227], v[14:17]
	v_mfma_f32_16x16x32_bf16 v[18:21], v[150:153], v[228:231], v[18:21]
	v_mfma_f32_16x16x32_bf16 v[18:21], v[172:175], v[232:235], v[18:21]
	v_mfma_f32_16x16x32_bf16 v[10:13], v[176:179], v[228:231], v[10:13]
	v_mfma_f32_16x16x32_bf16 v[10:13], v[184:187], v[232:235], v[10:13]
	v_mfma_f32_16x16x32_bf16 v[6:9], v[188:191], v[228:231], v[6:9]
	v_mfma_f32_16x16x32_bf16 v[6:9], v[192:195], v[232:235], v[6:9]
	v_mfma_f32_16x16x32_bf16 v[2:5], v[196:199], v[228:231], v[2:5]
	v_mfma_f32_16x16x32_bf16 v[2:5], v[200:203], v[232:235], v[2:5]
	s_barrier
	s_add_i32 s87, s87, 2
	s_add_u32 s6, s6, 0x100
	s_addc_u32 s7, s7, 0
	s_add_u32 s85, s85, 0x100
	s_addc_u32 s86, s86, 0
	s_cmp_gt_u32 s87, 61
	s_cbranch_scc0 .LBB0_2464
	s_setprio 0
	s_and_b64 vcc, exec, s[38:39]
	s_cbranch_vccz .LBB0_2467
	s_barrier

.LBB0_2493:
	s_ashr_i32 s43, s42, 31
	s_lshl_b64 s[44:45], s[42:43], 21
	s_add_u32 s44, s16, s44
	s_addc_u32 s45, s17, s45
	s_and_b64 s[46:47], s[4:5], exec
	s_cselect_b32 s43, s45, s7
	s_cselect_b32 s85, s44, s6
	s_ashr_i32 s41, s40, 31
	s_lshl_b64 s[46:47], s[40:41], 21
	s_add_u32 s46, s59, s46
	s_addc_u32 s47, s62, s47
	s_and_b64 s[50:51], s[4:5], exec
	s_cselect_b32 s41, s47, s49
	s_cselect_b32 s86, s46, s48
	s_add_u32 s6, s6, 0x100080
	s_addc_u32 s7, s7, 0
	s_add_u32 s87, s48, 0x100
	v_mov_b32_e32 v2, 0
	s_addc_u32 s88, s49, 0
	s_mov_b32 s89, -2
	v_mov_b32_e32 v3, v2
	v_mov_b32_e32 v4, v2
	v_mov_b32_e32 v5, v2
	v_mov_b32_e32 v6, v2
	v_mov_b32_e32 v7, v2
	v_mov_b32_e32 v8, v2
	v_mov_b32_e32 v9, v2
	v_mov_b32_e32 v14, v2
	v_mov_b32_e32 v15, v2
	v_mov_b32_e32 v16, v2
	v_mov_b32_e32 v17, v2
	v_mov_b32_e32 v22, v2
	v_mov_b32_e32 v23, v2
	v_mov_b32_e32 v24, v2
	v_mov_b32_e32 v25, v2
	v_mov_b32_e32 v30, v2
	v_mov_b32_e32 v31, v2
	v_mov_b32_e32 v32, v2
	v_mov_b32_e32 v33, v2
	v_mov_b32_e32 v38, v2
	v_mov_b32_e32 v39, v2
	v_mov_b32_e32 v40, v2
	v_mov_b32_e32 v41, v2
	v_mov_b32_e32 v46, v2
	v_mov_b32_e32 v47, v2
	v_mov_b32_e32 v48, v2
	v_mov_b32_e32 v49, v2
	v_mov_b32_e32 v54, v2
	v_mov_b32_e32 v55, v2
	v_mov_b32_e32 v56, v2
	v_mov_b32_e32 v57, v2
	v_mov_b32_e32 v10, v2
	v_mov_b32_e32 v11, v2
	v_mov_b32_e32 v12, v2
	v_mov_b32_e32 v13, v2
	v_mov_b32_e32 v18, v2
	v_mov_b32_e32 v19, v2
	v_mov_b32_e32 v20, v2
	v_mov_b32_e32 v21, v2
	v_mov_b32_e32 v26, v2
	v_mov_b32_e32 v27, v2
	v_mov_b32_e32 v28, v2
	v_mov_b32_e32 v29, v2
	v_mov_b32_e32 v34, v2
	v_mov_b32_e32 v35, v2
	v_mov_b32_e32 v36, v2
	v_mov_b32_e32 v37, v2
	v_mov_b32_e32 v42, v2
	v_mov_b32_e32 v43, v2
	v_mov_b32_e32 v44, v2
	v_mov_b32_e32 v45, v2
	v_mov_b32_e32 v50, v2
	v_mov_b32_e32 v51, v2
	v_mov_b32_e32 v52, v2
	v_mov_b32_e32 v53, v2
	v_mov_b32_e32 v58, v2
	v_mov_b32_e32 v59, v2
	v_mov_b32_e32 v60, v2
	v_mov_b32_e32 v61, v2
	v_mov_b32_e32 v62, v2
	v_mov_b32_e32 v63, v2
	v_mov_b32_e32 v64, v2
	v_mov_b32_e32 v65, v2
	v_mov_b32_e32 v66, v2
	v_mov_b32_e32 v67, v2
	v_mov_b32_e32 v68, v2
	v_mov_b32_e32 v69, v2
	v_mov_b32_e32 v70, v2
	v_mov_b32_e32 v71, v2
	v_mov_b32_e32 v72, v2
	v_mov_b32_e32 v73, v2
	v_mov_b32_e32 v82, v2
	v_mov_b32_e32 v83, v2
	v_mov_b32_e32 v84, v2
	v_mov_b32_e32 v85, v2
	v_mov_b32_e32 v86, v2
	v_mov_b32_e32 v87, v2
	v_mov_b32_e32 v88, v2
	v_mov_b32_e32 v89, v2
	v_mov_b32_e32 v98, v2
	v_mov_b32_e32 v99, v2
	v_mov_b32_e32 v100, v2
	v_mov_b32_e32 v101, v2
	v_mov_b32_e32 v102, v2
	v_mov_b32_e32 v103, v2
	v_mov_b32_e32 v104, v2
	v_mov_b32_e32 v105, v2
	v_mov_b32_e32 v114, v2
	v_mov_b32_e32 v115, v2
	v_mov_b32_e32 v116, v2
	v_mov_b32_e32 v117, v2
	v_mov_b32_e32 v118, v2
	v_mov_b32_e32 v119, v2
	v_mov_b32_e32 v120, v2
	v_mov_b32_e32 v121, v2
	v_mov_b32_e32 v74, v2
	v_mov_b32_e32 v75, v2
	v_mov_b32_e32 v76, v2
	v_mov_b32_e32 v77, v2
	v_mov_b32_e32 v78, v2
	v_mov_b32_e32 v79, v2
	v_mov_b32_e32 v80, v2
	v_mov_b32_e32 v81, v2
	v_mov_b32_e32 v90, v2
	v_mov_b32_e32 v91, v2
	v_mov_b32_e32 v92, v2
	v_mov_b32_e32 v93, v2
	v_mov_b32_e32 v94, v2
	v_mov_b32_e32 v95, v2
	v_mov_b32_e32 v96, v2
	v_mov_b32_e32 v97, v2
	v_mov_b32_e32 v106, v2
	v_mov_b32_e32 v107, v2
	v_mov_b32_e32 v108, v2
	v_mov_b32_e32 v109, v2
	v_mov_b32_e32 v110, v2
	v_mov_b32_e32 v111, v2
	v_mov_b32_e32 v112, v2
	v_mov_b32_e32 v113, v2
	v_mov_b32_e32 v122, v2
	v_mov_b32_e32 v123, v2
	v_mov_b32_e32 v124, v2
	v_mov_b32_e32 v125, v2
	v_mov_b32_e32 v126, v2
	v_mov_b32_e32 v127, v2
	v_mov_b32_e32 v128, v2
	v_mov_b32_e32 v129, v2
	s_and_b64 vcc, exec, s[38:39]
	s_cbranch_vccnz .Lsprio_5
	s_setprio 1
.Lsprio_5:
.LBB0_2494:
	ds_read_b128 v[160:163], v155
	ds_read_b128 v[164:167], v155 offset:1024
	ds_read_b128 v[168:171], v155 offset:2048
	ds_read_b128 v[172:175], v155 offset:3072
	ds_read_b128 v[176:179], v156
	ds_read_b128 v[184:187], v156 offset:1024
	ds_read_b128 v[188:191], v156 offset:2048
	ds_read_b128 v[192:195], v156 offset:3072
	s_add_u32 s48, s6, 0xfff00080
	s_addc_u32 s49, s7, -1
	s_cmp_eq_u32 s89, 60
	s_cselect_b32 s51, s43, s49
	s_cselect_b32 s50, s85, s48
	s_cselect_b32 s49, s41, s88
	s_cselect_b32 s48, s86, s87
	s_add_i32 m0, s63, 0xc000
	ds_read_b128 v[196:199], v157
	ds_read_b128 v[200:203], v157 offset:1024
	ds_read_b128 v[204:207], v157 offset:2048
	ds_read_b128 v[208:211], v157 offset:3072
	ds_read_b128 v[212:215], v157 offset:4096
	ds_read_b128 v[216:219], v157 offset:5120
	ds_read_b128 v[220:223], v157 offset:6144
	ds_read_b128 v[224:227], v157 offset:7168
	global_load_lds_dwordx4 v140, s[6:7]
	s_add_i32 m0, s63, 0xe000
	s_nop 0
	global_load_lds_dwordx4 v142, s[6:7]
	s_waitcnt vmcnt(8)
	s_waitcnt lgkmcnt(0)
	s_barrier
	v_mfma_f32_16x16x32_bf16 v[126:129], v[160:163], v[196:199], v[126:129]
	v_mfma_f32_16x16x32_bf16 v[126:129], v[164:167], v[200:203], v[126:129]
	v_mfma_f32_16x16x32_bf16 v[122:125], v[168:171], v[196:199], v[122:125]
	v_mfma_f32_16x16x32_bf16 v[122:125], v[172:175], v[200:203], v[122:125]
	v_mfma_f32_16x16x32_bf16 v[118:121], v[176:179], v[196:199], v[118:121]
	v_mfma_f32_16x16x32_bf16 v[118:121], v[184:187], v[200:203], v[118:121]
	v_mfma_f32_16x16x32_bf16 v[114:117], v[188:191], v[196:199], v[114:117]
	v_mfma_f32_16x16x32_bf16 v[114:117], v[192:195], v[200:203], v[114:117]
	v_mfma_f32_16x16x32_bf16 v[110:113], v[160:163], v[204:207], v[110:113]
	v_mfma_f32_16x16x32_bf16 v[110:113], v[164:167], v[208:211], v[110:113]
	v_mfma_f32_16x16x32_bf16 v[106:109], v[168:171], v[204:207], v[106:109]
	v_mfma_f32_16x16x32_bf16 v[106:109], v[172:175], v[208:211], v[106:109]
	v_mfma_f32_16x16x32_bf16 v[102:105], v[176:179], v[204:207], v[102:105]
	v_mfma_f32_16x16x32_bf16 v[102:105], v[184:187], v[208:211], v[102:105]
	v_mfma_f32_16x16x32_bf16 v[98:101], v[188:191], v[204:207], v[98:101]
	v_mfma_f32_16x16x32_bf16 v[98:101], v[192:195], v[208:211], v[98:101]
	v_mfma_f32_16x16x32_bf16 v[94:97], v[160:163], v[212:215], v[94:97]
	v_mfma_f32_16x16x32_bf16 v[94:97], v[164:167], v[216:219], v[94:97]
	v_mfma_f32_16x16x32_bf16 v[90:93], v[168:171], v[212:215], v[90:93]
	v_mfma_f32_16x16x32_bf16 v[90:93], v[172:175], v[216:219], v[90:93]
	v_mfma_f32_16x16x32_bf16 v[86:89], v[176:179], v[212:215], v[86:89]
	v_mfma_f32_16x16x32_bf16 v[86:89], v[184:187], v[216:219], v[86:89]
	v_mfma_f32_16x16x32_bf16 v[82:85], v[188:191], v[212:215], v[82:85]
	v_mfma_f32_16x16x32_bf16 v[82:85], v[192:195], v[216:219], v[82:85]
	v_mfma_f32_16x16x32_bf16 v[78:81], v[160:163], v[220:223], v[78:81]
	v_mfma_f32_16x16x32_bf16 v[78:81], v[164:167], v[224:227], v[78:81]
	v_mfma_f32_16x16x32_bf16 v[74:77], v[168:171], v[220:223], v[74:77]
	v_mfma_f32_16x16x32_bf16 v[74:77], v[172:175], v[224:227], v[74:77]
	v_mfma_f32_16x16x32_bf16 v[70:73], v[176:179], v[220:223], v[70:73]
	v_mfma_f32_16x16x32_bf16 v[70:73], v[184:187], v[224:227], v[70:73]
	v_mfma_f32_16x16x32_bf16 v[66:69], v[188:191], v[220:223], v[66:69]
	v_mfma_f32_16x16x32_bf16 v[66:69], v[192:195], v[224:227], v[66:69]
	s_barrier
	s_add_i32 s90, s73, s27
	s_add_u32 s98, s48, 0x80
	s_addc_u32 s99, s49, 0
	s_mov_b32 m0, s90
	ds_read_b128 v[196:199], v157 offset:16384
	ds_read_b128 v[200:203], v157 offset:17408
	ds_read_b128 v[204:207], v157 offset:18432
	ds_read_b128 v[208:211], v157 offset:19456
	ds_read_b128 v[212:215], v157 offset:20480
	ds_read_b128 v[216:219], v157 offset:21504
	ds_read_b128 v[220:223], v157 offset:22528
	ds_read_b128 v[224:227], v157 offset:23552
	global_load_lds_dwordx4 v132, s[48:49]
	s_add_i32 m0, s90, 0x2000
	s_add_u32 s90, s48, 0x100000
	s_addc_u32 s91, s49, 0
	s_add_i32 s92, s74, s27
	global_load_lds_dwordx4 v136, s[48:49]
	s_mov_b32 m0, s92
	global_load_lds_dwordx4 v132, s[90:91]
	s_add_i32 m0, s92, 0x2000
	s_nop 0
	global_load_lds_dwordx4 v136, s[90:91]
	s_add_u32 s100, s50, 0x80
	s_addc_u32 s101, s51, 0
	s_mov_b32 m0, s63
	s_nop 0
	global_load_lds_dwordx4 v130, s[50:51]
	s_mov_b32 m0, s65
	s_nop 0
	global_load_lds_dwordx4 v134, s[50:51]
	s_waitcnt vmcnt(8)
	s_waitcnt lgkmcnt(0)
	s_barrier
	v_mfma_f32_16x16x32_bf16 v[62:65], v[160:163], v[196:199], v[62:65]
	v_mfma_f32_16x16x32_bf16 v[62:65], v[164:167], v[200:203], v[62:65]
	v_mfma_f32_16x16x32_bf16 v[58:61], v[168:171], v[196:199], v[58:61]
	v_mfma_f32_16x16x32_bf16 v[58:61], v[172:175], v[200:203], v[58:61]
	v_mfma_f32_16x16x32_bf16 v[54:57], v[176:179], v[196:199], v[54:57]
	v_mfma_f32_16x16x32_bf16 v[54:57], v[184:187], v[200:203], v[54:57]
	v_mfma_f32_16x16x32_bf16 v[46:49], v[188:191], v[196:199], v[46:49]
	v_mfma_f32_16x16x32_bf16 v[46:49], v[192:195], v[200:203], v[46:49]
	v_mfma_f32_16x16x32_bf16 v[50:53], v[160:163], v[204:207], v[50:53]
	v_mfma_f32_16x16x32_bf16 v[50:53], v[164:167], v[208:211], v[50:53]
	v_mfma_f32_16x16x32_bf16 v[42:45], v[168:171], v[204:207], v[42:45]
	v_mfma_f32_16x16x32_bf16 v[42:45], v[172:175], v[208:211], v[42:45]
	v_mfma_f32_16x16x32_bf16 v[38:41], v[176:179], v[204:207], v[38:41]
	v_mfma_f32_16x16x32_bf16 v[38:41], v[184:187], v[208:211], v[38:41]
	v_mfma_f32_16x16x32_bf16 v[30:33], v[188:191], v[204:207], v[30:33]
	v_mfma_f32_16x16x32_bf16 v[30:33], v[192:195], v[208:211], v[30:33]
	v_mfma_f32_16x16x32_bf16 v[34:37], v[160:163], v[212:215], v[34:37]
	v_mfma_f32_16x16x32_bf16 v[34:37], v[164:167], v[216:219], v[34:37]
	v_mfma_f32_16x16x32_bf16 v[26:29], v[168:171], v[212:215], v[26:29]
	v_mfma_f32_16x16x32_bf16 v[26:29], v[172:175], v[216:219], v[26:29]
	v_mfma_f32_16x16x32_bf16 v[22:25], v[176:179], v[212:215], v[22:25]
	v_mfma_f32_16x16x32_bf16 v[22:25], v[184:187], v[216:219], v[22:25]
	v_mfma_f32_16x16x32_bf16 v[14:17], v[188:191], v[212:215], v[14:17]
	v_mfma_f32_16x16x32_bf16 v[14:17], v[192:195], v[216:219], v[14:17]
	v_mfma_f32_16x16x32_bf16 v[18:21], v[160:163], v[220:223], v[18:21]
	v_mfma_f32_16x16x32_bf16 v[18:21], v[164:167], v[224:227], v[18:21]
	v_mfma_f32_16x16x32_bf16 v[10:13], v[168:171], v[220:223], v[10:13]
	v_mfma_f32_16x16x32_bf16 v[10:13], v[172:175], v[224:227], v[10:13]
	v_mfma_f32_16x16x32_bf16 v[6:9], v[176:179], v[220:223], v[6:9]
	v_mfma_f32_16x16x32_bf16 v[6:9], v[184:187], v[224:227], v[6:9]
	v_mfma_f32_16x16x32_bf16 v[2:5], v[188:191], v[220:223], v[2:5]
	v_mfma_f32_16x16x32_bf16 v[2:5], v[192:195], v[224:227], v[2:5]
	s_barrier
	s_add_i32 s90, 0, 0x18000
	v_add_u32_e32 v138, s90, v151
	s_add_i32 s91, 0, 0x1c000
	ds_read_b128 v[160:163], v138
	ds_read_b128 v[164:167], v138 offset:1024
	ds_read_b128 v[168:171], v138 offset:2048
	ds_read_b128 v[172:175], v138 offset:3072
	v_add_u32_e32 v138, s91, v151
	ds_read_b128 v[176:179], v138
	ds_read_b128 v[184:187], v138 offset:1024
	ds_read_b128 v[188:191], v138 offset:2048
	ds_read_b128 v[192:195], v138 offset:3072
	s_add_u32 s50, s50, 0x100000
	s_addc_u32 s51, s51, 0
	s_mov_b32 m0, s66
	ds_read_b128 v[196:199], v157 offset:32768
	ds_read_b128 v[200:203], v157 offset:33792
	ds_read_b128 v[204:207], v157 offset:34816
	ds_read_b128 v[208:211], v157 offset:35840
	ds_read_b128 v[212:215], v157 offset:36864
	ds_read_b128 v[216:219], v157 offset:37888
	ds_read_b128 v[220:223], v157 offset:38912
	ds_read_b128 v[224:227], v157 offset:39936
	global_load_lds_dwordx4 v130, s[50:51]
	s_mov_b32 m0, s67
	s_nop 0
	global_load_lds_dwordx4 v134, s[50:51]
	s_waitcnt vmcnt(8)
	s_waitcnt lgkmcnt(0)
	s_barrier
	v_mfma_f32_16x16x32_bf16 v[126:129], v[160:163], v[196:199], v[126:129]
	v_mfma_f32_16x16x32_bf16 v[126:129], v[164:167], v[200:203], v[126:129]
	v_mfma_f32_16x16x32_bf16 v[122:125], v[168:171], v[196:199], v[122:125]
	v_mfma_f32_16x16x32_bf16 v[122:125], v[172:175], v[200:203], v[122:125]
	v_mfma_f32_16x16x32_bf16 v[118:121], v[176:179], v[196:199], v[118:121]
	v_mfma_f32_16x16x32_bf16 v[118:121], v[184:187], v[200:203], v[118:121]
	v_mfma_f32_16x16x32_bf16 v[114:117], v[188:191], v[196:199], v[114:117]
	v_mfma_f32_16x16x32_bf16 v[114:117], v[192:195], v[200:203], v[114:117]
	v_mfma_f32_16x16x32_bf16 v[110:113], v[160:163], v[204:207], v[110:113]
	v_mfma_f32_16x16x32_bf16 v[110:113], v[164:167], v[208:211], v[110:113]
	v_mfma_f32_16x16x32_bf16 v[106:109], v[168:171], v[204:207], v[106:109]
	v_mfma_f32_16x16x32_bf16 v[106:109], v[172:175], v[208:211], v[106:109]
	v_mfma_f32_16x16x32_bf16 v[102:105], v[176:179], v[204:207], v[102:105]
	v_mfma_f32_16x16x32_bf16 v[102:105], v[184:187], v[208:211], v[102:105]
	v_mfma_f32_16x16x32_bf16 v[98:101], v[188:191], v[204:207], v[98:101]
	v_mfma_f32_16x16x32_bf16 v[98:101], v[192:195], v[208:211], v[98:101]
	v_mfma_f32_16x16x32_bf16 v[94:97], v[160:163], v[212:215], v[94:97]
	v_mfma_f32_16x16x32_bf16 v[94:97], v[164:167], v[216:219], v[94:97]
	v_mfma_f32_16x16x32_bf16 v[90:93], v[168:171], v[212:215], v[90:93]
	v_mfma_f32_16x16x32_bf16 v[90:93], v[172:175], v[216:219], v[90:93]
	v_mfma_f32_16x16x32_bf16 v[86:89], v[176:179], v[212:215], v[86:89]
	v_mfma_f32_16x16x32_bf16 v[86:89], v[184:187], v[216:219], v[86:89]
	v_mfma_f32_16x16x32_bf16 v[82:85], v[188:191], v[212:215], v[82:85]
	v_mfma_f32_16x16x32_bf16 v[82:85], v[192:195], v[216:219], v[82:85]
	v_mfma_f32_16x16x32_bf16 v[78:81], v[160:163], v[220:223], v[78:81]
	v_mfma_f32_16x16x32_bf16 v[78:81], v[164:167], v[224:227], v[78:81]
	v_mfma_f32_16x16x32_bf16 v[74:77], v[168:171], v[220:223], v[74:77]
	v_mfma_f32_16x16x32_bf16 v[74:77], v[172:175], v[224:227], v[74:77]
	v_mfma_f32_16x16x32_bf16 v[70:73], v[176:179], v[220:223], v[70:73]
	v_mfma_f32_16x16x32_bf16 v[70:73], v[184:187], v[224:227], v[70:73]
	v_mfma_f32_16x16x32_bf16 v[66:69], v[188:191], v[220:223], v[66:69]
	v_mfma_f32_16x16x32_bf16 v[66:69], v[192:195], v[224:227], v[66:69]
	s_barrier
	s_add_i32 s50, s90, s27
	s_mov_b32 m0, s50
	ds_read_b128 v[196:199], v157 offset:49152
	ds_read_b128 v[200:203], v157 offset:50176
	ds_read_b128 v[204:207], v157 offset:51200
	ds_read_b128 v[208:211], v157 offset:52224
	ds_read_b128 v[212:215], v157 offset:53248
	ds_read_b128 v[216:219], v157 offset:54272
	ds_read_b128 v[220:223], v157 offset:55296
	ds_read_b128 v[224:227], v157 offset:56320
	global_load_lds_dwordx4 v132, s[98:99]
	s_add_i32 m0, s50, 0x2000
	s_add_u32 s48, s48, 0x100080
	s_addc_u32 s49, s49, 0
	s_add_i32 s50, s91, s27
	global_load_lds_dwordx4 v136, s[98:99]
	s_mov_b32 m0, s50
	s_nop 0
	global_load_lds_dwordx4 v132, s[48:49]
	s_add_i32 m0, s50, 0x2000
	s_nop 0
	global_load_lds_dwordx4 v136, s[48:49]
	s_mov_b32 m0, s69
	s_nop 0
	global_load_lds_dwordx4 v130, s[100:101]
	s_mov_b32 m0, s70
	s_nop 0
	global_load_lds_dwordx4 v134, s[100:101]
	s_waitcnt vmcnt(8)
	s_waitcnt lgkmcnt(0)
	s_barrier
	v_mfma_f32_16x16x32_bf16 v[62:65], v[160:163], v[196:199], v[62:65]
	v_mfma_f32_16x16x32_bf16 v[62:65], v[164:167], v[200:203], v[62:65]
	v_mfma_f32_16x16x32_bf16 v[58:61], v[168:171], v[196:199], v[58:61]
	v_mfma_f32_16x16x32_bf16 v[58:61], v[172:175], v[200:203], v[58:61]
	v_mfma_f32_16x16x32_bf16 v[54:57], v[176:179], v[196:199], v[54:57]
	v_mfma_f32_16x16x32_bf16 v[54:57], v[184:187], v[200:203], v[54:57]
	v_mfma_f32_16x16x32_bf16 v[46:49], v[188:191], v[196:199], v[46:49]
	v_mfma_f32_16x16x32_bf16 v[46:49], v[192:195], v[200:203], v[46:49]
	v_mfma_f32_16x16x32_bf16 v[50:53], v[160:163], v[204:207], v[50:53]
	v_mfma_f32_16x16x32_bf16 v[50:53], v[164:167], v[208:211], v[50:53]
	v_mfma_f32_16x16x32_bf16 v[42:45], v[168:171], v[204:207], v[42:45]
	v_mfma_f32_16x16x32_bf16 v[42:45], v[172:175], v[208:211], v[42:45]
	v_mfma_f32_16x16x32_bf16 v[38:41], v[176:179], v[204:207], v[38:41]
	v_mfma_f32_16x16x32_bf16 v[38:41], v[184:187], v[208:211], v[38:41]
	v_mfma_f32_16x16x32_bf16 v[30:33], v[188:191], v[204:207], v[30:33]
	v_mfma_f32_16x16x32_bf16 v[30:33], v[192:195], v[208:211], v[30:33]
	v_mfma_f32_16x16x32_bf16 v[34:37], v[160:163], v[212:215], v[34:37]
	v_mfma_f32_16x16x32_bf16 v[34:37], v[164:167], v[216:219], v[34:37]
	v_mfma_f32_16x16x32_bf16 v[26:29], v[168:171], v[212:215], v[26:29]
	v_mfma_f32_16x16x32_bf16 v[26:29], v[172:175], v[216:219], v[26:29]
	v_mfma_f32_16x16x32_bf16 v[22:25], v[176:179], v[212:215], v[22:25]
	v_mfma_f32_16x16x32_bf16 v[22:25], v[184:187], v[216:219], v[22:25]
	v_mfma_f32_16x16x32_bf16 v[14:17], v[188:191], v[212:215], v[14:17]
	v_mfma_f32_16x16x32_bf16 v[14:17], v[192:195], v[216:219], v[14:17]
	v_mfma_f32_16x16x32_bf16 v[18:21], v[160:163], v[220:223], v[18:21]
	v_mfma_f32_16x16x32_bf16 v[18:21], v[164:167], v[224:227], v[18:21]
	v_mfma_f32_16x16x32_bf16 v[10:13], v[168:171], v[220:223], v[10:13]
	v_mfma_f32_16x16x32_bf16 v[10:13], v[172:175], v[224:227], v[10:13]
	v_mfma_f32_16x16x32_bf16 v[6:9], v[176:179], v[220:223], v[6:9]
	v_mfma_f32_16x16x32_bf16 v[6:9], v[184:187], v[224:227], v[6:9]
	v_mfma_f32_16x16x32_bf16 v[2:5], v[188:191], v[220:223], v[2:5]
	v_mfma_f32_16x16x32_bf16 v[2:5], v[192:195], v[224:227], v[2:5]
	s_barrier
	s_add_i32 s89, s89, 2
	s_add_u32 s6, s6, 0x100
	s_addc_u32 s7, s7, 0
	s_add_u32 s87, s87, 0x100
	s_addc_u32 s88, s88, 0
	s_cmp_gt_u32 s89, 61
	s_cbranch_scc0 .LBB0_2494
	s_setprio 0
	s_and_b64 vcc, exec, s[38:39]
	s_cbranch_vccz .LBB0_2497
	s_barrier

.LBB0_2634:
	s_ashr_i32 s41, s40, 31
	s_lshl_b64 s[42:43], s[40:41], 21
	s_add_u32 s42, s10, s42
	s_addc_u32 s43, s11, s43
	s_and_b64 s[44:45], s[6:7], exec
	s_cselect_b32 s22, s43, s47
	s_cselect_b32 s41, s42, s46
	s_ashr_i32 s39, s38, 31
	s_lshl_b64 s[44:45], s[38:39], 21
	v_readlane_b32 s50, v245, 12
	v_readlane_b32 s51, v245, 13
	s_add_u32 s44, s50, s44
	s_addc_u32 s45, s51, s45
	s_and_b64 s[50:51], s[6:7], exec
	s_cselect_b32 s39, s45, s49
	s_cselect_b32 s70, s44, s48
	s_add_u32 s46, s46, 0x100080
	s_addc_u32 s47, s47, 0
	s_add_u32 s71, s48, 0x100
	v_mov_b32_e32 v2, 0
	s_addc_u32 s72, s49, 0
	s_mov_b32 s73, -2
	s_waitcnt lgkmcnt(0)
	v_mov_b32_e32 v3, v2
	v_mov_b32_e32 v4, v2
	v_mov_b32_e32 v5, v2
	v_mov_b32_e32 v6, v2
	v_mov_b32_e32 v7, v2
	v_mov_b32_e32 v8, v2
	v_mov_b32_e32 v9, v2
	v_mov_b32_e32 v18, v2
	v_mov_b32_e32 v19, v2
	v_mov_b32_e32 v20, v2
	v_mov_b32_e32 v21, v2
	v_mov_b32_e32 v22, v2
	v_mov_b32_e32 v23, v2
	v_mov_b32_e32 v24, v2
	v_mov_b32_e32 v25, v2
	v_mov_b32_e32 v34, v2
	v_mov_b32_e32 v35, v2
	v_mov_b32_e32 v36, v2
	v_mov_b32_e32 v37, v2
	v_mov_b32_e32 v38, v2
	v_mov_b32_e32 v39, v2
	v_mov_b32_e32 v40, v2
	v_mov_b32_e32 v41, v2
	v_mov_b32_e32 v50, v2
	v_mov_b32_e32 v51, v2
	v_mov_b32_e32 v52, v2
	v_mov_b32_e32 v53, v2
	v_mov_b32_e32 v54, v2
	v_mov_b32_e32 v55, v2
	v_mov_b32_e32 v56, v2
	v_mov_b32_e32 v57, v2
	v_mov_b32_e32 v10, v2
	v_mov_b32_e32 v11, v2
	v_mov_b32_e32 v12, v2
	v_mov_b32_e32 v13, v2
	v_mov_b32_e32 v14, v2
	v_mov_b32_e32 v15, v2
	v_mov_b32_e32 v16, v2
	v_mov_b32_e32 v17, v2
	v_mov_b32_e32 v26, v2
	v_mov_b32_e32 v27, v2
	v_mov_b32_e32 v28, v2
	v_mov_b32_e32 v29, v2
	v_mov_b32_e32 v30, v2
	v_mov_b32_e32 v31, v2
	v_mov_b32_e32 v32, v2
	v_mov_b32_e32 v33, v2
	v_mov_b32_e32 v42, v2
	v_mov_b32_e32 v43, v2
	v_mov_b32_e32 v44, v2
	v_mov_b32_e32 v45, v2
	v_mov_b32_e32 v46, v2
	v_mov_b32_e32 v47, v2
	v_mov_b32_e32 v48, v2
	v_mov_b32_e32 v49, v2
	v_mov_b32_e32 v58, v2
	v_mov_b32_e32 v59, v2
	v_mov_b32_e32 v60, v2
	v_mov_b32_e32 v61, v2
	v_mov_b32_e32 v62, v2
	v_mov_b32_e32 v63, v2
	v_mov_b32_e32 v64, v2
	v_mov_b32_e32 v65, v2
	v_mov_b32_e32 v66, v2
	v_mov_b32_e32 v67, v2
	v_mov_b32_e32 v68, v2
	v_mov_b32_e32 v69, v2
	v_mov_b32_e32 v70, v2
	v_mov_b32_e32 v71, v2
	v_mov_b32_e32 v72, v2
	v_mov_b32_e32 v73, v2
	v_mov_b32_e32 v82, v2
	v_mov_b32_e32 v83, v2
	v_mov_b32_e32 v84, v2
	v_mov_b32_e32 v85, v2
	v_mov_b32_e32 v86, v2
	v_mov_b32_e32 v87, v2
	v_mov_b32_e32 v88, v2
	v_mov_b32_e32 v89, v2
	v_mov_b32_e32 v98, v2
	v_mov_b32_e32 v99, v2
	v_mov_b32_e32 v100, v2
	v_mov_b32_e32 v101, v2
	v_mov_b32_e32 v102, v2
	v_mov_b32_e32 v103, v2
	v_mov_b32_e32 v104, v2
	v_mov_b32_e32 v105, v2
	v_mov_b32_e32 v114, v2
	v_mov_b32_e32 v115, v2
	v_mov_b32_e32 v116, v2
	v_mov_b32_e32 v117, v2
	v_mov_b32_e32 v118, v2
	v_mov_b32_e32 v119, v2
	v_mov_b32_e32 v120, v2
	v_mov_b32_e32 v121, v2
	v_mov_b32_e32 v74, v2
	v_mov_b32_e32 v75, v2
	v_mov_b32_e32 v76, v2
	v_mov_b32_e32 v77, v2
	v_mov_b32_e32 v78, v2
	v_mov_b32_e32 v79, v2
	v_mov_b32_e32 v80, v2
	v_mov_b32_e32 v81, v2
	v_mov_b32_e32 v90, v2
	v_mov_b32_e32 v91, v2
	v_mov_b32_e32 v92, v2
	v_mov_b32_e32 v93, v2
	v_mov_b32_e32 v94, v2
	v_mov_b32_e32 v95, v2
	v_mov_b32_e32 v96, v2
	v_mov_b32_e32 v97, v2
	v_mov_b32_e32 v106, v2
	v_mov_b32_e32 v107, v2
	v_mov_b32_e32 v108, v2
	v_mov_b32_e32 v109, v2
	v_mov_b32_e32 v110, v2
	v_mov_b32_e32 v111, v2
	v_mov_b32_e32 v112, v2
	v_mov_b32_e32 v113, v2
	v_mov_b32_e32 v122, v2
	v_mov_b32_e32 v123, v2
	v_mov_b32_e32 v124, v2
	v_mov_b32_e32 v125, v2
	v_mov_b32_e32 v126, v2
	v_mov_b32_e32 v127, v2
	v_mov_b32_e32 v128, v2
	v_mov_b32_e32 v129, v2
	s_and_b64 vcc, exec, s[36:37]
	s_cbranch_vccnz .Lsprio_6
	s_setprio 1
.Lsprio_6:
.LBB0_2635:
	ds_read_b128 v[130:133], v163
	ds_read_b128 v[134:137], v163 offset:1024
	ds_read_b128 v[138:141], v163 offset:2048
	ds_read_b128 v[142:145], v163 offset:3072
	ds_read_b128 v[146:149], v188
	ds_read_b128 v[150:153], v188 offset:1024
	ds_read_b128 v[174:177], v188 offset:2048
	ds_read_b128 v[178:181], v188 offset:3072
	s_add_u32 s48, s46, 0xfff00080
	s_addc_u32 s49, s47, -1
	s_cmp_eq_u32 s73, 60
	s_cselect_b32 s51, s22, s49
	s_cselect_b32 s50, s41, s48
	s_cselect_b32 s49, s39, s72
	s_cselect_b32 s48, s70, s71
	s_add_i32 m0, s13, 0xc000
	ds_read_b128 v[184:187], v189
	ds_read_b128 v[192:195], v189 offset:1024
	ds_read_b128 v[196:199], v189 offset:2048
	ds_read_b128 v[200:203], v189 offset:3072
	ds_read_b128 v[204:207], v189 offset:4096
	ds_read_b128 v[208:211], v189 offset:5120
	ds_read_b128 v[212:215], v189 offset:6144
	ds_read_b128 v[216:219], v189 offset:7168
	global_load_lds_dwordx4 v166, s[46:47]
	s_add_i32 m0, s13, 0xe000
	s_nop 0
	global_load_lds_dwordx4 v168, s[46:47]
	s_waitcnt vmcnt(8)
	s_waitcnt lgkmcnt(0)
	s_barrier
	v_mfma_f32_16x16x32_bf16 v[126:129], v[130:133], v[184:187], v[126:129]
	v_mfma_f32_16x16x32_bf16 v[126:129], v[134:137], v[192:195], v[126:129]
	v_mfma_f32_16x16x32_bf16 v[122:125], v[138:141], v[184:187], v[122:125]
	v_mfma_f32_16x16x32_bf16 v[122:125], v[142:145], v[192:195], v[122:125]
	v_mfma_f32_16x16x32_bf16 v[118:121], v[146:149], v[184:187], v[118:121]
	v_mfma_f32_16x16x32_bf16 v[118:121], v[150:153], v[192:195], v[118:121]
	v_mfma_f32_16x16x32_bf16 v[114:117], v[174:177], v[184:187], v[114:117]
	v_mfma_f32_16x16x32_bf16 v[114:117], v[178:181], v[192:195], v[114:117]
	v_mfma_f32_16x16x32_bf16 v[110:113], v[130:133], v[196:199], v[110:113]
	v_mfma_f32_16x16x32_bf16 v[110:113], v[134:137], v[200:203], v[110:113]
	v_mfma_f32_16x16x32_bf16 v[106:109], v[138:141], v[196:199], v[106:109]
	v_mfma_f32_16x16x32_bf16 v[106:109], v[142:145], v[200:203], v[106:109]
	v_mfma_f32_16x16x32_bf16 v[102:105], v[146:149], v[196:199], v[102:105]
	v_mfma_f32_16x16x32_bf16 v[102:105], v[150:153], v[200:203], v[102:105]
	v_mfma_f32_16x16x32_bf16 v[98:101], v[174:177], v[196:199], v[98:101]
	v_mfma_f32_16x16x32_bf16 v[98:101], v[178:181], v[200:203], v[98:101]
	v_mfma_f32_16x16x32_bf16 v[94:97], v[130:133], v[204:207], v[94:97]
	v_mfma_f32_16x16x32_bf16 v[94:97], v[134:137], v[208:211], v[94:97]
	v_mfma_f32_16x16x32_bf16 v[90:93], v[138:141], v[204:207], v[90:93]
	v_mfma_f32_16x16x32_bf16 v[90:93], v[142:145], v[208:211], v[90:93]
	v_mfma_f32_16x16x32_bf16 v[86:89], v[146:149], v[204:207], v[86:89]
	v_mfma_f32_16x16x32_bf16 v[86:89], v[150:153], v[208:211], v[86:89]
	v_mfma_f32_16x16x32_bf16 v[82:85], v[174:177], v[204:207], v[82:85]
	v_mfma_f32_16x16x32_bf16 v[82:85], v[178:181], v[208:211], v[82:85]
	v_mfma_f32_16x16x32_bf16 v[78:81], v[130:133], v[212:215], v[78:81]
	v_mfma_f32_16x16x32_bf16 v[78:81], v[134:137], v[216:219], v[78:81]
	v_mfma_f32_16x16x32_bf16 v[74:77], v[138:141], v[212:215], v[74:77]
	v_mfma_f32_16x16x32_bf16 v[74:77], v[142:145], v[216:219], v[74:77]
	v_mfma_f32_16x16x32_bf16 v[70:73], v[146:149], v[212:215], v[70:73]
	v_mfma_f32_16x16x32_bf16 v[70:73], v[150:153], v[216:219], v[70:73]
	v_mfma_f32_16x16x32_bf16 v[66:69], v[174:177], v[212:215], v[66:69]
	v_mfma_f32_16x16x32_bf16 v[66:69], v[178:181], v[216:219], v[66:69]
	s_barrier
	s_add_i32 s74, s67, s3
	s_add_u32 s98, s48, 0x80
	s_addc_u32 s99, s49, 0
	s_mov_b32 m0, s74
	ds_read_b128 v[184:187], v189 offset:16384
	ds_read_b128 v[192:195], v189 offset:17408
	ds_read_b128 v[196:199], v189 offset:18432
	ds_read_b128 v[200:203], v189 offset:19456
	ds_read_b128 v[204:207], v189 offset:20480
	ds_read_b128 v[208:211], v189 offset:21504
	ds_read_b128 v[212:215], v189 offset:22528
	ds_read_b128 v[216:219], v189 offset:23552
	global_load_lds_dwordx4 v156, s[48:49]
	s_add_i32 m0, s74, 0x2000
	s_add_u32 s74, s48, 0x100000
	s_addc_u32 s75, s49, 0
	s_add_i32 s76, s68, s3
	global_load_lds_dwordx4 v160, s[48:49]
	s_mov_b32 m0, s76
	global_load_lds_dwordx4 v156, s[74:75]
	s_add_i32 m0, s76, 0x2000
	s_nop 0
	global_load_lds_dwordx4 v160, s[74:75]
	s_add_u32 s100, s50, 0x80
	s_addc_u32 s101, s51, 0
	s_mov_b32 m0, s13
	s_nop 0
	global_load_lds_dwordx4 v154, s[50:51]
	s_mov_b32 m0, s21
	s_nop 0
	global_load_lds_dwordx4 v158, s[50:51]
	s_waitcnt vmcnt(8)
	s_waitcnt lgkmcnt(0)
	s_barrier
	v_mfma_f32_16x16x32_bf16 v[62:65], v[130:133], v[184:187], v[62:65]
	v_mfma_f32_16x16x32_bf16 v[62:65], v[134:137], v[192:195], v[62:65]
	v_mfma_f32_16x16x32_bf16 v[58:61], v[138:141], v[184:187], v[58:61]
	v_mfma_f32_16x16x32_bf16 v[58:61], v[142:145], v[192:195], v[58:61]
	v_mfma_f32_16x16x32_bf16 v[54:57], v[146:149], v[184:187], v[54:57]
	v_mfma_f32_16x16x32_bf16 v[54:57], v[150:153], v[192:195], v[54:57]
	v_mfma_f32_16x16x32_bf16 v[50:53], v[174:177], v[184:187], v[50:53]
	v_mfma_f32_16x16x32_bf16 v[50:53], v[178:181], v[192:195], v[50:53]
	v_mfma_f32_16x16x32_bf16 v[46:49], v[130:133], v[196:199], v[46:49]
	v_mfma_f32_16x16x32_bf16 v[46:49], v[134:137], v[200:203], v[46:49]
	v_mfma_f32_16x16x32_bf16 v[42:45], v[138:141], v[196:199], v[42:45]
	v_mfma_f32_16x16x32_bf16 v[42:45], v[142:145], v[200:203], v[42:45]
	v_mfma_f32_16x16x32_bf16 v[38:41], v[146:149], v[196:199], v[38:41]
	v_mfma_f32_16x16x32_bf16 v[38:41], v[150:153], v[200:203], v[38:41]
	v_mfma_f32_16x16x32_bf16 v[34:37], v[174:177], v[196:199], v[34:37]
	v_mfma_f32_16x16x32_bf16 v[34:37], v[178:181], v[200:203], v[34:37]
	v_mfma_f32_16x16x32_bf16 v[30:33], v[130:133], v[204:207], v[30:33]
	v_mfma_f32_16x16x32_bf16 v[30:33], v[134:137], v[208:211], v[30:33]
	v_mfma_f32_16x16x32_bf16 v[26:29], v[138:141], v[204:207], v[26:29]
	v_mfma_f32_16x16x32_bf16 v[26:29], v[142:145], v[208:211], v[26:29]
	v_mfma_f32_16x16x32_bf16 v[22:25], v[146:149], v[204:207], v[22:25]
	v_mfma_f32_16x16x32_bf16 v[22:25], v[150:153], v[208:211], v[22:25]
	v_mfma_f32_16x16x32_bf16 v[18:21], v[174:177], v[204:207], v[18:21]
	v_mfma_f32_16x16x32_bf16 v[18:21], v[178:181], v[208:211], v[18:21]
	v_mfma_f32_16x16x32_bf16 v[14:17], v[130:133], v[212:215], v[14:17]
	v_mfma_f32_16x16x32_bf16 v[14:17], v[134:137], v[216:219], v[14:17]
	v_mfma_f32_16x16x32_bf16 v[10:13], v[138:141], v[212:215], v[10:13]
	v_mfma_f32_16x16x32_bf16 v[10:13], v[142:145], v[216:219], v[10:13]
	v_mfma_f32_16x16x32_bf16 v[6:9], v[146:149], v[212:215], v[6:9]
	v_mfma_f32_16x16x32_bf16 v[6:9], v[150:153], v[216:219], v[6:9]
	v_mfma_f32_16x16x32_bf16 v[2:5], v[174:177], v[212:215], v[2:5]
	v_mfma_f32_16x16x32_bf16 v[2:5], v[178:181], v[216:219], v[2:5]
	s_barrier
	s_add_i32 s74, 0, 0x18000
	s_add_i32 s75, 0, 0x1c000
	v_add_u32_e32 v142, s74, v1
	v_add_u32_e32 v178, s75, v1
	ds_read_b128 v[130:133], v142
	ds_read_b128 v[134:137], v142 offset:1024
	ds_read_b128 v[138:141], v142 offset:2048
	ds_read_b128 v[142:145], v142 offset:3072
	ds_read_b128 v[146:149], v178
	ds_read_b128 v[150:153], v178 offset:1024
	ds_read_b128 v[174:177], v178 offset:2048
	ds_read_b128 v[178:181], v178 offset:3072
	s_add_u32 s50, s50, 0x100000
	s_addc_u32 s51, s51, 0
	s_mov_b32 m0, s33
	ds_read_b128 v[184:187], v189 offset:32768
	ds_read_b128 v[192:195], v189 offset:33792
	ds_read_b128 v[196:199], v189 offset:34816
	ds_read_b128 v[200:203], v189 offset:35840
	ds_read_b128 v[204:207], v189 offset:36864
	ds_read_b128 v[208:211], v189 offset:37888
	ds_read_b128 v[212:215], v189 offset:38912
	ds_read_b128 v[216:219], v189 offset:39936
	global_load_lds_dwordx4 v154, s[50:51]
	s_mov_b32 m0, s35
	s_nop 0
	global_load_lds_dwordx4 v158, s[50:51]
	s_waitcnt vmcnt(8)
	s_waitcnt lgkmcnt(0)
	s_barrier
	v_mfma_f32_16x16x32_bf16 v[126:129], v[130:133], v[184:187], v[126:129]
	v_mfma_f32_16x16x32_bf16 v[126:129], v[134:137], v[192:195], v[126:129]
	v_mfma_f32_16x16x32_bf16 v[122:125], v[138:141], v[184:187], v[122:125]
	v_mfma_f32_16x16x32_bf16 v[122:125], v[142:145], v[192:195], v[122:125]
	v_mfma_f32_16x16x32_bf16 v[118:121], v[146:149], v[184:187], v[118:121]
	v_mfma_f32_16x16x32_bf16 v[118:121], v[150:153], v[192:195], v[118:121]
	v_mfma_f32_16x16x32_bf16 v[114:117], v[174:177], v[184:187], v[114:117]
	v_mfma_f32_16x16x32_bf16 v[114:117], v[178:181], v[192:195], v[114:117]
	v_mfma_f32_16x16x32_bf16 v[110:113], v[130:133], v[196:199], v[110:113]
	v_mfma_f32_16x16x32_bf16 v[110:113], v[134:137], v[200:203], v[110:113]
	v_mfma_f32_16x16x32_bf16 v[106:109], v[138:141], v[196:199], v[106:109]
	v_mfma_f32_16x16x32_bf16 v[106:109], v[142:145], v[200:203], v[106:109]
	v_mfma_f32_16x16x32_bf16 v[102:105], v[146:149], v[196:199], v[102:105]
	v_mfma_f32_16x16x32_bf16 v[102:105], v[150:153], v[200:203], v[102:105]
	v_mfma_f32_16x16x32_bf16 v[98:101], v[174:177], v[196:199], v[98:101]
	v_mfma_f32_16x16x32_bf16 v[98:101], v[178:181], v[200:203], v[98:101]
	v_mfma_f32_16x16x32_bf16 v[94:97], v[130:133], v[204:207], v[94:97]
	v_mfma_f32_16x16x32_bf16 v[94:97], v[134:137], v[208:211], v[94:97]
	v_mfma_f32_16x16x32_bf16 v[90:93], v[138:141], v[204:207], v[90:93]
	v_mfma_f32_16x16x32_bf16 v[90:93], v[142:145], v[208:211], v[90:93]
	v_mfma_f32_16x16x32_bf16 v[86:89], v[146:149], v[204:207], v[86:89]
	v_mfma_f32_16x16x32_bf16 v[86:89], v[150:153], v[208:211], v[86:89]
	v_mfma_f32_16x16x32_bf16 v[82:85], v[174:177], v[204:207], v[82:85]
	v_mfma_f32_16x16x32_bf16 v[82:85], v[178:181], v[208:211], v[82:85]
	v_mfma_f32_16x16x32_bf16 v[78:81], v[130:133], v[212:215], v[78:81]
	v_mfma_f32_16x16x32_bf16 v[78:81], v[134:137], v[216:219], v[78:81]
	v_mfma_f32_16x16x32_bf16 v[74:77], v[138:141], v[212:215], v[74:77]
	v_mfma_f32_16x16x32_bf16 v[74:77], v[142:145], v[216:219], v[74:77]
	v_mfma_f32_16x16x32_bf16 v[70:73], v[146:149], v[212:215], v[70:73]
	v_mfma_f32_16x16x32_bf16 v[70:73], v[150:153], v[216:219], v[70:73]
	v_mfma_f32_16x16x32_bf16 v[66:69], v[174:177], v[212:215], v[66:69]
	v_mfma_f32_16x16x32_bf16 v[66:69], v[178:181], v[216:219], v[66:69]
	s_barrier
	s_add_i32 s50, s74, s3
	s_mov_b32 m0, s50
	ds_read_b128 v[184:187], v189 offset:49152
	ds_read_b128 v[192:195], v189 offset:50176
	ds_read_b128 v[196:199], v189 offset:51200
	ds_read_b128 v[200:203], v189 offset:52224
	ds_read_b128 v[204:207], v189 offset:53248
	ds_read_b128 v[208:211], v189 offset:54272
	ds_read_b128 v[212:215], v189 offset:55296
	ds_read_b128 v[216:219], v189 offset:56320
	global_load_lds_dwordx4 v156, s[98:99]
	s_add_i32 m0, s50, 0x2000
	s_add_u32 s48, s48, 0x100080
	s_addc_u32 s49, s49, 0
	s_add_i32 s50, s75, s3
	global_load_lds_dwordx4 v160, s[98:99]
	s_mov_b32 m0, s50
	s_nop 0
	global_load_lds_dwordx4 v156, s[48:49]
	s_add_i32 m0, s50, 0x2000
	s_nop 0
	global_load_lds_dwordx4 v160, s[48:49]
	s_mov_b32 m0, s62
	s_nop 0
	global_load_lds_dwordx4 v154, s[100:101]
	s_mov_b32 m0, s63
	s_nop 0
	global_load_lds_dwordx4 v158, s[100:101]
	s_waitcnt vmcnt(8)
	s_waitcnt lgkmcnt(0)
	s_barrier
	v_mfma_f32_16x16x32_bf16 v[62:65], v[130:133], v[184:187], v[62:65]
	v_mfma_f32_16x16x32_bf16 v[62:65], v[134:137], v[192:195], v[62:65]
	v_mfma_f32_16x16x32_bf16 v[58:61], v[138:141], v[184:187], v[58:61]
	v_mfma_f32_16x16x32_bf16 v[58:61], v[142:145], v[192:195], v[58:61]
	v_mfma_f32_16x16x32_bf16 v[54:57], v[146:149], v[184:187], v[54:57]
	v_mfma_f32_16x16x32_bf16 v[54:57], v[150:153], v[192:195], v[54:57]
	v_mfma_f32_16x16x32_bf16 v[50:53], v[174:177], v[184:187], v[50:53]
	v_mfma_f32_16x16x32_bf16 v[50:53], v[178:181], v[192:195], v[50:53]
	v_mfma_f32_16x16x32_bf16 v[46:49], v[130:133], v[196:199], v[46:49]
	v_mfma_f32_16x16x32_bf16 v[46:49], v[134:137], v[200:203], v[46:49]
	v_mfma_f32_16x16x32_bf16 v[42:45], v[138:141], v[196:199], v[42:45]
	v_mfma_f32_16x16x32_bf16 v[42:45], v[142:145], v[200:203], v[42:45]
	v_mfma_f32_16x16x32_bf16 v[38:41], v[146:149], v[196:199], v[38:41]
	v_mfma_f32_16x16x32_bf16 v[38:41], v[150:153], v[200:203], v[38:41]
	v_mfma_f32_16x16x32_bf16 v[34:37], v[174:177], v[196:199], v[34:37]
	v_mfma_f32_16x16x32_bf16 v[34:37], v[178:181], v[200:203], v[34:37]
	v_mfma_f32_16x16x32_bf16 v[30:33], v[130:133], v[204:207], v[30:33]
	v_mfma_f32_16x16x32_bf16 v[30:33], v[134:137], v[208:211], v[30:33]
	v_mfma_f32_16x16x32_bf16 v[26:29], v[138:141], v[204:207], v[26:29]
	v_mfma_f32_16x16x32_bf16 v[26:29], v[142:145], v[208:211], v[26:29]
	v_mfma_f32_16x16x32_bf16 v[22:25], v[146:149], v[204:207], v[22:25]
	v_mfma_f32_16x16x32_bf16 v[22:25], v[150:153], v[208:211], v[22:25]
	v_mfma_f32_16x16x32_bf16 v[18:21], v[174:177], v[204:207], v[18:21]
	v_mfma_f32_16x16x32_bf16 v[18:21], v[178:181], v[208:211], v[18:21]
	v_mfma_f32_16x16x32_bf16 v[14:17], v[130:133], v[212:215], v[14:17]
	v_mfma_f32_16x16x32_bf16 v[14:17], v[134:137], v[216:219], v[14:17]
	v_mfma_f32_16x16x32_bf16 v[10:13], v[138:141], v[212:215], v[10:13]
	v_mfma_f32_16x16x32_bf16 v[10:13], v[142:145], v[216:219], v[10:13]
	v_mfma_f32_16x16x32_bf16 v[6:9], v[146:149], v[212:215], v[6:9]
	v_mfma_f32_16x16x32_bf16 v[6:9], v[150:153], v[216:219], v[6:9]
	v_mfma_f32_16x16x32_bf16 v[2:5], v[174:177], v[212:215], v[2:5]
	v_mfma_f32_16x16x32_bf16 v[2:5], v[178:181], v[216:219], v[2:5]
	s_barrier
	s_add_i32 s73, s73, 2
	s_add_u32 s46, s46, 0x100
	s_addc_u32 s47, s47, 0
	s_add_u32 s71, s71, 0x100
	s_addc_u32 s72, s72, 0
	s_cmp_gt_u32 s73, 61
	s_cbranch_scc0 .LBB0_2635
	s_setprio 0
	s_and_b64 vcc, exec, s[36:37]
	s_cbranch_vccz .LBB0_2638
	s_barrier

.LBB0_2719:
	s_ashr_i32 s29, s28, 31
	s_lshl_b64 s[36:37], s[28:29], 21
	s_add_u32 s36, s16, s36
	s_addc_u32 s37, s17, s37
	s_and_b64 s[38:39], s[4:5], exec
	s_cselect_b32 s29, s37, s7
	s_cselect_b32 s78, s36, s6
	s_ashr_i32 s27, s26, 31
	s_lshl_b64 s[38:39], s[26:27], 21
	v_readlane_b32 s42, v245, 14
	v_readlane_b32 s43, v245, 15
	s_add_u32 s38, s42, s38
	s_addc_u32 s39, s43, s39
	s_and_b64 s[42:43], s[4:5], exec
	s_cselect_b32 s27, s39, s41
	s_cselect_b32 s79, s38, s40
	s_add_u32 s6, s6, 0x100080
	s_addc_u32 s7, s7, 0
	s_add_u32 s80, s40, 0x100
	v_mov_b32_e32 v2, 0
	s_addc_u32 s81, s41, 0
	s_mov_b32 s82, -2
	v_mov_b32_e32 v3, v2
	v_mov_b32_e32 v4, v2
	v_mov_b32_e32 v5, v2
	v_mov_b32_e32 v10, v2
	v_mov_b32_e32 v11, v2
	v_mov_b32_e32 v12, v2
	v_mov_b32_e32 v13, v2
	v_mov_b32_e32 v18, v2
	v_mov_b32_e32 v19, v2
	v_mov_b32_e32 v20, v2
	v_mov_b32_e32 v21, v2
	v_mov_b32_e32 v26, v2
	v_mov_b32_e32 v27, v2
	v_mov_b32_e32 v28, v2
	v_mov_b32_e32 v29, v2
	v_mov_b32_e32 v34, v2
	v_mov_b32_e32 v35, v2
	v_mov_b32_e32 v36, v2
	v_mov_b32_e32 v37, v2
	v_mov_b32_e32 v42, v2
	v_mov_b32_e32 v43, v2
	v_mov_b32_e32 v44, v2
	v_mov_b32_e32 v45, v2
	v_mov_b32_e32 v50, v2
	v_mov_b32_e32 v51, v2
	v_mov_b32_e32 v52, v2
	v_mov_b32_e32 v53, v2
	v_mov_b32_e32 v58, v2
	v_mov_b32_e32 v59, v2
	v_mov_b32_e32 v60, v2
	v_mov_b32_e32 v61, v2
	v_mov_b32_e32 v6, v2
	v_mov_b32_e32 v7, v2
	v_mov_b32_e32 v8, v2
	v_mov_b32_e32 v9, v2
	v_mov_b32_e32 v14, v2
	v_mov_b32_e32 v15, v2
	v_mov_b32_e32 v16, v2
	v_mov_b32_e32 v17, v2
	v_mov_b32_e32 v22, v2
	v_mov_b32_e32 v23, v2
	v_mov_b32_e32 v24, v2
	v_mov_b32_e32 v25, v2
	v_mov_b32_e32 v30, v2
	v_mov_b32_e32 v31, v2
	v_mov_b32_e32 v32, v2
	v_mov_b32_e32 v33, v2
	v_mov_b32_e32 v38, v2
	v_mov_b32_e32 v39, v2
	v_mov_b32_e32 v40, v2
	v_mov_b32_e32 v41, v2
	v_mov_b32_e32 v46, v2
	v_mov_b32_e32 v47, v2
	v_mov_b32_e32 v48, v2
	v_mov_b32_e32 v49, v2
	v_mov_b32_e32 v54, v2
	v_mov_b32_e32 v55, v2
	v_mov_b32_e32 v56, v2
	v_mov_b32_e32 v57, v2
	v_mov_b32_e32 v62, v2
	v_mov_b32_e32 v63, v2
	v_mov_b32_e32 v64, v2
	v_mov_b32_e32 v65, v2
	v_mov_b32_e32 v66, v2
	v_mov_b32_e32 v67, v2
	v_mov_b32_e32 v68, v2
	v_mov_b32_e32 v69, v2
	v_mov_b32_e32 v74, v2
	v_mov_b32_e32 v75, v2
	v_mov_b32_e32 v76, v2
	v_mov_b32_e32 v77, v2
	v_mov_b32_e32 v82, v2
	v_mov_b32_e32 v83, v2
	v_mov_b32_e32 v84, v2
	v_mov_b32_e32 v85, v2
	v_mov_b32_e32 v90, v2
	v_mov_b32_e32 v91, v2
	v_mov_b32_e32 v92, v2
	v_mov_b32_e32 v93, v2
	v_mov_b32_e32 v98, v2
	v_mov_b32_e32 v99, v2
	v_mov_b32_e32 v100, v2
	v_mov_b32_e32 v101, v2
	v_mov_b32_e32 v106, v2
	v_mov_b32_e32 v107, v2
	v_mov_b32_e32 v108, v2
	v_mov_b32_e32 v109, v2
	v_mov_b32_e32 v114, v2
	v_mov_b32_e32 v115, v2
	v_mov_b32_e32 v116, v2
	v_mov_b32_e32 v117, v2
	v_mov_b32_e32 v122, v2
	v_mov_b32_e32 v123, v2
	v_mov_b32_e32 v124, v2
	v_mov_b32_e32 v125, v2
	v_mov_b32_e32 v70, v2
	v_mov_b32_e32 v71, v2
	v_mov_b32_e32 v72, v2
	v_mov_b32_e32 v73, v2
	v_mov_b32_e32 v78, v2
	v_mov_b32_e32 v79, v2
	v_mov_b32_e32 v80, v2
	v_mov_b32_e32 v81, v2
	v_mov_b32_e32 v86, v2
	v_mov_b32_e32 v87, v2
	v_mov_b32_e32 v88, v2
	v_mov_b32_e32 v89, v2
	v_mov_b32_e32 v94, v2
	v_mov_b32_e32 v95, v2
	v_mov_b32_e32 v96, v2
	v_mov_b32_e32 v97, v2
	v_mov_b32_e32 v102, v2
	v_mov_b32_e32 v103, v2
	v_mov_b32_e32 v104, v2
	v_mov_b32_e32 v105, v2
	v_mov_b32_e32 v110, v2
	v_mov_b32_e32 v111, v2
	v_mov_b32_e32 v112, v2
	v_mov_b32_e32 v113, v2
	v_mov_b32_e32 v118, v2
	v_mov_b32_e32 v119, v2
	v_mov_b32_e32 v120, v2
	v_mov_b32_e32 v121, v2
	v_mov_b32_e32 v126, v2
	v_mov_b32_e32 v127, v2
	v_mov_b32_e32 v128, v2
	v_mov_b32_e32 v129, v2
	s_and_b64 vcc, exec, s[24:25]
	s_cbranch_vccnz .Lsprio_7
	s_setprio 1
.Lsprio_7:
.LBB0_2720:
	ds_read_b128 v[148:151], v159
	ds_read_b128 v[164:167], v159 offset:1024
	ds_read_b128 v[168:171], v159 offset:2048
	ds_read_b128 v[172:175], v159 offset:3072
	ds_read_b128 v[176:179], v160
	ds_read_b128 v[184:187], v160 offset:1024
	ds_read_b128 v[188:191], v160 offset:2048
	ds_read_b128 v[192:195], v160 offset:3072
	s_add_u32 s40, s6, 0xfff00080
	s_addc_u32 s41, s7, -1
	s_cmp_eq_u32 s82, 60
	s_cselect_b32 s43, s29, s41
	s_cselect_b32 s42, s78, s40
	s_cselect_b32 s41, s27, s81
	s_cselect_b32 s40, s79, s80
	s_add_i32 m0, s44, 0xc000
	ds_read_b128 v[196:199], v161
	ds_read_b128 v[200:203], v161 offset:1024
	ds_read_b128 v[204:207], v161 offset:2048
	ds_read_b128 v[208:211], v161 offset:3072
	ds_read_b128 v[212:215], v161 offset:4096
	ds_read_b128 v[216:219], v161 offset:5120
	ds_read_b128 v[220:223], v161 offset:6144
	ds_read_b128 v[224:227], v161 offset:7168
	global_load_lds_dwordx4 v140, s[6:7]
	s_add_i32 m0, s44, 0xe000
	s_nop 0
	global_load_lds_dwordx4 v142, s[6:7]
	s_waitcnt vmcnt(8)
	s_waitcnt lgkmcnt(0)
	s_barrier
	v_mfma_f32_16x16x32_bf16 v[126:129], v[148:151], v[196:199], v[126:129]
	v_mfma_f32_16x16x32_bf16 v[126:129], v[164:167], v[200:203], v[126:129]
	v_mfma_f32_16x16x32_bf16 v[118:121], v[168:171], v[196:199], v[118:121]
	v_mfma_f32_16x16x32_bf16 v[118:121], v[172:175], v[200:203], v[118:121]
	v_mfma_f32_16x16x32_bf16 v[122:125], v[176:179], v[196:199], v[122:125]
	v_mfma_f32_16x16x32_bf16 v[122:125], v[184:187], v[200:203], v[122:125]
	v_mfma_f32_16x16x32_bf16 v[114:117], v[188:191], v[196:199], v[114:117]
	v_mfma_f32_16x16x32_bf16 v[114:117], v[192:195], v[200:203], v[114:117]
	v_mfma_f32_16x16x32_bf16 v[110:113], v[148:151], v[204:207], v[110:113]
	v_mfma_f32_16x16x32_bf16 v[110:113], v[164:167], v[208:211], v[110:113]
	v_mfma_f32_16x16x32_bf16 v[102:105], v[168:171], v[204:207], v[102:105]
	v_mfma_f32_16x16x32_bf16 v[102:105], v[172:175], v[208:211], v[102:105]
	v_mfma_f32_16x16x32_bf16 v[106:109], v[176:179], v[204:207], v[106:109]
	v_mfma_f32_16x16x32_bf16 v[106:109], v[184:187], v[208:211], v[106:109]
	v_mfma_f32_16x16x32_bf16 v[98:101], v[188:191], v[204:207], v[98:101]
	v_mfma_f32_16x16x32_bf16 v[98:101], v[192:195], v[208:211], v[98:101]
	v_mfma_f32_16x16x32_bf16 v[94:97], v[148:151], v[212:215], v[94:97]
	v_mfma_f32_16x16x32_bf16 v[94:97], v[164:167], v[216:219], v[94:97]
	v_mfma_f32_16x16x32_bf16 v[86:89], v[168:171], v[212:215], v[86:89]
	v_mfma_f32_16x16x32_bf16 v[86:89], v[172:175], v[216:219], v[86:89]
	v_mfma_f32_16x16x32_bf16 v[90:93], v[176:179], v[212:215], v[90:93]
	v_mfma_f32_16x16x32_bf16 v[90:93], v[184:187], v[216:219], v[90:93]
	v_mfma_f32_16x16x32_bf16 v[82:85], v[188:191], v[212:215], v[82:85]
	v_mfma_f32_16x16x32_bf16 v[82:85], v[192:195], v[216:219], v[82:85]
	v_mfma_f32_16x16x32_bf16 v[78:81], v[148:151], v[220:223], v[78:81]
	v_mfma_f32_16x16x32_bf16 v[78:81], v[164:167], v[224:227], v[78:81]
	v_mfma_f32_16x16x32_bf16 v[70:73], v[168:171], v[220:223], v[70:73]
	v_mfma_f32_16x16x32_bf16 v[70:73], v[172:175], v[224:227], v[70:73]
	v_mfma_f32_16x16x32_bf16 v[74:77], v[176:179], v[220:223], v[74:77]
	v_mfma_f32_16x16x32_bf16 v[74:77], v[184:187], v[224:227], v[74:77]
	v_mfma_f32_16x16x32_bf16 v[66:69], v[188:191], v[220:223], v[66:69]
	v_mfma_f32_16x16x32_bf16 v[66:69], v[192:195], v[224:227], v[66:69]
	s_barrier
	s_add_i32 s83, s68, s13
	s_add_u32 s98, s40, 0x80
	s_addc_u32 s99, s41, 0
	s_mov_b32 m0, s83
	ds_read_b128 v[196:199], v161 offset:16384
	ds_read_b128 v[200:203], v161 offset:17408
	ds_read_b128 v[204:207], v161 offset:18432
	ds_read_b128 v[208:211], v161 offset:19456
	ds_read_b128 v[212:215], v161 offset:20480
	ds_read_b128 v[216:219], v161 offset:21504
	ds_read_b128 v[220:223], v161 offset:22528
	ds_read_b128 v[224:227], v161 offset:23552
	global_load_lds_dwordx4 v132, s[40:41]
	s_add_i32 m0, s83, 0x2000
	s_add_u32 s84, s40, 0x100000
	s_addc_u32 s85, s41, 0
	s_add_i32 s83, s69, s13
	global_load_lds_dwordx4 v136, s[40:41]
	s_mov_b32 m0, s83
	global_load_lds_dwordx4 v132, s[84:85]
	s_add_i32 m0, s83, 0x2000
	s_nop 0
	global_load_lds_dwordx4 v136, s[84:85]
	s_add_u32 s100, s42, 0x80
	s_addc_u32 s101, s43, 0
	s_mov_b32 m0, s44
	s_nop 0
	global_load_lds_dwordx4 v130, s[42:43]
	s_mov_b32 m0, s45
	s_nop 0
	global_load_lds_dwordx4 v134, s[42:43]
	s_waitcnt vmcnt(8)
	s_waitcnt lgkmcnt(0)
	s_barrier
	v_mfma_f32_16x16x32_bf16 v[62:65], v[148:151], v[196:199], v[62:65]
	v_mfma_f32_16x16x32_bf16 v[62:65], v[164:167], v[200:203], v[62:65]
	v_mfma_f32_16x16x32_bf16 v[54:57], v[168:171], v[196:199], v[54:57]
	v_mfma_f32_16x16x32_bf16 v[54:57], v[172:175], v[200:203], v[54:57]
	v_mfma_f32_16x16x32_bf16 v[58:61], v[176:179], v[196:199], v[58:61]
	v_mfma_f32_16x16x32_bf16 v[58:61], v[184:187], v[200:203], v[58:61]
	v_mfma_f32_16x16x32_bf16 v[50:53], v[188:191], v[196:199], v[50:53]
	v_mfma_f32_16x16x32_bf16 v[50:53], v[192:195], v[200:203], v[50:53]
	v_mfma_f32_16x16x32_bf16 v[46:49], v[148:151], v[204:207], v[46:49]
	v_mfma_f32_16x16x32_bf16 v[46:49], v[164:167], v[208:211], v[46:49]
	v_mfma_f32_16x16x32_bf16 v[38:41], v[168:171], v[204:207], v[38:41]
	v_mfma_f32_16x16x32_bf16 v[38:41], v[172:175], v[208:211], v[38:41]
	v_mfma_f32_16x16x32_bf16 v[42:45], v[176:179], v[204:207], v[42:45]
	v_mfma_f32_16x16x32_bf16 v[42:45], v[184:187], v[208:211], v[42:45]
	v_mfma_f32_16x16x32_bf16 v[34:37], v[188:191], v[204:207], v[34:37]
	v_mfma_f32_16x16x32_bf16 v[34:37], v[192:195], v[208:211], v[34:37]
	v_mfma_f32_16x16x32_bf16 v[30:33], v[148:151], v[212:215], v[30:33]
	v_mfma_f32_16x16x32_bf16 v[30:33], v[164:167], v[216:219], v[30:33]
	v_mfma_f32_16x16x32_bf16 v[22:25], v[168:171], v[212:215], v[22:25]
	v_mfma_f32_16x16x32_bf16 v[22:25], v[172:175], v[216:219], v[22:25]
	v_mfma_f32_16x16x32_bf16 v[26:29], v[176:179], v[212:215], v[26:29]
	v_mfma_f32_16x16x32_bf16 v[26:29], v[184:187], v[216:219], v[26:29]
	v_mfma_f32_16x16x32_bf16 v[18:21], v[188:191], v[212:215], v[18:21]
	v_mfma_f32_16x16x32_bf16 v[18:21], v[192:195], v[216:219], v[18:21]
	v_mfma_f32_16x16x32_bf16 v[14:17], v[148:151], v[220:223], v[14:17]
	v_mfma_f32_16x16x32_bf16 v[14:17], v[164:167], v[224:227], v[14:17]
	v_mfma_f32_16x16x32_bf16 v[6:9], v[168:171], v[220:223], v[6:9]
	v_mfma_f32_16x16x32_bf16 v[6:9], v[172:175], v[224:227], v[6:9]
	v_mfma_f32_16x16x32_bf16 v[10:13], v[176:179], v[220:223], v[10:13]
	v_mfma_f32_16x16x32_bf16 v[10:13], v[184:187], v[224:227], v[10:13]
	v_mfma_f32_16x16x32_bf16 v[2:5], v[188:191], v[220:223], v[2:5]
	v_mfma_f32_16x16x32_bf16 v[2:5], v[192:195], v[224:227], v[2:5]
	s_barrier
	s_add_i32 s83, 0, 0x18000
	v_add_u32_e32 v138, s83, v155
	s_add_i32 s84, 0, 0x1c000
	ds_read_b128 v[148:151], v138
	ds_read_b128 v[164:167], v138 offset:1024
	ds_read_b128 v[168:171], v138 offset:2048
	ds_read_b128 v[172:175], v138 offset:3072
	v_add_u32_e32 v138, s84, v155
	ds_read_b128 v[176:179], v138
	ds_read_b128 v[184:187], v138 offset:1024
	ds_read_b128 v[188:191], v138 offset:2048
	ds_read_b128 v[192:195], v138 offset:3072
	s_add_u32 s42, s42, 0x100000
	s_addc_u32 s43, s43, 0
	s_mov_b32 m0, s46
	ds_read_b128 v[196:199], v161 offset:32768
	ds_read_b128 v[200:203], v161 offset:33792
	ds_read_b128 v[204:207], v161 offset:34816
	ds_read_b128 v[208:211], v161 offset:35840
	ds_read_b128 v[212:215], v161 offset:36864
	ds_read_b128 v[216:219], v161 offset:37888
	ds_read_b128 v[220:223], v161 offset:38912
	ds_read_b128 v[224:227], v161 offset:39936
	global_load_lds_dwordx4 v130, s[42:43]
	s_mov_b32 m0, s47
	s_nop 0
	global_load_lds_dwordx4 v134, s[42:43]
	s_waitcnt vmcnt(8)
	s_waitcnt lgkmcnt(0)
	s_barrier
	v_mfma_f32_16x16x32_bf16 v[126:129], v[148:151], v[196:199], v[126:129]
	v_mfma_f32_16x16x32_bf16 v[126:129], v[164:167], v[200:203], v[126:129]
	v_mfma_f32_16x16x32_bf16 v[118:121], v[168:171], v[196:199], v[118:121]
	v_mfma_f32_16x16x32_bf16 v[118:121], v[172:175], v[200:203], v[118:121]
	v_mfma_f32_16x16x32_bf16 v[122:125], v[176:179], v[196:199], v[122:125]
	v_mfma_f32_16x16x32_bf16 v[122:125], v[184:187], v[200:203], v[122:125]
	v_mfma_f32_16x16x32_bf16 v[114:117], v[188:191], v[196:199], v[114:117]
	v_mfma_f32_16x16x32_bf16 v[114:117], v[192:195], v[200:203], v[114:117]
	v_mfma_f32_16x16x32_bf16 v[110:113], v[148:151], v[204:207], v[110:113]
	v_mfma_f32_16x16x32_bf16 v[110:113], v[164:167], v[208:211], v[110:113]
	v_mfma_f32_16x16x32_bf16 v[102:105], v[168:171], v[204:207], v[102:105]
	v_mfma_f32_16x16x32_bf16 v[102:105], v[172:175], v[208:211], v[102:105]
	v_mfma_f32_16x16x32_bf16 v[106:109], v[176:179], v[204:207], v[106:109]
	v_mfma_f32_16x16x32_bf16 v[106:109], v[184:187], v[208:211], v[106:109]
	v_mfma_f32_16x16x32_bf16 v[98:101], v[188:191], v[204:207], v[98:101]
	v_mfma_f32_16x16x32_bf16 v[98:101], v[192:195], v[208:211], v[98:101]
	v_mfma_f32_16x16x32_bf16 v[94:97], v[148:151], v[212:215], v[94:97]
	v_mfma_f32_16x16x32_bf16 v[94:97], v[164:167], v[216:219], v[94:97]
	v_mfma_f32_16x16x32_bf16 v[86:89], v[168:171], v[212:215], v[86:89]
	v_mfma_f32_16x16x32_bf16 v[86:89], v[172:175], v[216:219], v[86:89]
	v_mfma_f32_16x16x32_bf16 v[90:93], v[176:179], v[212:215], v[90:93]
	v_mfma_f32_16x16x32_bf16 v[90:93], v[184:187], v[216:219], v[90:93]
	v_mfma_f32_16x16x32_bf16 v[82:85], v[188:191], v[212:215], v[82:85]
	v_mfma_f32_16x16x32_bf16 v[82:85], v[192:195], v[216:219], v[82:85]
	v_mfma_f32_16x16x32_bf16 v[78:81], v[148:151], v[220:223], v[78:81]
	v_mfma_f32_16x16x32_bf16 v[78:81], v[164:167], v[224:227], v[78:81]
	v_mfma_f32_16x16x32_bf16 v[70:73], v[168:171], v[220:223], v[70:73]
	v_mfma_f32_16x16x32_bf16 v[70:73], v[172:175], v[224:227], v[70:73]
	v_mfma_f32_16x16x32_bf16 v[74:77], v[176:179], v[220:223], v[74:77]
	v_mfma_f32_16x16x32_bf16 v[74:77], v[184:187], v[224:227], v[74:77]
	v_mfma_f32_16x16x32_bf16 v[66:69], v[188:191], v[220:223], v[66:69]
	v_mfma_f32_16x16x32_bf16 v[66:69], v[192:195], v[224:227], v[66:69]
	s_barrier
	s_add_i32 s42, s83, s13
	s_mov_b32 m0, s42
	ds_read_b128 v[196:199], v161 offset:49152
	ds_read_b128 v[200:203], v161 offset:50176
	ds_read_b128 v[204:207], v161 offset:51200
	ds_read_b128 v[208:211], v161 offset:52224
	ds_read_b128 v[212:215], v161 offset:53248
	ds_read_b128 v[216:219], v161 offset:54272
	ds_read_b128 v[220:223], v161 offset:55296
	ds_read_b128 v[224:227], v161 offset:56320
	global_load_lds_dwordx4 v132, s[98:99]
	s_add_i32 m0, s42, 0x2000
	s_add_u32 s40, s40, 0x100080
	s_addc_u32 s41, s41, 0
	s_add_i32 s42, s84, s13
	global_load_lds_dwordx4 v136, s[98:99]
	s_mov_b32 m0, s42
	s_nop 0
	global_load_lds_dwordx4 v132, s[40:41]
	s_add_i32 m0, s42, 0x2000
	s_nop 0
	global_load_lds_dwordx4 v136, s[40:41]
	s_mov_b32 m0, s59
	s_nop 0
	global_load_lds_dwordx4 v130, s[100:101]
	s_mov_b32 m0, s62
	s_nop 0
	global_load_lds_dwordx4 v134, s[100:101]
	s_waitcnt vmcnt(8)
	s_waitcnt lgkmcnt(0)
	s_barrier
	v_mfma_f32_16x16x32_bf16 v[62:65], v[148:151], v[196:199], v[62:65]
	v_mfma_f32_16x16x32_bf16 v[62:65], v[164:167], v[200:203], v[62:65]
	v_mfma_f32_16x16x32_bf16 v[54:57], v[168:171], v[196:199], v[54:57]
	v_mfma_f32_16x16x32_bf16 v[54:57], v[172:175], v[200:203], v[54:57]
	v_mfma_f32_16x16x32_bf16 v[58:61], v[176:179], v[196:199], v[58:61]
	v_mfma_f32_16x16x32_bf16 v[58:61], v[184:187], v[200:203], v[58:61]
	v_mfma_f32_16x16x32_bf16 v[50:53], v[188:191], v[196:199], v[50:53]
	v_mfma_f32_16x16x32_bf16 v[50:53], v[192:195], v[200:203], v[50:53]
	v_mfma_f32_16x16x32_bf16 v[46:49], v[148:151], v[204:207], v[46:49]
	v_mfma_f32_16x16x32_bf16 v[46:49], v[164:167], v[208:211], v[46:49]
	v_mfma_f32_16x16x32_bf16 v[38:41], v[168:171], v[204:207], v[38:41]
	v_mfma_f32_16x16x32_bf16 v[38:41], v[172:175], v[208:211], v[38:41]
	v_mfma_f32_16x16x32_bf16 v[42:45], v[176:179], v[204:207], v[42:45]
	v_mfma_f32_16x16x32_bf16 v[42:45], v[184:187], v[208:211], v[42:45]
	v_mfma_f32_16x16x32_bf16 v[34:37], v[188:191], v[204:207], v[34:37]
	v_mfma_f32_16x16x32_bf16 v[34:37], v[192:195], v[208:211], v[34:37]
	v_mfma_f32_16x16x32_bf16 v[30:33], v[148:151], v[212:215], v[30:33]
	v_mfma_f32_16x16x32_bf16 v[30:33], v[164:167], v[216:219], v[30:33]
	v_mfma_f32_16x16x32_bf16 v[22:25], v[168:171], v[212:215], v[22:25]
	v_mfma_f32_16x16x32_bf16 v[22:25], v[172:175], v[216:219], v[22:25]
	v_mfma_f32_16x16x32_bf16 v[26:29], v[176:179], v[212:215], v[26:29]
	v_mfma_f32_16x16x32_bf16 v[26:29], v[184:187], v[216:219], v[26:29]
	v_mfma_f32_16x16x32_bf16 v[18:21], v[188:191], v[212:215], v[18:21]
	v_mfma_f32_16x16x32_bf16 v[18:21], v[192:195], v[216:219], v[18:21]
	v_mfma_f32_16x16x32_bf16 v[14:17], v[148:151], v[220:223], v[14:17]
	v_mfma_f32_16x16x32_bf16 v[14:17], v[164:167], v[224:227], v[14:17]
	v_mfma_f32_16x16x32_bf16 v[6:9], v[168:171], v[220:223], v[6:9]
	v_mfma_f32_16x16x32_bf16 v[6:9], v[172:175], v[224:227], v[6:9]
	v_mfma_f32_16x16x32_bf16 v[10:13], v[176:179], v[220:223], v[10:13]
	v_mfma_f32_16x16x32_bf16 v[10:13], v[184:187], v[224:227], v[10:13]
	v_mfma_f32_16x16x32_bf16 v[2:5], v[188:191], v[220:223], v[2:5]
	v_mfma_f32_16x16x32_bf16 v[2:5], v[192:195], v[224:227], v[2:5]
	s_barrier
	s_add_i32 s82, s82, 2
	s_add_u32 s6, s6, 0x100
	s_addc_u32 s7, s7, 0
	s_add_u32 s80, s80, 0x100
	s_addc_u32 s81, s81, 0
	s_cmp_gt_u32 s82, 61
	s_cbranch_scc0 .LBB0_2720
	s_setprio 0
	s_and_b64 vcc, exec, s[24:25]
	s_cbranch_vccz .LBB0_2723
	s_barrier

.LBB0_2804:
	s_add_u32 s26, s26, 0x2b0080
	s_addc_u32 s27, s27, 0
	s_add_u32 s12, s28, 0x100
	v_mov_b32_e32 v2, 0
	s_addc_u32 s59, s29, 0
	s_mov_b32 s62, -2
	s_waitcnt lgkmcnt(0)
	v_mov_b32_e32 v3, v2
	v_mov_b32_e32 v4, v2
	v_mov_b32_e32 v5, v2
	v_mov_b32_e32 v6, v2
	v_mov_b32_e32 v7, v2
	v_mov_b32_e32 v8, v2
	v_mov_b32_e32 v9, v2
	v_mov_b32_e32 v18, v2
	v_mov_b32_e32 v19, v2
	v_mov_b32_e32 v20, v2
	v_mov_b32_e32 v21, v2
	v_mov_b32_e32 v22, v2
	v_mov_b32_e32 v23, v2
	v_mov_b32_e32 v24, v2
	v_mov_b32_e32 v25, v2
	v_mov_b32_e32 v34, v2
	v_mov_b32_e32 v35, v2
	v_mov_b32_e32 v36, v2
	v_mov_b32_e32 v37, v2
	v_mov_b32_e32 v38, v2
	v_mov_b32_e32 v39, v2
	v_mov_b32_e32 v40, v2
	v_mov_b32_e32 v41, v2
	v_mov_b32_e32 v50, v2
	v_mov_b32_e32 v51, v2
	v_mov_b32_e32 v52, v2
	v_mov_b32_e32 v53, v2
	v_mov_b32_e32 v54, v2
	v_mov_b32_e32 v55, v2
	v_mov_b32_e32 v56, v2
	v_mov_b32_e32 v57, v2
	v_mov_b32_e32 v10, v2
	v_mov_b32_e32 v11, v2
	v_mov_b32_e32 v12, v2
	v_mov_b32_e32 v13, v2
	v_mov_b32_e32 v14, v2
	v_mov_b32_e32 v15, v2
	v_mov_b32_e32 v16, v2
	v_mov_b32_e32 v17, v2
	v_mov_b32_e32 v26, v2
	v_mov_b32_e32 v27, v2
	v_mov_b32_e32 v28, v2
	v_mov_b32_e32 v29, v2
	v_mov_b32_e32 v30, v2
	v_mov_b32_e32 v31, v2
	v_mov_b32_e32 v32, v2
	v_mov_b32_e32 v33, v2
	v_mov_b32_e32 v42, v2
	v_mov_b32_e32 v43, v2
	v_mov_b32_e32 v44, v2
	v_mov_b32_e32 v45, v2
	v_mov_b32_e32 v46, v2
	v_mov_b32_e32 v47, v2
	v_mov_b32_e32 v48, v2
	v_mov_b32_e32 v49, v2
	v_mov_b32_e32 v58, v2
	v_mov_b32_e32 v59, v2
	v_mov_b32_e32 v60, v2
	v_mov_b32_e32 v61, v2
	v_mov_b32_e32 v62, v2
	v_mov_b32_e32 v63, v2
	v_mov_b32_e32 v64, v2
	v_mov_b32_e32 v65, v2
	v_mov_b32_e32 v66, v2
	v_mov_b32_e32 v67, v2
	v_mov_b32_e32 v68, v2
	v_mov_b32_e32 v69, v2
	v_mov_b32_e32 v70, v2
	v_mov_b32_e32 v71, v2
	v_mov_b32_e32 v72, v2
	v_mov_b32_e32 v73, v2
	v_mov_b32_e32 v82, v2
	v_mov_b32_e32 v83, v2
	v_mov_b32_e32 v84, v2
	v_mov_b32_e32 v85, v2
	v_mov_b32_e32 v86, v2
	v_mov_b32_e32 v87, v2
	v_mov_b32_e32 v88, v2
	v_mov_b32_e32 v89, v2
	v_mov_b32_e32 v98, v2
	v_mov_b32_e32 v99, v2
	v_mov_b32_e32 v100, v2
	v_mov_b32_e32 v101, v2
	v_mov_b32_e32 v102, v2
	v_mov_b32_e32 v103, v2
	v_mov_b32_e32 v104, v2
	v_mov_b32_e32 v105, v2
	v_mov_b32_e32 v114, v2
	v_mov_b32_e32 v115, v2
	v_mov_b32_e32 v116, v2
	v_mov_b32_e32 v117, v2
	v_mov_b32_e32 v118, v2
	v_mov_b32_e32 v119, v2
	v_mov_b32_e32 v120, v2
	v_mov_b32_e32 v121, v2
	v_mov_b32_e32 v74, v2
	v_mov_b32_e32 v75, v2
	v_mov_b32_e32 v76, v2
	v_mov_b32_e32 v77, v2
	v_mov_b32_e32 v78, v2
	v_mov_b32_e32 v79, v2
	v_mov_b32_e32 v80, v2
	v_mov_b32_e32 v81, v2
	v_mov_b32_e32 v90, v2
	v_mov_b32_e32 v91, v2
	v_mov_b32_e32 v92, v2
	v_mov_b32_e32 v93, v2
	v_mov_b32_e32 v94, v2
	v_mov_b32_e32 v95, v2
	v_mov_b32_e32 v96, v2
	v_mov_b32_e32 v97, v2
	v_mov_b32_e32 v106, v2
	v_mov_b32_e32 v107, v2
	v_mov_b32_e32 v108, v2
	v_mov_b32_e32 v109, v2
	v_mov_b32_e32 v110, v2
	v_mov_b32_e32 v111, v2
	v_mov_b32_e32 v112, v2
	v_mov_b32_e32 v113, v2
	v_mov_b32_e32 v122, v2
	v_mov_b32_e32 v123, v2
	v_mov_b32_e32 v124, v2
	v_mov_b32_e32 v125, v2
	v_mov_b32_e32 v126, v2
	v_mov_b32_e32 v127, v2
	v_mov_b32_e32 v128, v2
	v_mov_b32_e32 v129, v2
	s_and_b64 vcc, exec, s[22:23]
	s_cbranch_vccnz .Lsprio_8
	s_setprio 1
.Lsprio_8:
.LBB0_2805:
	ds_read_b128 v[130:133], v163
	ds_read_b128 v[134:137], v163 offset:1024
	ds_read_b128 v[138:141], v163 offset:2048
	ds_read_b128 v[142:145], v163 offset:3072
	ds_read_b128 v[146:149], v188
	ds_read_b128 v[150:153], v188 offset:1024
	ds_read_b128 v[174:177], v188 offset:2048
	ds_read_b128 v[178:181], v188 offset:3072
	s_add_u32 s28, s26, 0xffd50080
	s_addc_u32 s29, s27, -1
	s_cmpk_eq_i32 s62, 0xa8
	s_cselect_b32 s37, s7, s29
	s_cselect_b32 s36, s6, s28
	s_cselect_b32 s29, s25, s59
	s_cselect_b32 s28, s24, s12
	s_add_i32 m0, s38, 0xc000
	ds_read_b128 v[184:187], v189
	ds_read_b128 v[192:195], v189 offset:1024
	ds_read_b128 v[196:199], v189 offset:2048
	ds_read_b128 v[200:203], v189 offset:3072
	ds_read_b128 v[204:207], v189 offset:4096
	ds_read_b128 v[208:211], v189 offset:5120
	ds_read_b128 v[212:215], v189 offset:6144
	ds_read_b128 v[216:219], v189 offset:7168
	global_load_lds_dwordx4 v166, s[26:27]
	s_add_i32 m0, s38, 0xe000
	s_nop 0
	global_load_lds_dwordx4 v168, s[26:27]
	s_waitcnt vmcnt(8)
	s_waitcnt lgkmcnt(0)
	s_barrier
	v_mfma_f32_16x16x32_bf16 v[126:129], v[130:133], v[184:187], v[126:129]
	v_mfma_f32_16x16x32_bf16 v[126:129], v[134:137], v[192:195], v[126:129]
	v_mfma_f32_16x16x32_bf16 v[122:125], v[138:141], v[184:187], v[122:125]
	v_mfma_f32_16x16x32_bf16 v[122:125], v[142:145], v[192:195], v[122:125]
	v_mfma_f32_16x16x32_bf16 v[118:121], v[146:149], v[184:187], v[118:121]
	v_mfma_f32_16x16x32_bf16 v[118:121], v[150:153], v[192:195], v[118:121]
	v_mfma_f32_16x16x32_bf16 v[114:117], v[174:177], v[184:187], v[114:117]
	v_mfma_f32_16x16x32_bf16 v[114:117], v[178:181], v[192:195], v[114:117]
	v_mfma_f32_16x16x32_bf16 v[110:113], v[130:133], v[196:199], v[110:113]
	v_mfma_f32_16x16x32_bf16 v[110:113], v[134:137], v[200:203], v[110:113]
	v_mfma_f32_16x16x32_bf16 v[106:109], v[138:141], v[196:199], v[106:109]
	v_mfma_f32_16x16x32_bf16 v[106:109], v[142:145], v[200:203], v[106:109]
	v_mfma_f32_16x16x32_bf16 v[102:105], v[146:149], v[196:199], v[102:105]
	v_mfma_f32_16x16x32_bf16 v[102:105], v[150:153], v[200:203], v[102:105]
	v_mfma_f32_16x16x32_bf16 v[98:101], v[174:177], v[196:199], v[98:101]
	v_mfma_f32_16x16x32_bf16 v[98:101], v[178:181], v[200:203], v[98:101]
	v_mfma_f32_16x16x32_bf16 v[94:97], v[130:133], v[204:207], v[94:97]
	v_mfma_f32_16x16x32_bf16 v[94:97], v[134:137], v[208:211], v[94:97]
	v_mfma_f32_16x16x32_bf16 v[90:93], v[138:141], v[204:207], v[90:93]
	v_mfma_f32_16x16x32_bf16 v[90:93], v[142:145], v[208:211], v[90:93]
	v_mfma_f32_16x16x32_bf16 v[86:89], v[146:149], v[204:207], v[86:89]
	v_mfma_f32_16x16x32_bf16 v[86:89], v[150:153], v[208:211], v[86:89]
	v_mfma_f32_16x16x32_bf16 v[82:85], v[174:177], v[204:207], v[82:85]
	v_mfma_f32_16x16x32_bf16 v[82:85], v[178:181], v[208:211], v[82:85]
	v_mfma_f32_16x16x32_bf16 v[78:81], v[130:133], v[212:215], v[78:81]
	v_mfma_f32_16x16x32_bf16 v[78:81], v[134:137], v[216:219], v[78:81]
	v_mfma_f32_16x16x32_bf16 v[74:77], v[138:141], v[212:215], v[74:77]
	v_mfma_f32_16x16x32_bf16 v[74:77], v[142:145], v[216:219], v[74:77]
	v_mfma_f32_16x16x32_bf16 v[70:73], v[146:149], v[212:215], v[70:73]
	v_mfma_f32_16x16x32_bf16 v[70:73], v[150:153], v[216:219], v[70:73]
	v_mfma_f32_16x16x32_bf16 v[66:69], v[174:177], v[212:215], v[66:69]
	v_mfma_f32_16x16x32_bf16 v[66:69], v[178:181], v[216:219], v[66:69]
	s_barrier
	s_add_i32 s63, s47, s35
	s_add_u32 s98, s28, 0x80
	s_addc_u32 s99, s29, 0
	s_mov_b32 m0, s63
	ds_read_b128 v[184:187], v189 offset:16384
	ds_read_b128 v[192:195], v189 offset:17408
	ds_read_b128 v[196:199], v189 offset:18432
	ds_read_b128 v[200:203], v189 offset:19456
	ds_read_b128 v[204:207], v189 offset:20480
	ds_read_b128 v[208:211], v189 offset:21504
	ds_read_b128 v[212:215], v189 offset:22528
	ds_read_b128 v[216:219], v189 offset:23552
	global_load_lds_dwordx4 v156, s[28:29]
	s_add_i32 m0, s63, 0x2000
	s_add_u32 s66, s28, 0x2b0000
	s_addc_u32 s67, s29, 0
	s_add_i32 s63, s48, s35
	global_load_lds_dwordx4 v160, s[28:29]
	s_mov_b32 m0, s63
	global_load_lds_dwordx4 v156, s[66:67]
	s_add_i32 m0, s63, 0x2000
	s_nop 0
	global_load_lds_dwordx4 v160, s[66:67]
	s_add_u32 s100, s36, 0x80
	s_addc_u32 s101, s37, 0
	s_mov_b32 m0, s38
	s_nop 0
	global_load_lds_dwordx4 v154, s[36:37]
	s_mov_b32 m0, s39
	s_nop 0
	global_load_lds_dwordx4 v158, s[36:37]
	s_waitcnt vmcnt(8)
	s_waitcnt lgkmcnt(0)
	s_barrier
	v_mfma_f32_16x16x32_bf16 v[62:65], v[130:133], v[184:187], v[62:65]
	v_mfma_f32_16x16x32_bf16 v[62:65], v[134:137], v[192:195], v[62:65]
	v_mfma_f32_16x16x32_bf16 v[58:61], v[138:141], v[184:187], v[58:61]
	v_mfma_f32_16x16x32_bf16 v[58:61], v[142:145], v[192:195], v[58:61]
	v_mfma_f32_16x16x32_bf16 v[54:57], v[146:149], v[184:187], v[54:57]
	v_mfma_f32_16x16x32_bf16 v[54:57], v[150:153], v[192:195], v[54:57]
	v_mfma_f32_16x16x32_bf16 v[50:53], v[174:177], v[184:187], v[50:53]
	v_mfma_f32_16x16x32_bf16 v[50:53], v[178:181], v[192:195], v[50:53]
	v_mfma_f32_16x16x32_bf16 v[46:49], v[130:133], v[196:199], v[46:49]
	v_mfma_f32_16x16x32_bf16 v[46:49], v[134:137], v[200:203], v[46:49]
	v_mfma_f32_16x16x32_bf16 v[42:45], v[138:141], v[196:199], v[42:45]
	v_mfma_f32_16x16x32_bf16 v[42:45], v[142:145], v[200:203], v[42:45]
	v_mfma_f32_16x16x32_bf16 v[38:41], v[146:149], v[196:199], v[38:41]
	v_mfma_f32_16x16x32_bf16 v[38:41], v[150:153], v[200:203], v[38:41]
	v_mfma_f32_16x16x32_bf16 v[34:37], v[174:177], v[196:199], v[34:37]
	v_mfma_f32_16x16x32_bf16 v[34:37], v[178:181], v[200:203], v[34:37]
	v_mfma_f32_16x16x32_bf16 v[30:33], v[130:133], v[204:207], v[30:33]
	v_mfma_f32_16x16x32_bf16 v[30:33], v[134:137], v[208:211], v[30:33]
	v_mfma_f32_16x16x32_bf16 v[26:29], v[138:141], v[204:207], v[26:29]
	v_mfma_f32_16x16x32_bf16 v[26:29], v[142:145], v[208:211], v[26:29]
	v_mfma_f32_16x16x32_bf16 v[22:25], v[146:149], v[204:207], v[22:25]
	v_mfma_f32_16x16x32_bf16 v[22:25], v[150:153], v[208:211], v[22:25]
	v_mfma_f32_16x16x32_bf16 v[18:21], v[174:177], v[204:207], v[18:21]
	v_mfma_f32_16x16x32_bf16 v[18:21], v[178:181], v[208:211], v[18:21]
	v_mfma_f32_16x16x32_bf16 v[14:17], v[130:133], v[212:215], v[14:17]
	v_mfma_f32_16x16x32_bf16 v[14:17], v[134:137], v[216:219], v[14:17]
	v_mfma_f32_16x16x32_bf16 v[10:13], v[138:141], v[212:215], v[10:13]
	v_mfma_f32_16x16x32_bf16 v[10:13], v[142:145], v[216:219], v[10:13]
	v_mfma_f32_16x16x32_bf16 v[6:9], v[146:149], v[212:215], v[6:9]
	v_mfma_f32_16x16x32_bf16 v[6:9], v[150:153], v[216:219], v[6:9]
	v_mfma_f32_16x16x32_bf16 v[2:5], v[174:177], v[212:215], v[2:5]
	v_mfma_f32_16x16x32_bf16 v[2:5], v[178:181], v[216:219], v[2:5]
	s_barrier
	s_add_i32 s63, 0, 0x18000
	s_add_i32 s65, 0, 0x1c000
	v_add_u32_e32 v142, s63, v1
	v_add_u32_e32 v178, s65, v1
	ds_read_b128 v[130:133], v142
	ds_read_b128 v[134:137], v142 offset:1024
	ds_read_b128 v[138:141], v142 offset:2048
	ds_read_b128 v[142:145], v142 offset:3072
	ds_read_b128 v[146:149], v178
	ds_read_b128 v[150:153], v178 offset:1024
	ds_read_b128 v[174:177], v178 offset:2048
	ds_read_b128 v[178:181], v178 offset:3072
	s_add_u32 s36, s36, 0x2b0000
	s_addc_u32 s37, s37, 0
	s_mov_b32 m0, s40
	ds_read_b128 v[184:187], v189 offset:32768
	ds_read_b128 v[192:195], v189 offset:33792
	ds_read_b128 v[196:199], v189 offset:34816
	ds_read_b128 v[200:203], v189 offset:35840
	ds_read_b128 v[204:207], v189 offset:36864
	ds_read_b128 v[208:211], v189 offset:37888
	ds_read_b128 v[212:215], v189 offset:38912
	ds_read_b128 v[216:219], v189 offset:39936
	global_load_lds_dwordx4 v154, s[36:37]
	s_mov_b32 m0, s41
	s_nop 0
	global_load_lds_dwordx4 v158, s[36:37]
	s_waitcnt vmcnt(8)
	s_waitcnt lgkmcnt(0)
	s_barrier
	v_mfma_f32_16x16x32_bf16 v[126:129], v[130:133], v[184:187], v[126:129]
	v_mfma_f32_16x16x32_bf16 v[126:129], v[134:137], v[192:195], v[126:129]
	v_mfma_f32_16x16x32_bf16 v[122:125], v[138:141], v[184:187], v[122:125]
	v_mfma_f32_16x16x32_bf16 v[122:125], v[142:145], v[192:195], v[122:125]
	v_mfma_f32_16x16x32_bf16 v[118:121], v[146:149], v[184:187], v[118:121]
	v_mfma_f32_16x16x32_bf16 v[118:121], v[150:153], v[192:195], v[118:121]
	v_mfma_f32_16x16x32_bf16 v[114:117], v[174:177], v[184:187], v[114:117]
	v_mfma_f32_16x16x32_bf16 v[114:117], v[178:181], v[192:195], v[114:117]
	v_mfma_f32_16x16x32_bf16 v[110:113], v[130:133], v[196:199], v[110:113]
	v_mfma_f32_16x16x32_bf16 v[110:113], v[134:137], v[200:203], v[110:113]
	v_mfma_f32_16x16x32_bf16 v[106:109], v[138:141], v[196:199], v[106:109]
	v_mfma_f32_16x16x32_bf16 v[106:109], v[142:145], v[200:203], v[106:109]
	v_mfma_f32_16x16x32_bf16 v[102:105], v[146:149], v[196:199], v[102:105]
	v_mfma_f32_16x16x32_bf16 v[102:105], v[150:153], v[200:203], v[102:105]
	v_mfma_f32_16x16x32_bf16 v[98:101], v[174:177], v[196:199], v[98:101]
	v_mfma_f32_16x16x32_bf16 v[98:101], v[178:181], v[200:203], v[98:101]
	v_mfma_f32_16x16x32_bf16 v[94:97], v[130:133], v[204:207], v[94:97]
	v_mfma_f32_16x16x32_bf16 v[94:97], v[134:137], v[208:211], v[94:97]
	v_mfma_f32_16x16x32_bf16 v[90:93], v[138:141], v[204:207], v[90:93]
	v_mfma_f32_16x16x32_bf16 v[90:93], v[142:145], v[208:211], v[90:93]
	v_mfma_f32_16x16x32_bf16 v[86:89], v[146:149], v[204:207], v[86:89]
	v_mfma_f32_16x16x32_bf16 v[86:89], v[150:153], v[208:211], v[86:89]
	v_mfma_f32_16x16x32_bf16 v[82:85], v[174:177], v[204:207], v[82:85]
	v_mfma_f32_16x16x32_bf16 v[82:85], v[178:181], v[208:211], v[82:85]
	v_mfma_f32_16x16x32_bf16 v[78:81], v[130:133], v[212:215], v[78:81]
	v_mfma_f32_16x16x32_bf16 v[78:81], v[134:137], v[216:219], v[78:81]
	v_mfma_f32_16x16x32_bf16 v[74:77], v[138:141], v[212:215], v[74:77]
	v_mfma_f32_16x16x32_bf16 v[74:77], v[142:145], v[216:219], v[74:77]
	v_mfma_f32_16x16x32_bf16 v[70:73], v[146:149], v[212:215], v[70:73]
	v_mfma_f32_16x16x32_bf16 v[70:73], v[150:153], v[216:219], v[70:73]
	v_mfma_f32_16x16x32_bf16 v[66:69], v[174:177], v[212:215], v[66:69]
	v_mfma_f32_16x16x32_bf16 v[66:69], v[178:181], v[216:219], v[66:69]
	s_barrier
	s_add_i32 s36, s63, s35
	s_mov_b32 m0, s36
	ds_read_b128 v[184:187], v189 offset:49152
	ds_read_b128 v[192:195], v189 offset:50176
	ds_read_b128 v[196:199], v189 offset:51200
	ds_read_b128 v[200:203], v189 offset:52224
	ds_read_b128 v[204:207], v189 offset:53248
	ds_read_b128 v[208:211], v189 offset:54272
	ds_read_b128 v[212:215], v189 offset:55296
	ds_read_b128 v[216:219], v189 offset:56320
	global_load_lds_dwordx4 v156, s[98:99]
	s_add_i32 m0, s36, 0x2000
	s_add_u32 s28, s28, 0x2b0080
	s_addc_u32 s29, s29, 0
	s_add_i32 s36, s65, s35
	global_load_lds_dwordx4 v160, s[98:99]
	s_mov_b32 m0, s36
	s_nop 0
	global_load_lds_dwordx4 v156, s[28:29]
	s_add_i32 m0, s36, 0x2000
	s_nop 0
	global_load_lds_dwordx4 v160, s[28:29]
	s_mov_b32 m0, s43
	s_nop 0
	global_load_lds_dwordx4 v154, s[100:101]
	s_mov_b32 m0, s44
	s_nop 0
	global_load_lds_dwordx4 v158, s[100:101]
	s_waitcnt vmcnt(8)
	s_waitcnt lgkmcnt(0)
	s_barrier
	v_mfma_f32_16x16x32_bf16 v[62:65], v[130:133], v[184:187], v[62:65]
	v_mfma_f32_16x16x32_bf16 v[62:65], v[134:137], v[192:195], v[62:65]
	v_mfma_f32_16x16x32_bf16 v[58:61], v[138:141], v[184:187], v[58:61]
	v_mfma_f32_16x16x32_bf16 v[58:61], v[142:145], v[192:195], v[58:61]
	v_mfma_f32_16x16x32_bf16 v[54:57], v[146:149], v[184:187], v[54:57]
	v_mfma_f32_16x16x32_bf16 v[54:57], v[150:153], v[192:195], v[54:57]
	v_mfma_f32_16x16x32_bf16 v[50:53], v[174:177], v[184:187], v[50:53]
	v_mfma_f32_16x16x32_bf16 v[50:53], v[178:181], v[192:195], v[50:53]
	v_mfma_f32_16x16x32_bf16 v[46:49], v[130:133], v[196:199], v[46:49]
	v_mfma_f32_16x16x32_bf16 v[46:49], v[134:137], v[200:203], v[46:49]
	v_mfma_f32_16x16x32_bf16 v[42:45], v[138:141], v[196:199], v[42:45]
	v_mfma_f32_16x16x32_bf16 v[42:45], v[142:145], v[200:203], v[42:45]
	v_mfma_f32_16x16x32_bf16 v[38:41], v[146:149], v[196:199], v[38:41]
	v_mfma_f32_16x16x32_bf16 v[38:41], v[150:153], v[200:203], v[38:41]
	v_mfma_f32_16x16x32_bf16 v[34:37], v[174:177], v[196:199], v[34:37]
	v_mfma_f32_16x16x32_bf16 v[34:37], v[178:181], v[200:203], v[34:37]
	v_mfma_f32_16x16x32_bf16 v[30:33], v[130:133], v[204:207], v[30:33]
	v_mfma_f32_16x16x32_bf16 v[30:33], v[134:137], v[208:211], v[30:33]
	v_mfma_f32_16x16x32_bf16 v[26:29], v[138:141], v[204:207], v[26:29]
	v_mfma_f32_16x16x32_bf16 v[26:29], v[142:145], v[208:211], v[26:29]
	v_mfma_f32_16x16x32_bf16 v[22:25], v[146:149], v[204:207], v[22:25]
	v_mfma_f32_16x16x32_bf16 v[22:25], v[150:153], v[208:211], v[22:25]
	v_mfma_f32_16x16x32_bf16 v[18:21], v[174:177], v[204:207], v[18:21]
	v_mfma_f32_16x16x32_bf16 v[18:21], v[178:181], v[208:211], v[18:21]
	v_mfma_f32_16x16x32_bf16 v[14:17], v[130:133], v[212:215], v[14:17]
	v_mfma_f32_16x16x32_bf16 v[14:17], v[134:137], v[216:219], v[14:17]
	v_mfma_f32_16x16x32_bf16 v[10:13], v[138:141], v[212:215], v[10:13]
	v_mfma_f32_16x16x32_bf16 v[10:13], v[142:145], v[216:219], v[10:13]
	v_mfma_f32_16x16x32_bf16 v[6:9], v[146:149], v[212:215], v[6:9]
	v_mfma_f32_16x16x32_bf16 v[6:9], v[150:153], v[216:219], v[6:9]
	v_mfma_f32_16x16x32_bf16 v[2:5], v[174:177], v[212:215], v[2:5]
	v_mfma_f32_16x16x32_bf16 v[2:5], v[178:181], v[216:219], v[2:5]
	s_barrier
	s_add_i32 s62, s62, 2
	s_add_u32 s26, s26, 0x100
	s_addc_u32 s27, s27, 0
	s_add_u32 s12, s12, 0x100
	s_addc_u32 s59, s59, 0
	s_cmpk_gt_u32 s62, 0xa9
	s_cbranch_scc0 .LBB0_2805
	s_setprio 0
	s_and_b64 vcc, exec, s[22:23]
	s_cbranch_vccz .LBB0_2808
	s_barrier
